# GEMM epilogue dwordx4 stores made write-through (sc1) on top of LN hoist
# speedup vs baseline: 1.0281x; 1.0118x over previous
.LBB0_209:
	v_mov_b32_e32 v129, v192
	s_lshl_b32 s15, s60, 8
	v_lshrrev_b32_e32 v128, 1, v129
	v_and_or_b32 v128, v128, 24, s15
	s_lshl_b32 s15, s57, 8
	v_or_b32_e32 v128, s44, v128
	s_add_i32 s15, s15, s38
	v_and_or_b32 v132, v129, 15, s15
	v_ashrrev_i32_e32 v129, 31, v128
	v_lshl_add_u64 v[128:129], v[128:129], 1, s[10:11]
	s_movk_i32 s15, 0x1800
	v_mad_i64_i32 v[130:131], s[22:23], v132, s15, v[128:129]
	v_cvt_pk_bf16_f32 v124, v124, v125
	v_cvt_pk_bf16_f32 v125, v126, v127
	v_cvt_pk_bf16_f32 v126, v120, v121
	v_cvt_pk_bf16_f32 v127, v122, v123
	global_store_dwordx4 v[130:131], v[124:127], off sc1
	v_cvt_pk_bf16_f32 v112, v112, v113
	v_cvt_pk_bf16_f32 v113, v114, v115
	v_cvt_pk_bf16_f32 v114, v104, v105
	v_or_b32_e32 v104, 16, v132
	v_cvt_pk_bf16_f32 v115, v106, v107
	global_store_dwordx4 v[130:131], v[112:115], off offset:256 sc1
	s_andn2_b64 vcc, exec, s[4:5]
	s_mov_b64 s[4:5], -1
	v_mad_i64_i32 v[112:113], s[22:23], v104, s15, v[128:129]
	v_cvt_pk_bf16_f32 v104, v116, v117
	v_cvt_pk_bf16_f32 v105, v118, v119
	v_cvt_pk_bf16_f32 v106, v108, v109
	v_cvt_pk_bf16_f32 v107, v110, v111
	global_store_dwordx4 v[112:113], v[104:107], off sc1
	v_cvt_pk_bf16_f32 v96, v96, v97
	v_cvt_pk_bf16_f32 v97, v98, v99
	v_cvt_pk_bf16_f32 v98, v88, v89
	v_or_b32_e32 v88, 32, v132
	v_cvt_pk_bf16_f32 v99, v90, v91
	global_store_dwordx4 v[112:113], v[96:99], off offset:256 sc1
	s_nop 1
	v_mad_i64_i32 v[96:97], s[22:23], v88, s15, v[128:129]
	v_cvt_pk_bf16_f32 v88, v100, v101
	v_cvt_pk_bf16_f32 v89, v102, v103
	v_cvt_pk_bf16_f32 v90, v92, v93
	v_cvt_pk_bf16_f32 v91, v94, v95
	global_store_dwordx4 v[96:97], v[88:91], off sc1
	v_cvt_pk_bf16_f32 v80, v80, v81
	v_cvt_pk_bf16_f32 v81, v82, v83
	v_cvt_pk_bf16_f32 v82, v72, v73
	v_or_b32_e32 v72, 48, v132
	v_cvt_pk_bf16_f32 v83, v74, v75
	global_store_dwordx4 v[96:97], v[80:83], off offset:256 sc1
	s_nop 1
	v_mad_i64_i32 v[80:81], s[22:23], v72, s15, v[128:129]
	v_cvt_pk_bf16_f32 v72, v84, v85
	v_cvt_pk_bf16_f32 v73, v86, v87
	v_cvt_pk_bf16_f32 v74, v76, v77
	v_cvt_pk_bf16_f32 v75, v78, v79
	global_store_dwordx4 v[80:81], v[72:75], off sc1
	v_cvt_pk_bf16_f32 v68, v68, v69
	v_cvt_pk_bf16_f32 v69, v70, v71
	v_cvt_pk_bf16_f32 v70, v64, v65
	v_add_u32_e32 v64, 0x80, v132
	v_mad_i64_i32 v[64:65], s[22:23], v64, s15, v[128:129]
	v_cvt_pk_bf16_f32 v71, v66, v67
	global_store_dwordx4 v[80:81], v[68:71], off offset:256 sc1
	v_cvt_pk_bf16_f32 v60, v60, v61
	v_cvt_pk_bf16_f32 v61, v62, v63
	v_cvt_pk_bf16_f32 v62, v56, v57
	v_cvt_pk_bf16_f32 v63, v58, v59
	global_store_dwordx4 v[64:65], v[60:63], off sc1
	v_cvt_pk_bf16_f32 v48, v48, v49
	v_cvt_pk_bf16_f32 v49, v50, v51
	v_cvt_pk_bf16_f32 v50, v40, v41
	v_add_u32_e32 v40, 0x90, v132
	v_cvt_pk_bf16_f32 v51, v42, v43
	global_store_dwordx4 v[64:65], v[48:51], off offset:256 sc1
	s_nop 1
	v_mad_i64_i32 v[48:49], s[22:23], v40, s15, v[128:129]
	v_cvt_pk_bf16_f32 v40, v52, v53
	v_cvt_pk_bf16_f32 v41, v54, v55
	v_cvt_pk_bf16_f32 v42, v44, v45
	v_cvt_pk_bf16_f32 v43, v46, v47
	global_store_dwordx4 v[48:49], v[40:43], off sc1
	v_cvt_pk_bf16_f32 v32, v32, v33
	v_cvt_pk_bf16_f32 v33, v34, v35
	v_cvt_pk_bf16_f32 v34, v24, v25
	v_add_u32_e32 v24, 0xa0, v132
	v_cvt_pk_bf16_f32 v35, v26, v27
	global_store_dwordx4 v[48:49], v[32:35], off offset:256 sc1
	s_nop 1
	v_mad_i64_i32 v[32:33], s[22:23], v24, s15, v[128:129]
	v_cvt_pk_bf16_f32 v24, v36, v37
	v_cvt_pk_bf16_f32 v25, v38, v39
	v_cvt_pk_bf16_f32 v26, v28, v29
	v_cvt_pk_bf16_f32 v27, v30, v31
	global_store_dwordx4 v[32:33], v[24:27], off sc1
	v_cvt_pk_bf16_f32 v16, v16, v17
	v_cvt_pk_bf16_f32 v17, v18, v19
	v_cvt_pk_bf16_f32 v18, v8, v9
	v_add_u32_e32 v8, 0xb0, v132
	v_cvt_pk_bf16_f32 v19, v10, v11
	global_store_dwordx4 v[32:33], v[16:19], off offset:256 sc1
	s_nop 1
	v_mad_i64_i32 v[16:17], s[22:23], v8, s15, v[128:129]
	v_cvt_pk_bf16_f32 v8, v20, v21
	v_cvt_pk_bf16_f32 v9, v22, v23
	v_cvt_pk_bf16_f32 v10, v12, v13
	v_cvt_pk_bf16_f32 v11, v14, v15
	global_store_dwordx4 v[16:17], v[8:11], off sc1
	v_cvt_pk_bf16_f32 v4, v4, v5
	v_cvt_pk_bf16_f32 v5, v6, v7
	v_cvt_pk_bf16_f32 v6, v0, v1
	v_cvt_pk_bf16_f32 v7, v2, v3
	global_store_dwordx4 v[16:17], v[4:7], off offset:256 sc1
	s_cbranch_vccnz .LBB0_202
	v_mov_b32_e32 v0, v192
	s_andn2_b64 vcc, exec, s[8:9]
	s_cbranch_vccnz .LBB0_201
	s_barrier
	s_branch .LBB0_201

.LBB0_605:
	v_or_b32_e32 v130, s62, v129
	s_add_u32 s18, s6, s20
	s_addc_u32 s19, s7, s21
	v_ashrrev_i32_e32 v129, 31, v128
	v_ashrrev_i32_e32 v131, 31, v130
	v_lshl_add_u64 v[132:133], v[128:129], 1, s[18:19]
	v_lshlrev_b64 v[128:129], 11, v[130:131]
	v_lshl_add_u64 v[128:129], v[132:133], 0, v[128:129]
	v_cvt_pk_bf16_f32 v124, v124, v125
	v_cvt_pk_bf16_f32 v125, v126, v127
	v_cvt_pk_bf16_f32 v126, v120, v121
	v_cvt_pk_bf16_f32 v127, v122, v123
	global_store_dwordx4 v[128:129], v[124:127], off sc1
	v_cvt_pk_bf16_f32 v112, v112, v113
	v_cvt_pk_bf16_f32 v113, v114, v115
	v_cvt_pk_bf16_f32 v114, v104, v105
	v_or_b32_e32 v104, 16, v130
	v_ashrrev_i32_e32 v105, 31, v104
	v_lshlrev_b64 v[104:105], 11, v[104:105]
	v_cvt_pk_bf16_f32 v115, v106, v107
	global_store_dwordx4 v[128:129], v[112:115], off offset:256 sc1
	s_mov_b64 s[18:19], 0x40000
	s_nop 0
	v_lshl_add_u64 v[112:113], v[132:133], 0, v[104:105]
	v_cvt_pk_bf16_f32 v104, v116, v117
	v_cvt_pk_bf16_f32 v105, v118, v119
	v_cvt_pk_bf16_f32 v106, v108, v109
	v_cvt_pk_bf16_f32 v107, v110, v111
	global_store_dwordx4 v[112:113], v[104:107], off sc1
	v_cvt_pk_bf16_f32 v96, v96, v97
	v_cvt_pk_bf16_f32 v97, v98, v99
	v_cvt_pk_bf16_f32 v98, v88, v89
	v_or_b32_e32 v88, 32, v130
	v_ashrrev_i32_e32 v89, 31, v88
	v_lshlrev_b64 v[88:89], 11, v[88:89]
	v_cvt_pk_bf16_f32 v99, v90, v91
	global_store_dwordx4 v[112:113], v[96:99], off offset:256 sc1
	s_nop 1
	v_lshl_add_u64 v[96:97], v[132:133], 0, v[88:89]
	v_cvt_pk_bf16_f32 v88, v100, v101
	v_cvt_pk_bf16_f32 v89, v102, v103
	v_cvt_pk_bf16_f32 v90, v92, v93
	v_cvt_pk_bf16_f32 v91, v94, v95
	global_store_dwordx4 v[96:97], v[88:91], off sc1
	v_cvt_pk_bf16_f32 v80, v80, v81
	v_cvt_pk_bf16_f32 v81, v82, v83
	v_cvt_pk_bf16_f32 v82, v72, v73
	v_or_b32_e32 v72, 48, v130
	v_ashrrev_i32_e32 v73, 31, v72
	v_lshlrev_b64 v[72:73], 11, v[72:73]
	v_cvt_pk_bf16_f32 v83, v74, v75
	global_store_dwordx4 v[96:97], v[80:83], off offset:256 sc1
	s_nop 1
	v_lshl_add_u64 v[80:81], v[132:133], 0, v[72:73]
	v_cvt_pk_bf16_f32 v72, v84, v85
	v_cvt_pk_bf16_f32 v73, v86, v87
	v_cvt_pk_bf16_f32 v74, v76, v77
	v_cvt_pk_bf16_f32 v75, v78, v79
	global_store_dwordx4 v[80:81], v[72:75], off sc1
	v_cvt_pk_bf16_f32 v68, v68, v69
	v_cvt_pk_bf16_f32 v69, v70, v71
	v_cvt_pk_bf16_f32 v70, v64, v65
	v_lshl_add_u64 v[64:65], v[128:129], 0, s[18:19]
	s_mov_b32 s18, 0x40000
	v_cvt_pk_bf16_f32 v71, v66, v67
	global_store_dwordx4 v[80:81], v[68:71], off offset:256 sc1
	v_cvt_pk_bf16_f32 v60, v60, v61
	v_cvt_pk_bf16_f32 v61, v62, v63
	v_cvt_pk_bf16_f32 v62, v56, v57
	v_add_co_u32_e32 v56, vcc, s18, v128
	v_cvt_pk_bf16_f32 v63, v58, v59
	s_mov_b64 s[18:19], 0x48000
	s_nop 0
	v_addc_co_u32_e32 v57, vcc, 0, v129, vcc
	global_store_dwordx4 v[56:57], v[60:63], off sc1
	v_cvt_pk_bf16_f32 v48, v48, v49
	v_cvt_pk_bf16_f32 v49, v50, v51
	v_cvt_pk_bf16_f32 v50, v40, v41
	v_cvt_pk_bf16_f32 v51, v42, v43
	global_store_dwordx4 v[64:65], v[48:51], off offset:256 sc1
	v_cvt_pk_bf16_f32 v40, v52, v53
	v_cvt_pk_bf16_f32 v41, v54, v55
	v_cvt_pk_bf16_f32 v42, v44, v45
	v_cvt_pk_bf16_f32 v43, v46, v47
	s_nop 1
	v_lshl_add_u64 v[48:49], v[128:129], 0, s[18:19]
	s_mov_b32 s18, 0x48000
	v_add_co_u32_e32 v44, vcc, s18, v128
	s_mov_b64 s[18:19], 0x50000
	s_nop 0
	v_addc_co_u32_e32 v45, vcc, 0, v129, vcc
	global_store_dwordx4 v[44:45], v[40:43], off sc1
	v_cvt_pk_bf16_f32 v32, v32, v33
	v_cvt_pk_bf16_f32 v33, v34, v35
	v_cvt_pk_bf16_f32 v34, v24, v25
	v_cvt_pk_bf16_f32 v35, v26, v27
	global_store_dwordx4 v[48:49], v[32:35], off offset:256 sc1
	v_cvt_pk_bf16_f32 v24, v36, v37
	v_cvt_pk_bf16_f32 v25, v38, v39
	v_cvt_pk_bf16_f32 v26, v28, v29
	v_cvt_pk_bf16_f32 v27, v30, v31
	s_nop 1
	v_lshl_add_u64 v[32:33], v[128:129], 0, s[18:19]
	s_mov_b32 s18, 0x50000
	v_add_co_u32_e32 v28, vcc, s18, v128
	s_mov_b64 s[18:19], 0x58000
	s_nop 0
	v_addc_co_u32_e32 v29, vcc, 0, v129, vcc
	global_store_dwordx4 v[28:29], v[24:27], off sc1
	v_cvt_pk_bf16_f32 v16, v16, v17
	v_cvt_pk_bf16_f32 v17, v18, v19
	v_cvt_pk_bf16_f32 v18, v8, v9
	v_cvt_pk_bf16_f32 v19, v10, v11
	global_store_dwordx4 v[32:33], v[16:19], off offset:256 sc1
	v_cvt_pk_bf16_f32 v8, v20, v21
	v_cvt_pk_bf16_f32 v9, v22, v23
	v_cvt_pk_bf16_f32 v10, v12, v13
	v_cvt_pk_bf16_f32 v11, v14, v15
	s_nop 1
	v_lshl_add_u64 v[16:17], v[128:129], 0, s[18:19]
	s_mov_b32 s18, 0x58000
	v_add_co_u32_e32 v12, vcc, s18, v128
	s_nop 1
	v_addc_co_u32_e32 v13, vcc, 0, v129, vcc
	global_store_dwordx4 v[12:13], v[8:11], off sc1
	v_cvt_pk_bf16_f32 v4, v4, v5
	v_cvt_pk_bf16_f32 v5, v6, v7
	v_cvt_pk_bf16_f32 v6, v0, v1
	v_cvt_pk_bf16_f32 v7, v2, v3
	global_store_dwordx4 v[16:17], v[4:7], off offset:256 sc1

.LBB0_674:
	v_mov_b32_e32 v128, v192
	s_lshl_b32 s7, s84, 8
	v_and_b32_e32 v129, 15, v128
	s_lshl_b32 s9, s77, 8
	v_lshrrev_b32_e32 v128, 1, v128
	s_add_i32 s7, s7, s66
	v_and_or_b32 v128, v128, 24, s9
	v_or_b32_e32 v128, s68, v128
	s_mov_b64 s[38:39], -1
	s_mov_b64 s[34:35], 0
	s_cmp_lt_i32 s76, 1
	s_mov_b64 s[36:37], 0
	s_mov_b32 s87, s22
	s_cbranch_scc1 .LBB0_684
	s_cmp_eq_u32 s76, 1
	s_mov_b64 s[36:37], -1
	s_cbranch_scc0 .LBB0_681
	v_cmp_gt_i32_e32 vcc, s58, v128
	v_or_b32_e32 v132, 16, v129
	v_or_b32_e32 v131, 32, v129
	v_or_b32_e32 v130, 48, v129
	s_and_saveexec_b64 s[36:37], vcc
	s_cbranch_execz .LBB0_678
	v_mul_hi_i32 v133, v128, s59
	v_lshrrev_b32_e32 v134, 31, v133
	v_ashrrev_i32_e32 v133, 7, v133
	v_add_u32_e32 v133, v133, v134
	v_mul_i32_i24_e32 v134, 0x810, v133
	v_lshlrev_b32_e32 v133, 4, v133
	s_ashr_i32 s9, s7, 6
	v_sub_u32_e32 v138, v128, v134
	v_add_u32_e32 v134, s9, v133
	v_ashrrev_i32_e32 v135, 31, v134
	v_readlane_b32 s22, v253, 38
	v_lshlrev_b64 v[140:141], 6, v[134:135]
	v_readlane_b32 s23, v253, 39
	v_or_b32_e32 v144, v140, v129
	v_ashrrev_i32_e32 v139, 31, v138
	v_mov_b64_e32 v[142:143], s[22:23]
	v_mad_u64_u32 v[144:145], s[38:39], v144, s52, v[142:143]
	v_mad_i32_i24 v145, v141, s52, v145
	v_lshlrev_b64 v[138:139], 1, v[138:139]
	v_lshl_add_u64 v[144:145], v[144:145], 0, v[138:139]
	v_cvt_pk_bf16_f32 v134, v124, v125
	v_cvt_pk_bf16_f32 v135, v126, v127
	v_cvt_pk_bf16_f32 v136, v120, v121
	v_cvt_pk_bf16_f32 v137, v122, v123
	global_store_dwordx4 v[144:145], v[134:137], off sc1
	v_or_b32_e32 v144, v140, v132
	v_mad_u64_u32 v[144:145], s[38:39], v144, s52, v[142:143]
	v_mad_i32_i24 v145, v141, s52, v145
	v_lshl_add_u64 v[144:145], v[144:145], 0, v[138:139]
	v_cvt_pk_bf16_f32 v134, v112, v113
	v_cvt_pk_bf16_f32 v135, v114, v115
	v_cvt_pk_bf16_f32 v136, v104, v105
	v_cvt_pk_bf16_f32 v137, v106, v107
	global_store_dwordx4 v[144:145], v[134:137], off sc1
	v_or_b32_e32 v144, v140, v131
	v_mad_u64_u32 v[144:145], s[38:39], v144, s52, v[142:143]
	v_mad_i32_i24 v145, v141, s52, v145
	v_lshl_add_u64 v[144:145], v[144:145], 0, v[138:139]
	v_or_b32_e32 v140, v140, v130
	v_cvt_pk_bf16_f32 v134, v96, v97
	v_cvt_pk_bf16_f32 v135, v98, v99
	v_cvt_pk_bf16_f32 v136, v88, v89
	v_cvt_pk_bf16_f32 v137, v90, v91
	global_store_dwordx4 v[144:145], v[134:137], off sc1
	v_mad_u64_u32 v[144:145], s[38:39], v140, s52, v[142:143]
	v_mad_i32_i24 v145, v141, s52, v145
	s_add_i32 s9, s7, 0x80
	v_cvt_pk_bf16_f32 v134, v80, v81
	v_lshl_add_u64 v[140:141], v[144:145], 0, v[138:139]
	s_ashr_i32 s9, s9, 6
	v_cvt_pk_bf16_f32 v135, v82, v83
	v_cvt_pk_bf16_f32 v136, v72, v73
	v_cvt_pk_bf16_f32 v137, v74, v75
	global_store_dwordx4 v[140:141], v[134:137], off sc1
	s_nop 1
	v_add_u32_e32 v134, s9, v133
	v_ashrrev_i32_e32 v135, 31, v134
	v_lshlrev_b64 v[140:141], 6, v[134:135]
	v_or_b32_e32 v133, v140, v129
	v_mad_u64_u32 v[144:145], s[38:39], v133, s52, v[142:143]
	v_mad_i32_i24 v145, v141, s52, v145
	v_lshl_add_u64 v[144:145], v[144:145], 0, v[138:139]
	v_or_b32_e32 v133, v140, v132
	v_cvt_pk_bf16_f32 v134, v60, v61
	v_cvt_pk_bf16_f32 v135, v62, v63
	v_cvt_pk_bf16_f32 v136, v56, v57
	v_cvt_pk_bf16_f32 v137, v58, v59
	global_store_dwordx4 v[144:145], v[134:137], off sc1
	v_mad_u64_u32 v[144:145], s[38:39], v133, s52, v[142:143]
	v_mad_i32_i24 v145, v141, s52, v145
	v_lshl_add_u64 v[144:145], v[144:145], 0, v[138:139]
	v_or_b32_e32 v133, v140, v131
	v_cvt_pk_bf16_f32 v134, v48, v49
	v_cvt_pk_bf16_f32 v135, v50, v51
	v_cvt_pk_bf16_f32 v136, v40, v41
	v_cvt_pk_bf16_f32 v137, v42, v43
	global_store_dwordx4 v[144:145], v[134:137], off sc1
	v_mad_u64_u32 v[144:145], s[38:39], v133, s52, v[142:143]
	v_or_b32_e32 v133, v140, v130
	v_mad_u64_u32 v[142:143], s[38:39], v133, s52, v[142:143]
	v_mad_i32_i24 v145, v141, s52, v145
	v_mad_i32_i24 v143, v141, s52, v143
	v_cvt_pk_bf16_f32 v134, v32, v33
	v_cvt_pk_bf16_f32 v135, v34, v35
	v_cvt_pk_bf16_f32 v136, v24, v25
	v_cvt_pk_bf16_f32 v137, v26, v27
	v_lshl_add_u64 v[144:145], v[144:145], 0, v[138:139]
	v_lshl_add_u64 v[138:139], v[142:143], 0, v[138:139]
	global_store_dwordx4 v[144:145], v[134:137], off sc1
	s_nop 1
	v_cvt_pk_bf16_f32 v134, v16, v17
	v_cvt_pk_bf16_f32 v135, v18, v19
	v_cvt_pk_bf16_f32 v136, v8, v9
	v_cvt_pk_bf16_f32 v137, v10, v11
	global_store_dwordx4 v[138:139], v[134:137], off sc1
.LBB0_678:
	s_or_b64 exec, exec, s[36:37]
	v_or_b32_e32 v133, 0x80, v128
	v_cmp_gt_i32_e32 vcc, s58, v133
	s_and_saveexec_b64 s[36:37], vcc
	s_cbranch_execz .LBB0_680
	v_mul_hi_i32 v134, v133, s59
	v_lshrrev_b32_e32 v135, 31, v134
	v_ashrrev_i32_e32 v134, 7, v134
	v_add_u32_e32 v134, v134, v135
	v_mul_i32_i24_e32 v135, 0x810, v134
	v_sub_u32_e32 v138, v133, v135
	v_lshlrev_b32_e32 v133, 4, v134
	s_ashr_i32 s9, s7, 6
	v_add_u32_e32 v134, s9, v133
	v_ashrrev_i32_e32 v135, 31, v134
	v_readlane_b32 s22, v253, 38
	v_lshlrev_b64 v[140:141], 6, v[134:135]
	v_readlane_b32 s23, v253, 39
	v_or_b32_e32 v144, v140, v129
	v_ashrrev_i32_e32 v139, 31, v138
	v_mov_b64_e32 v[142:143], s[22:23]
	v_mad_u64_u32 v[144:145], s[38:39], v144, s52, v[142:143]
	v_mad_i32_i24 v145, v141, s52, v145
	v_lshlrev_b64 v[138:139], 1, v[138:139]
	v_lshl_add_u64 v[144:145], v[144:145], 0, v[138:139]
	v_cvt_pk_bf16_f32 v134, v116, v117
	v_cvt_pk_bf16_f32 v135, v118, v119
	v_cvt_pk_bf16_f32 v136, v108, v109
	v_cvt_pk_bf16_f32 v137, v110, v111
	global_store_dwordx4 v[144:145], v[134:137], off sc1
	v_or_b32_e32 v144, v140, v132
	v_mad_u64_u32 v[144:145], s[38:39], v144, s52, v[142:143]
	v_mad_i32_i24 v145, v141, s52, v145
	v_lshl_add_u64 v[144:145], v[144:145], 0, v[138:139]
	v_cvt_pk_bf16_f32 v134, v100, v101
	v_cvt_pk_bf16_f32 v135, v102, v103
	v_cvt_pk_bf16_f32 v136, v92, v93
	v_cvt_pk_bf16_f32 v137, v94, v95
	global_store_dwordx4 v[144:145], v[134:137], off sc1
	v_or_b32_e32 v144, v140, v131
	v_mad_u64_u32 v[144:145], s[38:39], v144, s52, v[142:143]
	v_mad_i32_i24 v145, v141, s52, v145
	v_lshl_add_u64 v[144:145], v[144:145], 0, v[138:139]
	v_or_b32_e32 v140, v140, v130
	v_cvt_pk_bf16_f32 v134, v84, v85
	v_cvt_pk_bf16_f32 v135, v86, v87
	v_cvt_pk_bf16_f32 v136, v76, v77
	v_cvt_pk_bf16_f32 v137, v78, v79
	global_store_dwordx4 v[144:145], v[134:137], off sc1
	v_mad_u64_u32 v[144:145], s[38:39], v140, s52, v[142:143]
	v_mad_i32_i24 v145, v141, s52, v145
	s_add_i32 s9, s7, 0x80
	v_cvt_pk_bf16_f32 v134, v68, v69
	v_lshl_add_u64 v[140:141], v[144:145], 0, v[138:139]
	s_ashr_i32 s9, s9, 6
	v_cvt_pk_bf16_f32 v135, v70, v71
	v_cvt_pk_bf16_f32 v136, v64, v65
	v_cvt_pk_bf16_f32 v137, v66, v67
	global_store_dwordx4 v[140:141], v[134:137], off sc1
	s_nop 1
	v_add_u32_e32 v134, s9, v133
	v_ashrrev_i32_e32 v135, 31, v134
	v_lshlrev_b64 v[140:141], 6, v[134:135]
	v_or_b32_e32 v133, v140, v129
	v_mad_u64_u32 v[144:145], s[38:39], v133, s52, v[142:143]
	v_or_b32_e32 v132, v140, v132
	v_mad_i32_i24 v145, v141, s52, v145
	v_mad_u64_u32 v[132:133], s[38:39], v132, s52, v[142:143]
	v_cvt_pk_bf16_f32 v134, v52, v53
	v_cvt_pk_bf16_f32 v135, v54, v55
	v_cvt_pk_bf16_f32 v136, v44, v45
	v_cvt_pk_bf16_f32 v137, v46, v47
	v_lshl_add_u64 v[144:145], v[144:145], 0, v[138:139]
	v_mad_i32_i24 v133, v141, s52, v133
	global_store_dwordx4 v[144:145], v[134:137], off sc1
	v_lshl_add_u64 v[132:133], v[132:133], 0, v[138:139]
	v_or_b32_e32 v131, v140, v131
	v_cvt_pk_bf16_f32 v134, v36, v37
	v_cvt_pk_bf16_f32 v135, v38, v39
	v_cvt_pk_bf16_f32 v136, v28, v29
	v_cvt_pk_bf16_f32 v137, v30, v31
	v_or_b32_e32 v130, v140, v130
	global_store_dwordx4 v[132:133], v[134:137], off sc1
	v_cvt_pk_bf16_f32 v132, v20, v21
	v_cvt_pk_bf16_f32 v133, v22, v23
	s_nop 1
	v_mad_u64_u32 v[136:137], s[38:39], v131, s52, v[142:143]
	v_mad_u64_u32 v[130:131], s[38:39], v130, s52, v[142:143]
	v_mad_i32_i24 v137, v141, s52, v137
	v_mad_i32_i24 v131, v141, s52, v131
	v_cvt_pk_bf16_f32 v134, v12, v13
	v_cvt_pk_bf16_f32 v135, v14, v15
	v_lshl_add_u64 v[136:137], v[136:137], 0, v[138:139]
	v_lshl_add_u64 v[130:131], v[130:131], 0, v[138:139]
	global_store_dwordx4 v[136:137], v[132:135], off sc1
	s_nop 1
	v_cvt_pk_bf16_f32 v132, v4, v5
	v_cvt_pk_bf16_f32 v133, v6, v7
	v_cvt_pk_bf16_f32 v134, v0, v1
	v_cvt_pk_bf16_f32 v135, v2, v3
	global_store_dwordx4 v[130:131], v[132:135], off sc1

.LBB0_687:
	s_cmp_eq_u32 s76, 2
	s_cselect_b64 s[34:35], -1, 0
	s_cmp_lt_i32 s77, 4
	v_or_b32_e32 v136, s7, v129
	s_cselect_b64 s[38:39], -1, 0
	s_and_b64 s[38:39], s[34:35], s[38:39]
	v_or_b32_e32 v134, 16, v136
	v_or_b32_e32 v132, 32, v136
	v_or_b32_e32 v130, 48, v136
	s_mov_b64 s[34:35], -1
	s_andn2_b64 vcc, exec, s[38:39]
	v_ashrrev_i32_e32 v129, 31, v128
	v_ashrrev_i32_e32 v137, 31, v136
	v_ashrrev_i32_e32 v135, 31, v134
	v_ashrrev_i32_e32 v133, 31, v132
	v_ashrrev_i32_e32 v131, 31, v130
	s_cbranch_vccz .LBB0_689
	s_cmp_eq_u32 s76, 0
	s_cselect_b32 s7, 10, 11
	v_lshl_add_u64 v[138:139], v[128:129], 1, s[36:37]
	v_lshlrev_b64 v[140:141], s7, v[136:137]
	v_lshl_add_u64 v[144:145], v[140:141], 1, v[138:139]
	v_cvt_pk_bf16_f32 v140, v124, v125
	v_cvt_pk_bf16_f32 v141, v126, v127
	v_cvt_pk_bf16_f32 v142, v120, v121
	v_cvt_pk_bf16_f32 v143, v122, v123
	global_store_dwordx4 v[144:145], v[140:143], off sc1
	s_mov_b64 s[34:35], 0
	s_nop 0
	v_cvt_pk_bf16_f32 v140, v116, v117
	v_cvt_pk_bf16_f32 v141, v118, v119
	v_cvt_pk_bf16_f32 v142, v108, v109
	v_cvt_pk_bf16_f32 v143, v110, v111
	global_store_dwordx4 v[144:145], v[140:143], off offset:256 sc1
	s_nop 1
	v_lshlrev_b64 v[140:141], s7, v[134:135]
	v_lshl_add_u64 v[144:145], v[140:141], 1, v[138:139]
	v_cvt_pk_bf16_f32 v140, v112, v113
	v_cvt_pk_bf16_f32 v141, v114, v115
	v_cvt_pk_bf16_f32 v142, v104, v105
	v_cvt_pk_bf16_f32 v143, v106, v107
	global_store_dwordx4 v[144:145], v[140:143], off sc1
	s_nop 1
	v_cvt_pk_bf16_f32 v140, v100, v101
	v_cvt_pk_bf16_f32 v141, v102, v103
	v_cvt_pk_bf16_f32 v142, v92, v93
	v_cvt_pk_bf16_f32 v143, v94, v95
	global_store_dwordx4 v[144:145], v[140:143], off offset:256 sc1
	s_nop 1
	v_lshlrev_b64 v[140:141], s7, v[132:133]
	v_lshl_add_u64 v[144:145], v[140:141], 1, v[138:139]
	v_cvt_pk_bf16_f32 v140, v96, v97
	v_cvt_pk_bf16_f32 v141, v98, v99
	v_cvt_pk_bf16_f32 v142, v88, v89
	v_cvt_pk_bf16_f32 v143, v90, v91
	global_store_dwordx4 v[144:145], v[140:143], off sc1
	s_nop 1
	v_cvt_pk_bf16_f32 v140, v84, v85
	v_cvt_pk_bf16_f32 v141, v86, v87
	v_cvt_pk_bf16_f32 v142, v76, v77
	v_cvt_pk_bf16_f32 v143, v78, v79
	global_store_dwordx4 v[144:145], v[140:143], off offset:256 sc1
	s_nop 1
	v_lshlrev_b64 v[140:141], s7, v[130:131]
	v_lshl_add_u64 v[144:145], v[140:141], 1, v[138:139]
	v_cvt_pk_bf16_f32 v140, v80, v81
	v_cvt_pk_bf16_f32 v141, v82, v83
	v_cvt_pk_bf16_f32 v142, v72, v73
	v_cvt_pk_bf16_f32 v143, v74, v75
	global_store_dwordx4 v[144:145], v[140:143], off sc1
	s_nop 1
	v_cvt_pk_bf16_f32 v140, v68, v69
	v_cvt_pk_bf16_f32 v141, v70, v71
	v_cvt_pk_bf16_f32 v142, v64, v65
	v_cvt_pk_bf16_f32 v143, v66, v67
	global_store_dwordx4 v[144:145], v[140:143], off offset:256 sc1
	s_nop 1
	v_add_u32_e32 v140, 0x80, v136
	v_ashrrev_i32_e32 v141, 31, v140
	v_lshlrev_b64 v[140:141], s7, v[140:141]
	v_lshl_add_u64 v[144:145], v[140:141], 1, v[138:139]
	v_cvt_pk_bf16_f32 v140, v60, v61
	v_cvt_pk_bf16_f32 v141, v62, v63
	v_cvt_pk_bf16_f32 v142, v56, v57
	v_cvt_pk_bf16_f32 v143, v58, v59
	global_store_dwordx4 v[144:145], v[140:143], off sc1
	s_nop 1
	v_cvt_pk_bf16_f32 v140, v52, v53
	v_cvt_pk_bf16_f32 v141, v54, v55
	v_cvt_pk_bf16_f32 v142, v44, v45
	v_cvt_pk_bf16_f32 v143, v46, v47
	global_store_dwordx4 v[144:145], v[140:143], off offset:256 sc1
	s_nop 1
	v_add_u32_e32 v140, 0x90, v136
	v_ashrrev_i32_e32 v141, 31, v140
	v_lshlrev_b64 v[140:141], s7, v[140:141]
	v_lshl_add_u64 v[144:145], v[140:141], 1, v[138:139]
	v_cvt_pk_bf16_f32 v140, v48, v49
	v_cvt_pk_bf16_f32 v141, v50, v51
	v_cvt_pk_bf16_f32 v142, v40, v41
	v_cvt_pk_bf16_f32 v143, v42, v43
	global_store_dwordx4 v[144:145], v[140:143], off sc1
	s_nop 1
	v_cvt_pk_bf16_f32 v140, v36, v37
	v_cvt_pk_bf16_f32 v141, v38, v39
	v_cvt_pk_bf16_f32 v142, v28, v29
	v_cvt_pk_bf16_f32 v143, v30, v31
	global_store_dwordx4 v[144:145], v[140:143], off offset:256 sc1
	s_nop 1
	v_add_u32_e32 v140, 0xa0, v136
	v_ashrrev_i32_e32 v141, 31, v140
	v_lshlrev_b64 v[140:141], s7, v[140:141]
	v_lshl_add_u64 v[144:145], v[140:141], 1, v[138:139]
	v_cvt_pk_bf16_f32 v140, v32, v33
	v_cvt_pk_bf16_f32 v141, v34, v35
	v_cvt_pk_bf16_f32 v142, v24, v25
	v_cvt_pk_bf16_f32 v143, v26, v27
	global_store_dwordx4 v[144:145], v[140:143], off sc1
	s_nop 1
	v_cvt_pk_bf16_f32 v140, v20, v21
	v_cvt_pk_bf16_f32 v141, v22, v23
	v_cvt_pk_bf16_f32 v142, v12, v13
	v_cvt_pk_bf16_f32 v143, v14, v15
	global_store_dwordx4 v[144:145], v[140:143], off offset:256 sc1
	s_nop 1
	v_add_u32_e32 v140, 0xb0, v136
	v_ashrrev_i32_e32 v141, 31, v140
	v_lshlrev_b64 v[140:141], s7, v[140:141]
	v_lshl_add_u64 v[142:143], v[140:141], 1, v[138:139]
	v_cvt_pk_bf16_f32 v138, v16, v17
	v_cvt_pk_bf16_f32 v139, v18, v19
	v_cvt_pk_bf16_f32 v140, v8, v9
	v_cvt_pk_bf16_f32 v141, v10, v11
	global_store_dwordx4 v[142:143], v[138:141], off sc1
	s_nop 1
	v_cvt_pk_bf16_f32 v138, v4, v5
	v_cvt_pk_bf16_f32 v139, v6, v7
	v_cvt_pk_bf16_f32 v140, v0, v1
	v_cvt_pk_bf16_f32 v141, v2, v3
	global_store_dwordx4 v[142:143], v[138:141], off offset:256 sc1
.LBB0_689:
	s_andn2_b64 vcc, exec, s[34:35]
	s_cbranch_vccnz .LBB0_691
	v_lshl_add_u64 v[138:139], v[128:129], 1, s[36:37]
	v_lshlrev_b64 v[128:129], 12, v[136:137]
	v_lshl_add_u64 v[128:129], v[138:139], 0, v[128:129]
	v_pk_mul_f32 v[126:127], v[126:127], s[48:49] op_sel_hi:[1,0]
	v_pk_mul_f32 v[124:125], v[124:125], s[48:49] op_sel_hi:[1,0]
	v_pk_mul_f32 v[136:137], v[122:123], s[48:49] op_sel_hi:[1,0]
	v_pk_mul_f32 v[122:123], v[120:121], s[48:49] op_sel_hi:[1,0]
	v_cvt_pk_bf16_f32 v120, v124, v125
	v_cvt_pk_bf16_f32 v121, v126, v127
	v_pk_mul_f32 v[118:119], v[118:119], s[48:49] op_sel_hi:[1,0]
	v_cvt_pk_bf16_f32 v122, v122, v123
	v_cvt_pk_bf16_f32 v123, v136, v137
	global_store_dwordx4 v[128:129], v[120:123], off sc1
	v_pk_mul_f32 v[116:117], v[116:117], s[48:49] op_sel_hi:[1,0]
	v_pk_mul_f32 v[112:113], v[112:113], s[48:49] op_sel_hi:[1,0]
	v_pk_mul_f32 v[120:121], v[110:111], s[48:49] op_sel_hi:[1,0]
	v_pk_mul_f32 v[110:111], v[108:109], s[48:49] op_sel_hi:[1,0]
	v_cvt_pk_bf16_f32 v108, v116, v117
	v_cvt_pk_bf16_f32 v109, v118, v119
	v_pk_mul_f32 v[102:103], v[102:103], s[48:49] op_sel_hi:[1,0]
	v_cvt_pk_bf16_f32 v110, v110, v111
	v_cvt_pk_bf16_f32 v111, v120, v121
	global_store_dwordx4 v[128:129], v[108:111], off offset:256 sc1
	v_pk_mul_f32 v[100:101], v[100:101], s[48:49] op_sel_hi:[1,0]
	v_pk_mul_f32 v[96:97], v[96:97], s[48:49] op_sel_hi:[1,0]
	v_lshlrev_b64 v[108:109], 12, v[134:135]
	v_lshl_add_u64 v[108:109], v[138:139], 0, v[108:109]
	v_pk_mul_f32 v[110:111], v[114:115], s[48:49] op_sel_hi:[1,0]
	v_pk_mul_f32 v[114:115], v[106:107], s[48:49] op_sel_hi:[1,0]
	v_pk_mul_f32 v[106:107], v[104:105], s[48:49] op_sel_hi:[1,0]
	v_cvt_pk_bf16_f32 v104, v112, v113
	v_cvt_pk_bf16_f32 v105, v110, v111
	v_pk_mul_f32 v[86:87], v[86:87], s[48:49] op_sel_hi:[1,0]
	v_cvt_pk_bf16_f32 v106, v106, v107
	v_cvt_pk_bf16_f32 v107, v114, v115
	global_store_dwordx4 v[108:109], v[104:107], off sc1
	v_pk_mul_f32 v[84:85], v[84:85], s[48:49] op_sel_hi:[1,0]
	v_pk_mul_f32 v[80:81], v[80:81], s[48:49] op_sel_hi:[1,0]
	v_pk_mul_f32 v[104:105], v[94:95], s[48:49] op_sel_hi:[1,0]
	v_pk_mul_f32 v[94:95], v[92:93], s[48:49] op_sel_hi:[1,0]
	v_cvt_pk_bf16_f32 v92, v100, v101
	v_cvt_pk_bf16_f32 v93, v102, v103
	v_pk_mul_f32 v[70:71], v[70:71], s[48:49] op_sel_hi:[1,0]
	v_cvt_pk_bf16_f32 v94, v94, v95
	v_cvt_pk_bf16_f32 v95, v104, v105
	global_store_dwordx4 v[108:109], v[92:95], off offset:256 sc1
	v_pk_mul_f32 v[68:69], v[68:69], s[48:49] op_sel_hi:[1,0]
	v_pk_mul_f32 v[60:61], v[60:61], s[48:49] op_sel_hi:[1,0]
	v_lshlrev_b64 v[92:93], 12, v[132:133]
	v_lshl_add_u64 v[92:93], v[138:139], 0, v[92:93]
	v_pk_mul_f32 v[94:95], v[98:99], s[48:49] op_sel_hi:[1,0]
	v_pk_mul_f32 v[98:99], v[90:91], s[48:49] op_sel_hi:[1,0]
	v_pk_mul_f32 v[90:91], v[88:89], s[48:49] op_sel_hi:[1,0]
	v_cvt_pk_bf16_f32 v88, v96, v97
	v_cvt_pk_bf16_f32 v89, v94, v95
	s_mov_b32 s7, 0x80000
	v_cvt_pk_bf16_f32 v90, v90, v91
	v_cvt_pk_bf16_f32 v91, v98, v99
	global_store_dwordx4 v[92:93], v[88:91], off sc1
	v_pk_mul_f32 v[62:63], v[62:63], s[48:49] op_sel_hi:[1,0]
	s_mov_b64 s[34:35], 0x80000
	v_pk_mul_f32 v[88:89], v[78:79], s[48:49] op_sel_hi:[1,0]
	v_pk_mul_f32 v[78:79], v[76:77], s[48:49] op_sel_hi:[1,0]
	v_cvt_pk_bf16_f32 v76, v84, v85
	v_cvt_pk_bf16_f32 v77, v86, v87
	v_pk_mul_f32 v[54:55], v[54:55], s[48:49] op_sel_hi:[1,0]
	v_cvt_pk_bf16_f32 v78, v78, v79
	v_cvt_pk_bf16_f32 v79, v88, v89
	global_store_dwordx4 v[92:93], v[76:79], off offset:256 sc1
	v_pk_mul_f32 v[52:53], v[52:53], s[48:49] op_sel_hi:[1,0]
	v_pk_mul_f32 v[48:49], v[48:49], s[48:49] op_sel_hi:[1,0]
	v_lshlrev_b64 v[76:77], 12, v[130:131]
	v_lshl_add_u64 v[76:77], v[138:139], 0, v[76:77]
	v_pk_mul_f32 v[78:79], v[82:83], s[48:49] op_sel_hi:[1,0]
	v_pk_mul_f32 v[82:83], v[74:75], s[48:49] op_sel_hi:[1,0]
	v_pk_mul_f32 v[74:75], v[72:73], s[48:49] op_sel_hi:[1,0]
	v_cvt_pk_bf16_f32 v72, v80, v81
	v_cvt_pk_bf16_f32 v73, v78, v79
	v_pk_mul_f32 v[38:39], v[38:39], s[48:49] op_sel_hi:[1,0]
	v_cvt_pk_bf16_f32 v74, v74, v75
	v_cvt_pk_bf16_f32 v75, v82, v83
	global_store_dwordx4 v[76:77], v[72:75], off sc1
	v_pk_mul_f32 v[36:37], v[36:37], s[48:49] op_sel_hi:[1,0]
	v_pk_mul_f32 v[32:33], v[32:33], s[48:49] op_sel_hi:[1,0]
	v_pk_mul_f32 v[72:73], v[66:67], s[48:49] op_sel_hi:[1,0]
	v_pk_mul_f32 v[66:67], v[64:65], s[48:49] op_sel_hi:[1,0]
	v_cvt_pk_bf16_f32 v64, v68, v69
	v_cvt_pk_bf16_f32 v65, v70, v71
	v_pk_mul_f32 v[22:23], v[22:23], s[48:49] op_sel_hi:[1,0]
	v_cvt_pk_bf16_f32 v66, v66, v67
	v_cvt_pk_bf16_f32 v67, v72, v73
	global_store_dwordx4 v[76:77], v[64:67], off offset:256 sc1
	v_pk_mul_f32 v[20:21], v[20:21], s[48:49] op_sel_hi:[1,0]
	v_pk_mul_f32 v[16:17], v[16:17], s[48:49] op_sel_hi:[1,0]
	v_pk_mul_f32 v[66:67], v[58:59], s[48:49] op_sel_hi:[1,0]
	v_pk_mul_f32 v[58:59], v[56:57], s[48:49] op_sel_hi:[1,0]
	v_cvt_pk_bf16_f32 v56, v60, v61
	v_add_co_u32_e32 v60, vcc, s7, v128
	v_cvt_pk_bf16_f32 v57, v62, v63
	v_cvt_pk_bf16_f32 v58, v58, v59
	v_cvt_pk_bf16_f32 v59, v66, v67
	v_lshl_add_u64 v[64:65], v[128:129], 0, s[34:35]
	s_nop 0
	v_addc_co_u32_e32 v61, vcc, 0, v129, vcc
	global_store_dwordx4 v[60:61], v[56:59], off sc1
	s_mov_b32 s7, 0x90000
	s_mov_b64 s[34:35], 0x90000
	v_pk_mul_f32 v[56:57], v[46:47], s[48:49] op_sel_hi:[1,0]
	v_pk_mul_f32 v[46:47], v[44:45], s[48:49] op_sel_hi:[1,0]
	v_cvt_pk_bf16_f32 v44, v52, v53
	v_cvt_pk_bf16_f32 v45, v54, v55
	v_pk_mul_f32 v[6:7], v[6:7], s[48:49] op_sel_hi:[1,0]
	v_cvt_pk_bf16_f32 v46, v46, v47
	v_cvt_pk_bf16_f32 v47, v56, v57
	global_store_dwordx4 v[64:65], v[44:47], off offset:256 sc1
	v_pk_mul_f32 v[4:5], v[4:5], s[48:49] op_sel_hi:[1,0]
	s_nop 0
	v_pk_mul_f32 v[46:47], v[50:51], s[48:49] op_sel_hi:[1,0]
	v_pk_mul_f32 v[50:51], v[42:43], s[48:49] op_sel_hi:[1,0]
	v_pk_mul_f32 v[42:43], v[40:41], s[48:49] op_sel_hi:[1,0]
	v_cvt_pk_bf16_f32 v40, v48, v49
	v_cvt_pk_bf16_f32 v41, v46, v47
	v_add_co_u32_e32 v46, vcc, s7, v128
	v_cvt_pk_bf16_f32 v42, v42, v43
	v_cvt_pk_bf16_f32 v43, v50, v51
	v_lshl_add_u64 v[44:45], v[128:129], 0, s[34:35]
	s_nop 0
	v_addc_co_u32_e32 v47, vcc, 0, v129, vcc
	global_store_dwordx4 v[46:47], v[40:43], off sc1
	s_mov_b32 s7, 0xa0000
	s_mov_b64 s[34:35], 0xa0000
	v_pk_mul_f32 v[40:41], v[30:31], s[48:49] op_sel_hi:[1,0]
	v_pk_mul_f32 v[30:31], v[28:29], s[48:49] op_sel_hi:[1,0]
	v_cvt_pk_bf16_f32 v28, v36, v37
	v_cvt_pk_bf16_f32 v29, v38, v39
	s_nop 0
	v_cvt_pk_bf16_f32 v30, v30, v31
	v_cvt_pk_bf16_f32 v31, v40, v41
	global_store_dwordx4 v[44:45], v[28:31], off offset:256 sc1
	s_nop 1
	v_pk_mul_f32 v[30:31], v[34:35], s[48:49] op_sel_hi:[1,0]
	v_pk_mul_f32 v[34:35], v[26:27], s[48:49] op_sel_hi:[1,0]
	v_pk_mul_f32 v[26:27], v[24:25], s[48:49] op_sel_hi:[1,0]
	v_cvt_pk_bf16_f32 v24, v32, v33
	v_cvt_pk_bf16_f32 v25, v30, v31
	v_add_co_u32_e32 v30, vcc, s7, v128
	v_cvt_pk_bf16_f32 v26, v26, v27
	v_cvt_pk_bf16_f32 v27, v34, v35
	v_lshl_add_u64 v[28:29], v[128:129], 0, s[34:35]
	s_nop 0
	v_addc_co_u32_e32 v31, vcc, 0, v129, vcc
	global_store_dwordx4 v[30:31], v[24:27], off sc1
	s_mov_b32 s7, 0xb0000
	s_mov_b64 s[34:35], 0xb0000
	v_pk_mul_f32 v[24:25], v[14:15], s[48:49] op_sel_hi:[1,0]
	v_pk_mul_f32 v[14:15], v[12:13], s[48:49] op_sel_hi:[1,0]
	v_cvt_pk_bf16_f32 v12, v20, v21
	v_cvt_pk_bf16_f32 v13, v22, v23
	s_nop 0
	v_cvt_pk_bf16_f32 v14, v14, v15
	v_cvt_pk_bf16_f32 v15, v24, v25
	global_store_dwordx4 v[28:29], v[12:15], off offset:256 sc1
	s_nop 1
	v_pk_mul_f32 v[14:15], v[18:19], s[48:49] op_sel_hi:[1,0]
	v_pk_mul_f32 v[18:19], v[10:11], s[48:49] op_sel_hi:[1,0]
	v_pk_mul_f32 v[10:11], v[8:9], s[48:49] op_sel_hi:[1,0]
	v_cvt_pk_bf16_f32 v8, v16, v17
	v_cvt_pk_bf16_f32 v9, v14, v15
	v_add_co_u32_e32 v14, vcc, s7, v128
	v_lshl_add_u64 v[12:13], v[128:129], 0, s[34:35]
	s_nop 0
	v_addc_co_u32_e32 v15, vcc, 0, v129, vcc
	v_cvt_pk_bf16_f32 v10, v10, v11
	v_cvt_pk_bf16_f32 v11, v18, v19
	global_store_dwordx4 v[14:15], v[8:11], off sc1
	s_nop 1
	v_pk_mul_f32 v[8:9], v[2:3], s[48:49] op_sel_hi:[1,0]
	v_pk_mul_f32 v[2:3], v[0:1], s[48:49] op_sel_hi:[1,0]
	v_cvt_pk_bf16_f32 v0, v4, v5
	v_cvt_pk_bf16_f32 v1, v6, v7
	s_nop 0
	v_cvt_pk_bf16_f32 v2, v2, v3
	v_cvt_pk_bf16_f32 v3, v8, v9
	global_store_dwordx4 v[12:13], v[0:3], off offset:256 sc1

.LBB0_750:
	v_mov_b32_e32 v128, v192
	s_lshl_b32 s15, s60, 8
	s_add_i32 s15, s15, s38
	v_and_or_b32 v132, v128, 15, s15
	s_lshl_b32 s15, s57, 8
	v_lshrrev_b32_e32 v128, 1, v128
	v_and_or_b32 v128, v128, 24, s15
	v_ashrrev_i32_e32 v133, 31, v132
	v_or_b32_e32 v138, 16, v132
	v_or_b32_e32 v136, 32, v132
	v_or_b32_e32 v134, 48, v132
	v_or_b32_e32 v140, s44, v128
	s_cmp_gt_i32 s57, 3
	v_lshlrev_b64 v[142:143], 12, v[132:133]
	s_mov_b64 s[22:23], -1
	v_ashrrev_i32_e32 v139, 31, v138
	v_ashrrev_i32_e32 v137, 31, v136
	v_ashrrev_i32_e32 v135, 31, v134
	s_cbranch_scc0 .LBB0_752
	v_mov_b32_e32 v141, v173
	v_lshl_add_u64 v[130:131], v[140:141], 1, s[10:11]
	v_lshl_add_u64 v[128:129], v[130:131], 0, v[142:143]
	v_cvt_pk_bf16_f32 v144, v124, v125
	v_cvt_pk_bf16_f32 v145, v126, v127
	v_cvt_pk_bf16_f32 v146, v120, v121
	v_cvt_pk_bf16_f32 v147, v122, v123
	global_store_dwordx4 v[128:129], v[144:147], off sc1
	s_mov_b32 s15, 0x80000
	s_mov_b64 s[22:23], 0x80000
	v_cvt_pk_bf16_f32 v144, v116, v117
	v_cvt_pk_bf16_f32 v145, v118, v119
	v_cvt_pk_bf16_f32 v146, v108, v109
	v_cvt_pk_bf16_f32 v147, v110, v111
	global_store_dwordx4 v[128:129], v[144:147], off offset:256 sc1
	s_nop 1
	v_lshlrev_b64 v[144:145], 12, v[138:139]
	v_lshl_add_u64 v[148:149], v[130:131], 0, v[144:145]
	v_cvt_pk_bf16_f32 v144, v112, v113
	v_cvt_pk_bf16_f32 v145, v114, v115
	v_cvt_pk_bf16_f32 v146, v104, v105
	v_cvt_pk_bf16_f32 v147, v106, v107
	global_store_dwordx4 v[148:149], v[144:147], off sc1
	s_nop 1
	v_cvt_pk_bf16_f32 v144, v100, v101
	v_cvt_pk_bf16_f32 v145, v102, v103
	v_cvt_pk_bf16_f32 v146, v92, v93
	v_cvt_pk_bf16_f32 v147, v94, v95
	global_store_dwordx4 v[148:149], v[144:147], off offset:256 sc1
	s_nop 1
	v_lshlrev_b64 v[144:145], 12, v[136:137]
	v_lshl_add_u64 v[148:149], v[130:131], 0, v[144:145]
	v_cvt_pk_bf16_f32 v144, v96, v97
	v_cvt_pk_bf16_f32 v145, v98, v99
	v_cvt_pk_bf16_f32 v146, v88, v89
	v_cvt_pk_bf16_f32 v147, v90, v91
	global_store_dwordx4 v[148:149], v[144:147], off sc1
	s_nop 1
	v_cvt_pk_bf16_f32 v144, v84, v85
	v_cvt_pk_bf16_f32 v145, v86, v87
	v_cvt_pk_bf16_f32 v146, v76, v77
	v_cvt_pk_bf16_f32 v147, v78, v79
	global_store_dwordx4 v[148:149], v[144:147], off offset:256 sc1
	v_add_co_u32_e32 v148, vcc, s15, v128
	s_nop 0
	v_lshlrev_b64 v[144:145], 12, v[134:135]
	v_lshl_add_u64 v[130:131], v[130:131], 0, v[144:145]
	v_cvt_pk_bf16_f32 v144, v80, v81
	v_cvt_pk_bf16_f32 v145, v82, v83
	v_cvt_pk_bf16_f32 v146, v72, v73
	v_cvt_pk_bf16_f32 v147, v74, v75
	global_store_dwordx4 v[130:131], v[144:147], off sc1
	v_addc_co_u32_e32 v149, vcc, 0, v129, vcc
	s_nop 0
	v_cvt_pk_bf16_f32 v144, v68, v69
	v_cvt_pk_bf16_f32 v145, v70, v71
	v_cvt_pk_bf16_f32 v146, v64, v65
	v_cvt_pk_bf16_f32 v147, v66, v67
	global_store_dwordx4 v[130:131], v[144:147], off offset:256 sc1
	s_mov_b32 s15, 0x90000
	v_lshl_add_u64 v[130:131], v[128:129], 0, s[22:23]
	v_cvt_pk_bf16_f32 v144, v60, v61
	v_cvt_pk_bf16_f32 v145, v62, v63
	v_cvt_pk_bf16_f32 v146, v56, v57
	v_cvt_pk_bf16_f32 v147, v58, v59
	global_store_dwordx4 v[148:149], v[144:147], off sc1
	v_add_co_u32_e32 v148, vcc, s15, v128
	s_nop 0
	v_cvt_pk_bf16_f32 v144, v52, v53
	v_cvt_pk_bf16_f32 v145, v54, v55
	v_cvt_pk_bf16_f32 v146, v44, v45
	v_cvt_pk_bf16_f32 v147, v46, v47
	global_store_dwordx4 v[130:131], v[144:147], off offset:256 sc1
	s_mov_b64 s[22:23], 0x90000
	v_addc_co_u32_e32 v149, vcc, 0, v129, vcc
	v_cvt_pk_bf16_f32 v144, v48, v49
	v_cvt_pk_bf16_f32 v145, v50, v51
	s_mov_b32 s15, 0xa0000
	v_lshl_add_u64 v[130:131], v[128:129], 0, s[22:23]
	v_cvt_pk_bf16_f32 v146, v40, v41
	v_cvt_pk_bf16_f32 v147, v42, v43
	global_store_dwordx4 v[148:149], v[144:147], off sc1
	v_add_co_u32_e32 v148, vcc, s15, v128
	s_nop 0
	v_cvt_pk_bf16_f32 v144, v36, v37
	v_cvt_pk_bf16_f32 v145, v38, v39
	v_cvt_pk_bf16_f32 v146, v28, v29
	v_cvt_pk_bf16_f32 v147, v30, v31
	global_store_dwordx4 v[130:131], v[144:147], off offset:256 sc1
	s_mov_b64 s[22:23], 0xa0000
	v_addc_co_u32_e32 v149, vcc, 0, v129, vcc
	v_cvt_pk_bf16_f32 v144, v32, v33
	v_cvt_pk_bf16_f32 v145, v34, v35
	v_lshl_add_u64 v[130:131], v[128:129], 0, s[22:23]
	v_cvt_pk_bf16_f32 v146, v24, v25
	v_cvt_pk_bf16_f32 v147, v26, v27
	global_store_dwordx4 v[148:149], v[144:147], off sc1
	s_mov_b64 s[22:23], 0xb0000
	s_mov_b32 s15, 0xb0000
	v_cvt_pk_bf16_f32 v144, v20, v21
	v_cvt_pk_bf16_f32 v145, v22, v23
	v_cvt_pk_bf16_f32 v146, v12, v13
	v_cvt_pk_bf16_f32 v147, v14, v15
	global_store_dwordx4 v[130:131], v[144:147], off offset:256 sc1
	s_nop 1
	v_lshl_add_u64 v[144:145], v[128:129], 0, s[22:23]
	v_add_co_u32_e32 v128, vcc, s15, v128
	v_cvt_pk_bf16_f32 v146, v16, v17
	v_cvt_pk_bf16_f32 v147, v18, v19
	v_cvt_pk_bf16_f32 v148, v8, v9
	v_cvt_pk_bf16_f32 v149, v10, v11
	s_nop 1
	v_addc_co_u32_e32 v129, vcc, 0, v129, vcc
	global_store_dwordx4 v[128:129], v[146:149], off sc1
	v_cvt_pk_bf16_f32 v128, v4, v5
	v_cvt_pk_bf16_f32 v129, v6, v7
	v_cvt_pk_bf16_f32 v130, v0, v1
	v_cvt_pk_bf16_f32 v131, v2, v3
	s_cbranch_execnz .LBB0_754
	s_branch .LBB0_753

.LBB0_753:
	v_ashrrev_i32_e32 v141, 31, v140
	v_lshl_add_u64 v[128:129], v[140:141], 1, s[10:11]
	v_lshl_add_u64 v[130:131], v[128:129], 0, v[142:143]
	v_pk_mul_f32 v[126:127], v[126:127], s[48:49] op_sel_hi:[1,0]
	v_pk_mul_f32 v[124:125], v[124:125], s[48:49] op_sel_hi:[1,0]
	v_pk_mul_f32 v[140:141], v[122:123], s[48:49] op_sel_hi:[1,0]
	v_pk_mul_f32 v[122:123], v[120:121], s[48:49] op_sel_hi:[1,0]
	v_cvt_pk_bf16_f32 v120, v124, v125
	v_cvt_pk_bf16_f32 v121, v126, v127
	v_pk_mul_f32 v[118:119], v[118:119], s[48:49] op_sel_hi:[1,0]
	v_cvt_pk_bf16_f32 v122, v122, v123
	v_cvt_pk_bf16_f32 v123, v140, v141
	global_store_dwordx4 v[130:131], v[120:123], off sc1
	v_pk_mul_f32 v[116:117], v[116:117], s[48:49] op_sel_hi:[1,0]
	v_pk_mul_f32 v[112:113], v[112:113], s[48:49] op_sel_hi:[1,0]
	v_pk_mul_f32 v[120:121], v[110:111], s[48:49] op_sel_hi:[1,0]
	v_pk_mul_f32 v[110:111], v[108:109], s[48:49] op_sel_hi:[1,0]
	v_cvt_pk_bf16_f32 v108, v116, v117
	v_cvt_pk_bf16_f32 v109, v118, v119
	v_pk_mul_f32 v[102:103], v[102:103], s[48:49] op_sel_hi:[1,0]
	v_cvt_pk_bf16_f32 v110, v110, v111
	v_cvt_pk_bf16_f32 v111, v120, v121
	global_store_dwordx4 v[130:131], v[108:111], off offset:256 sc1
	v_pk_mul_f32 v[100:101], v[100:101], s[48:49] op_sel_hi:[1,0]
	v_pk_mul_f32 v[96:97], v[96:97], s[48:49] op_sel_hi:[1,0]
	v_lshlrev_b64 v[108:109], 12, v[138:139]
	v_lshl_add_u64 v[108:109], v[128:129], 0, v[108:109]
	v_pk_mul_f32 v[110:111], v[114:115], s[48:49] op_sel_hi:[1,0]
	v_pk_mul_f32 v[114:115], v[106:107], s[48:49] op_sel_hi:[1,0]
	v_pk_mul_f32 v[106:107], v[104:105], s[48:49] op_sel_hi:[1,0]
	v_cvt_pk_bf16_f32 v104, v112, v113
	v_cvt_pk_bf16_f32 v105, v110, v111
	v_pk_mul_f32 v[86:87], v[86:87], s[48:49] op_sel_hi:[1,0]
	v_cvt_pk_bf16_f32 v106, v106, v107
	v_cvt_pk_bf16_f32 v107, v114, v115
	global_store_dwordx4 v[108:109], v[104:107], off sc1
	v_pk_mul_f32 v[84:85], v[84:85], s[48:49] op_sel_hi:[1,0]
	v_pk_mul_f32 v[80:81], v[80:81], s[48:49] op_sel_hi:[1,0]
	v_pk_mul_f32 v[104:105], v[94:95], s[48:49] op_sel_hi:[1,0]
	v_pk_mul_f32 v[94:95], v[92:93], s[48:49] op_sel_hi:[1,0]
	v_cvt_pk_bf16_f32 v92, v100, v101
	v_cvt_pk_bf16_f32 v93, v102, v103
	v_pk_mul_f32 v[70:71], v[70:71], s[48:49] op_sel_hi:[1,0]
	v_cvt_pk_bf16_f32 v94, v94, v95
	v_cvt_pk_bf16_f32 v95, v104, v105
	global_store_dwordx4 v[108:109], v[92:95], off offset:256 sc1
	v_pk_mul_f32 v[68:69], v[68:69], s[48:49] op_sel_hi:[1,0]
	v_pk_mul_f32 v[60:61], v[60:61], s[48:49] op_sel_hi:[1,0]
	v_lshlrev_b64 v[92:93], 12, v[136:137]
	v_lshl_add_u64 v[92:93], v[128:129], 0, v[92:93]
	v_pk_mul_f32 v[94:95], v[98:99], s[48:49] op_sel_hi:[1,0]
	v_pk_mul_f32 v[98:99], v[90:91], s[48:49] op_sel_hi:[1,0]
	v_pk_mul_f32 v[90:91], v[88:89], s[48:49] op_sel_hi:[1,0]
	v_cvt_pk_bf16_f32 v88, v96, v97
	v_cvt_pk_bf16_f32 v89, v94, v95
	s_mov_b32 s15, 0x80000
	v_cvt_pk_bf16_f32 v90, v90, v91
	v_cvt_pk_bf16_f32 v91, v98, v99
	global_store_dwordx4 v[92:93], v[88:91], off sc1
	v_pk_mul_f32 v[62:63], v[62:63], s[48:49] op_sel_hi:[1,0]
	s_mov_b64 s[22:23], 0x80000
	v_pk_mul_f32 v[88:89], v[78:79], s[48:49] op_sel_hi:[1,0]
	v_pk_mul_f32 v[78:79], v[76:77], s[48:49] op_sel_hi:[1,0]
	v_cvt_pk_bf16_f32 v76, v84, v85
	v_cvt_pk_bf16_f32 v77, v86, v87
	v_pk_mul_f32 v[54:55], v[54:55], s[48:49] op_sel_hi:[1,0]
	v_cvt_pk_bf16_f32 v78, v78, v79
	v_cvt_pk_bf16_f32 v79, v88, v89
	global_store_dwordx4 v[92:93], v[76:79], off offset:256 sc1
	v_pk_mul_f32 v[52:53], v[52:53], s[48:49] op_sel_hi:[1,0]
	v_pk_mul_f32 v[48:49], v[48:49], s[48:49] op_sel_hi:[1,0]
	v_lshlrev_b64 v[76:77], 12, v[134:135]
	v_lshl_add_u64 v[76:77], v[128:129], 0, v[76:77]
	v_pk_mul_f32 v[78:79], v[82:83], s[48:49] op_sel_hi:[1,0]
	v_pk_mul_f32 v[82:83], v[74:75], s[48:49] op_sel_hi:[1,0]
	v_pk_mul_f32 v[74:75], v[72:73], s[48:49] op_sel_hi:[1,0]
	v_cvt_pk_bf16_f32 v72, v80, v81
	v_cvt_pk_bf16_f32 v73, v78, v79
	v_pk_mul_f32 v[38:39], v[38:39], s[48:49] op_sel_hi:[1,0]
	v_cvt_pk_bf16_f32 v74, v74, v75
	v_cvt_pk_bf16_f32 v75, v82, v83
	global_store_dwordx4 v[76:77], v[72:75], off sc1
	v_pk_mul_f32 v[36:37], v[36:37], s[48:49] op_sel_hi:[1,0]
	v_pk_mul_f32 v[32:33], v[32:33], s[48:49] op_sel_hi:[1,0]
	v_pk_mul_f32 v[72:73], v[66:67], s[48:49] op_sel_hi:[1,0]
	v_pk_mul_f32 v[66:67], v[64:65], s[48:49] op_sel_hi:[1,0]
	v_cvt_pk_bf16_f32 v64, v68, v69
	v_cvt_pk_bf16_f32 v65, v70, v71
	v_pk_mul_f32 v[68:69], v[58:59], s[48:49] op_sel_hi:[1,0]
	v_cvt_pk_bf16_f32 v66, v66, v67
	v_cvt_pk_bf16_f32 v67, v72, v73
	global_store_dwordx4 v[76:77], v[64:67], off offset:256 sc1
	v_pk_mul_f32 v[58:59], v[56:57], s[48:49] op_sel_hi:[1,0]
	v_cvt_pk_bf16_f32 v56, v60, v61
	v_cvt_pk_bf16_f32 v57, v62, v63
	v_pk_mul_f32 v[22:23], v[22:23], s[48:49] op_sel_hi:[1,0]
	v_lshlrev_b64 v[64:65], 12, v[132:133]
	v_lshl_add_u64 v[64:65], v[128:129], 0, v[64:65]
	v_add_co_u32_e32 v60, vcc, s15, v64
	v_cvt_pk_bf16_f32 v58, v58, v59
	v_cvt_pk_bf16_f32 v59, v68, v69
	v_lshl_add_u64 v[66:67], v[64:65], 0, s[22:23]
	s_nop 0
	v_addc_co_u32_e32 v61, vcc, 0, v65, vcc
	global_store_dwordx4 v[60:61], v[56:59], off sc1
	s_mov_b32 s15, 0x90000
	s_mov_b64 s[22:23], 0x90000
	v_pk_mul_f32 v[56:57], v[46:47], s[48:49] op_sel_hi:[1,0]
	v_pk_mul_f32 v[46:47], v[44:45], s[48:49] op_sel_hi:[1,0]
	v_cvt_pk_bf16_f32 v44, v52, v53
	v_cvt_pk_bf16_f32 v45, v54, v55
	v_pk_mul_f32 v[20:21], v[20:21], s[48:49] op_sel_hi:[1,0]
	v_cvt_pk_bf16_f32 v46, v46, v47
	v_cvt_pk_bf16_f32 v47, v56, v57
	global_store_dwordx4 v[66:67], v[44:47], off offset:256 sc1
	v_pk_mul_f32 v[6:7], v[6:7], s[48:49] op_sel_hi:[1,0]
	v_pk_mul_f32 v[4:5], v[4:5], s[48:49] op_sel_hi:[1,0]
	v_pk_mul_f32 v[46:47], v[50:51], s[48:49] op_sel_hi:[1,0]
	v_pk_mul_f32 v[50:51], v[42:43], s[48:49] op_sel_hi:[1,0]
	v_pk_mul_f32 v[42:43], v[40:41], s[48:49] op_sel_hi:[1,0]
	v_cvt_pk_bf16_f32 v40, v48, v49
	v_cvt_pk_bf16_f32 v41, v46, v47
	v_add_co_u32_e32 v46, vcc, s15, v64
	v_cvt_pk_bf16_f32 v42, v42, v43
	v_cvt_pk_bf16_f32 v43, v50, v51
	v_lshl_add_u64 v[44:45], v[64:65], 0, s[22:23]
	s_nop 0
	v_addc_co_u32_e32 v47, vcc, 0, v65, vcc
	global_store_dwordx4 v[46:47], v[40:43], off sc1
	s_mov_b32 s15, 0xa0000
	s_mov_b64 s[22:23], 0xa0000
	v_pk_mul_f32 v[40:41], v[30:31], s[48:49] op_sel_hi:[1,0]
	v_pk_mul_f32 v[30:31], v[28:29], s[48:49] op_sel_hi:[1,0]
	v_cvt_pk_bf16_f32 v28, v36, v37
	v_cvt_pk_bf16_f32 v29, v38, v39
	v_pk_mul_f32 v[2:3], v[2:3], s[48:49] op_sel_hi:[1,0]
	v_cvt_pk_bf16_f32 v30, v30, v31
	v_cvt_pk_bf16_f32 v31, v40, v41
	global_store_dwordx4 v[44:45], v[28:31], off offset:256 sc1
	v_pk_mul_f32 v[0:1], v[0:1], s[48:49] op_sel_hi:[1,0]
	s_nop 0
	v_pk_mul_f32 v[30:31], v[34:35], s[48:49] op_sel_hi:[1,0]
	v_pk_mul_f32 v[34:35], v[26:27], s[48:49] op_sel_hi:[1,0]
	v_pk_mul_f32 v[26:27], v[24:25], s[48:49] op_sel_hi:[1,0]
	v_cvt_pk_bf16_f32 v24, v32, v33
	v_cvt_pk_bf16_f32 v25, v30, v31
	v_add_co_u32_e32 v30, vcc, s15, v64
	v_lshl_add_u64 v[28:29], v[64:65], 0, s[22:23]
	s_nop 0
	v_addc_co_u32_e32 v31, vcc, 0, v65, vcc
	v_cvt_pk_bf16_f32 v26, v26, v27
	v_cvt_pk_bf16_f32 v27, v34, v35
	global_store_dwordx4 v[30:31], v[24:27], off sc1
	s_mov_b32 s15, 0xb0000
	s_mov_b64 s[22:23], 0xb0000
	v_pk_mul_f32 v[24:25], v[14:15], s[48:49] op_sel_hi:[1,0]
	v_pk_mul_f32 v[14:15], v[12:13], s[48:49] op_sel_hi:[1,0]
	v_cvt_pk_bf16_f32 v12, v20, v21
	v_cvt_pk_bf16_f32 v13, v22, v23
	v_lshl_add_u64 v[144:145], v[64:65], 0, s[22:23]
	v_cvt_pk_bf16_f32 v14, v14, v15
	v_cvt_pk_bf16_f32 v15, v24, v25
	global_store_dwordx4 v[28:29], v[12:15], off offset:256 sc1
	s_nop 1
	v_pk_mul_f32 v[12:13], v[18:19], s[48:49] op_sel_hi:[1,0]
	v_pk_mul_f32 v[14:15], v[16:17], s[48:49] op_sel_hi:[1,0]
	v_pk_mul_f32 v[16:17], v[10:11], s[48:49] op_sel_hi:[1,0]
	v_pk_mul_f32 v[10:11], v[8:9], s[48:49] op_sel_hi:[1,0]
	v_cvt_pk_bf16_f32 v8, v14, v15
	v_cvt_pk_bf16_f32 v9, v12, v13
	v_add_co_u32_e32 v12, vcc, s15, v64
	v_cvt_pk_bf16_f32 v10, v10, v11
	v_cvt_pk_bf16_f32 v11, v16, v17
	s_nop 1
	v_addc_co_u32_e32 v13, vcc, 0, v65, vcc
	global_store_dwordx4 v[12:13], v[8:11], off sc1
	v_cvt_pk_bf16_f32 v128, v4, v5
	v_cvt_pk_bf16_f32 v129, v6, v7
	v_cvt_pk_bf16_f32 v130, v0, v1
	v_cvt_pk_bf16_f32 v131, v2, v3
.LBB0_754:
	s_andn2_b64 vcc, exec, s[4:5]
	s_mov_b64 s[4:5], -1
	global_store_dwordx4 v[144:145], v[128:131], off offset:256 sc1
	s_cbranch_vccnz .LBB0_739
	v_mov_b32_e32 v0, v192
	s_andn2_b64 vcc, exec, s[8:9]
	s_cbranch_vccnz .LBB0_738
	s_barrier
	s_branch .LBB0_738

.LBB0_893:
	v_or_b32_e32 v130, s19, v129
	s_add_u32 s6, s10, s22
	s_addc_u32 s7, s11, s23
	v_ashrrev_i32_e32 v129, 31, v128
	v_ashrrev_i32_e32 v131, 31, v130
	v_lshl_add_u64 v[132:133], v[128:129], 1, s[6:7]
	v_lshlrev_b64 v[128:129], 11, v[130:131]
	v_lshl_add_u64 v[128:129], v[132:133], 0, v[128:129]
	v_cvt_pk_bf16_f32 v124, v124, v125
	v_cvt_pk_bf16_f32 v125, v126, v127
	v_cvt_pk_bf16_f32 v126, v120, v121
	v_cvt_pk_bf16_f32 v127, v122, v123
	global_store_dwordx4 v[128:129], v[124:127], off sc1
	v_cvt_pk_bf16_f32 v112, v112, v113
	v_cvt_pk_bf16_f32 v113, v114, v115
	v_cvt_pk_bf16_f32 v114, v104, v105
	v_or_b32_e32 v104, 16, v130
	v_ashrrev_i32_e32 v105, 31, v104
	v_lshlrev_b64 v[104:105], 11, v[104:105]
	v_cvt_pk_bf16_f32 v115, v106, v107
	global_store_dwordx4 v[128:129], v[112:115], off offset:256 sc1
	s_mov_b64 s[6:7], 0x40000
	s_nop 0
	v_lshl_add_u64 v[112:113], v[132:133], 0, v[104:105]
	v_cvt_pk_bf16_f32 v104, v116, v117
	v_cvt_pk_bf16_f32 v105, v118, v119
	v_cvt_pk_bf16_f32 v106, v108, v109
	v_cvt_pk_bf16_f32 v107, v110, v111
	global_store_dwordx4 v[112:113], v[104:107], off sc1
	v_cvt_pk_bf16_f32 v96, v96, v97
	v_cvt_pk_bf16_f32 v97, v98, v99
	v_cvt_pk_bf16_f32 v98, v88, v89
	v_or_b32_e32 v88, 32, v130
	v_ashrrev_i32_e32 v89, 31, v88
	v_lshlrev_b64 v[88:89], 11, v[88:89]
	v_cvt_pk_bf16_f32 v99, v90, v91
	global_store_dwordx4 v[112:113], v[96:99], off offset:256 sc1
	s_nop 1
	v_lshl_add_u64 v[96:97], v[132:133], 0, v[88:89]
	v_cvt_pk_bf16_f32 v88, v100, v101
	v_cvt_pk_bf16_f32 v89, v102, v103
	v_cvt_pk_bf16_f32 v90, v92, v93
	v_cvt_pk_bf16_f32 v91, v94, v95
	global_store_dwordx4 v[96:97], v[88:91], off sc1
	v_cvt_pk_bf16_f32 v80, v80, v81
	v_cvt_pk_bf16_f32 v81, v82, v83
	v_cvt_pk_bf16_f32 v82, v72, v73
	v_or_b32_e32 v72, 48, v130
	v_ashrrev_i32_e32 v73, 31, v72
	v_lshlrev_b64 v[72:73], 11, v[72:73]
	v_cvt_pk_bf16_f32 v83, v74, v75
	global_store_dwordx4 v[96:97], v[80:83], off offset:256 sc1
	s_nop 1
	v_lshl_add_u64 v[80:81], v[132:133], 0, v[72:73]
	v_cvt_pk_bf16_f32 v72, v84, v85
	v_cvt_pk_bf16_f32 v73, v86, v87
	v_cvt_pk_bf16_f32 v74, v76, v77
	v_cvt_pk_bf16_f32 v75, v78, v79
	global_store_dwordx4 v[80:81], v[72:75], off sc1
	v_cvt_pk_bf16_f32 v68, v68, v69
	v_cvt_pk_bf16_f32 v69, v70, v71
	v_cvt_pk_bf16_f32 v70, v64, v65
	v_lshl_add_u64 v[64:65], v[128:129], 0, s[6:7]
	s_mov_b32 s6, 0x40000
	v_cvt_pk_bf16_f32 v71, v66, v67
	global_store_dwordx4 v[80:81], v[68:71], off offset:256 sc1
	v_cvt_pk_bf16_f32 v60, v60, v61
	v_cvt_pk_bf16_f32 v61, v62, v63
	v_cvt_pk_bf16_f32 v62, v56, v57
	v_add_co_u32_e32 v56, vcc, s6, v128
	v_cvt_pk_bf16_f32 v63, v58, v59
	s_mov_b64 s[6:7], 0x48000
	s_nop 0
	v_addc_co_u32_e32 v57, vcc, 0, v129, vcc
	global_store_dwordx4 v[56:57], v[60:63], off sc1
	v_cvt_pk_bf16_f32 v48, v48, v49
	v_cvt_pk_bf16_f32 v49, v50, v51
	v_cvt_pk_bf16_f32 v50, v40, v41
	v_cvt_pk_bf16_f32 v51, v42, v43
	global_store_dwordx4 v[64:65], v[48:51], off offset:256 sc1
	v_cvt_pk_bf16_f32 v40, v52, v53
	v_cvt_pk_bf16_f32 v41, v54, v55
	v_cvt_pk_bf16_f32 v42, v44, v45
	v_cvt_pk_bf16_f32 v43, v46, v47
	s_nop 1
	v_lshl_add_u64 v[48:49], v[128:129], 0, s[6:7]
	s_mov_b32 s6, 0x48000
	v_add_co_u32_e32 v44, vcc, s6, v128
	s_mov_b64 s[6:7], 0x50000
	s_nop 0
	v_addc_co_u32_e32 v45, vcc, 0, v129, vcc
	global_store_dwordx4 v[44:45], v[40:43], off sc1
	v_cvt_pk_bf16_f32 v32, v32, v33
	v_cvt_pk_bf16_f32 v33, v34, v35
	v_cvt_pk_bf16_f32 v34, v24, v25
	v_cvt_pk_bf16_f32 v35, v26, v27
	global_store_dwordx4 v[48:49], v[32:35], off offset:256 sc1
	v_cvt_pk_bf16_f32 v24, v36, v37
	v_cvt_pk_bf16_f32 v25, v38, v39
	v_cvt_pk_bf16_f32 v26, v28, v29
	v_cvt_pk_bf16_f32 v27, v30, v31
	s_nop 1
	v_lshl_add_u64 v[32:33], v[128:129], 0, s[6:7]
	s_mov_b32 s6, 0x50000
	v_add_co_u32_e32 v28, vcc, s6, v128
	s_mov_b64 s[6:7], 0x58000
	s_nop 0
	v_addc_co_u32_e32 v29, vcc, 0, v129, vcc
	global_store_dwordx4 v[28:29], v[24:27], off sc1
	v_cvt_pk_bf16_f32 v16, v16, v17
	v_cvt_pk_bf16_f32 v17, v18, v19
	v_cvt_pk_bf16_f32 v18, v8, v9
	v_cvt_pk_bf16_f32 v19, v10, v11
	global_store_dwordx4 v[32:33], v[16:19], off offset:256 sc1
	v_cvt_pk_bf16_f32 v8, v20, v21
	v_cvt_pk_bf16_f32 v9, v22, v23
	v_cvt_pk_bf16_f32 v10, v12, v13
	v_cvt_pk_bf16_f32 v11, v14, v15
	s_nop 1
	v_lshl_add_u64 v[16:17], v[128:129], 0, s[6:7]
	s_mov_b32 s6, 0x58000
	v_add_co_u32_e32 v12, vcc, s6, v128
	s_nop 1
	v_addc_co_u32_e32 v13, vcc, 0, v129, vcc
	global_store_dwordx4 v[12:13], v[8:11], off sc1
	v_cvt_pk_bf16_f32 v4, v4, v5
	v_cvt_pk_bf16_f32 v5, v6, v7
	v_cvt_pk_bf16_f32 v6, v0, v1
	v_cvt_pk_bf16_f32 v7, v2, v3
	global_store_dwordx4 v[16:17], v[4:7], off offset:256 sc1

.LBB0_993:
	v_mov_b32_e32 v134, v192
	v_mov_b32_e32 v135, v192
	s_lshl_b32 s6, s30, 7
	v_bfe_i32 v128, v135, 7, 1
	v_and_b32_e32 v128, 0xb00, v128
	v_add_u32_e32 v128, s6, v128
	s_movk_i32 s7, 0x7f
	v_and_or_b32 v128, v135, s7, v128
	v_ashrrev_i32_e32 v129, 31, v128
	v_lshl_add_u64 v[130:131], v[128:129], 2, s[20:21]
	v_ashrrev_i32_e32 v129, 8, v135
	v_mad_i32_i24 v132, v129, s79, v128
	v_ashrrev_i32_e32 v133, 31, v132
	v_lshl_add_u64 v[132:133], v[132:133], 2, s[18:19]
	v_cmp_gt_i32_e32 vcc, 3, v129
	v_add_u32_e32 v129, 0x200, v135
	v_lshl_add_u32 v135, v135, 2, 0
	v_cndmask_b32_e32 v133, v131, v133, vcc
	v_cndmask_b32_e32 v132, v130, v132, vcc
	global_load_dword v132, v[132:133], off
	v_ashrrev_i32_e32 v133, 8, v129
	v_mad_i32_i24 v128, v133, s79, v128
	v_ashrrev_i32_e32 v129, 31, v128
	v_lshl_add_u64 v[128:129], v[128:129], 2, s[18:19]
	v_cmp_gt_i32_e32 vcc, 3, v133
	s_mulk_i32 s0, 0xfc
	v_lshrrev_b32_e32 v136, 1, v134
	v_cndmask_b32_e32 v129, v131, v129, vcc
	v_cndmask_b32_e32 v128, v130, v128, vcc
	global_load_dword v133, v[128:129], off
	v_add_u32_e32 v135, 0x20000, v135
	s_add_i32 s0, s66, s0
	v_and_b32_e32 v219, 15, v134
	v_and_or_b32 v134, v136, 24, s62
	v_add_u32_e32 v218, s0, v219
	v_or_b32_e32 v136, 0x80, v134
	v_or_b32_e32 v137, 4, v134
	v_or_b32_e32 v138, 0x84, v134
	v_cmp_lt_u32_e32 vcc, 1, v219
	v_or_b32_e32 v188, s6, v134
	v_cmp_gt_i32_e64 s[6:7], s58, v218
	v_lshlrev_b32_e32 v172, 2, v134
	v_lshlrev_b32_e32 v210, 2, v137
	v_lshlrev_b32_e32 v206, 2, v136
	v_lshlrev_b32_e32 v212, 2, v138
	v_mov_b32_dpp v236, v124 row_shr:1 row_mask:0xf bank_mask:0xf bound_ctrl:1
	v_mov_b32_dpp v234, v124 row_shr:2 row_mask:0xf bank_mask:0xf bound_ctrl:1
	v_mov_b32_dpp v241, v125 row_shr:1 row_mask:0xf bank_mask:0xf bound_ctrl:1
	v_mov_b32_dpp v240, v125 row_shr:2 row_mask:0xf bank_mask:0xf bound_ctrl:1
	v_mov_b32_dpp v245, v126 row_shr:1 row_mask:0xf bank_mask:0xf bound_ctrl:1
	v_mov_b32_dpp v244, v126 row_shr:2 row_mask:0xf bank_mask:0xf bound_ctrl:1
	v_mov_b32_dpp v129, v127 row_shr:1 row_mask:0xf bank_mask:0xf bound_ctrl:1
	v_mov_b32_dpp v128, v127 row_shr:2 row_mask:0xf bank_mask:0xf bound_ctrl:1
	v_mov_b32_dpp v239, v116 row_shr:1 row_mask:0xf bank_mask:0xf bound_ctrl:1
	v_mov_b32_dpp v238, v116 row_shr:2 row_mask:0xf bank_mask:0xf bound_ctrl:1
	v_mov_b32_dpp v243, v117 row_shr:1 row_mask:0xf bank_mask:0xf bound_ctrl:1
	v_mov_b32_dpp v242, v117 row_shr:2 row_mask:0xf bank_mask:0xf bound_ctrl:1
	v_mov_b32_dpp v247, v118 row_shr:1 row_mask:0xf bank_mask:0xf bound_ctrl:1
	v_mov_b32_dpp v246, v118 row_shr:2 row_mask:0xf bank_mask:0xf bound_ctrl:1
	v_mov_b32_dpp v131, v119 row_shr:1 row_mask:0xf bank_mask:0xf bound_ctrl:1
	v_mov_b32_dpp v130, v119 row_shr:2 row_mask:0xf bank_mask:0xf bound_ctrl:1
	v_mov_b32_dpp v221, v120 row_shr:1 row_mask:0xf bank_mask:0xf bound_ctrl:1
	v_mov_b32_dpp v220, v120 row_shr:2 row_mask:0xf bank_mask:0xf bound_ctrl:1
	v_mov_b32_dpp v225, v121 row_shr:1 row_mask:0xf bank_mask:0xf bound_ctrl:1
	v_mov_b32_dpp v224, v121 row_shr:2 row_mask:0xf bank_mask:0xf bound_ctrl:1
	v_mov_b32_dpp v229, v122 row_shr:1 row_mask:0xf bank_mask:0xf bound_ctrl:1
	v_mov_b32_dpp v228, v122 row_shr:2 row_mask:0xf bank_mask:0xf bound_ctrl:1
	v_mov_b32_dpp v233, v123 row_shr:1 row_mask:0xf bank_mask:0xf bound_ctrl:1
	v_mov_b32_dpp v232, v123 row_shr:2 row_mask:0xf bank_mask:0xf bound_ctrl:1
	v_mov_b32_dpp v223, v112 row_shr:1 row_mask:0xf bank_mask:0xf bound_ctrl:1
	v_mov_b32_dpp v222, v112 row_shr:2 row_mask:0xf bank_mask:0xf bound_ctrl:1
	v_mov_b32_dpp v227, v113 row_shr:1 row_mask:0xf bank_mask:0xf bound_ctrl:1
	v_mov_b32_dpp v226, v113 row_shr:2 row_mask:0xf bank_mask:0xf bound_ctrl:1
	v_mov_b32_dpp v231, v114 row_shr:1 row_mask:0xf bank_mask:0xf bound_ctrl:1
	v_mov_b32_dpp v230, v114 row_shr:2 row_mask:0xf bank_mask:0xf bound_ctrl:1
	v_mov_b32_dpp v237, v115 row_shr:1 row_mask:0xf bank_mask:0xf bound_ctrl:1
	v_mov_b32_dpp v235, v115 row_shr:2 row_mask:0xf bank_mask:0xf bound_ctrl:1
	v_ashrrev_i32_e32 v189, 31, v188
	s_and_b64 s[6:7], vcc, s[6:7]
	v_add_u32_e32 v205, s40, v172
	v_add_u32_e32 v204, s41, v172
	v_add_u32_e32 v211, s92, v210
	v_add_u32_e32 v214, s40, v210
	v_add_u32_e32 v213, s41, v210
	v_add_u32_e32 v209, s40, v206
	v_add_u32_e32 v208, s41, v206
	v_add_u32_e32 v207, s92, v206
	v_add_u32_e32 v203, s92, v172
	v_add_u32_e32 v216, s40, v212
	v_add_u32_e32 v215, s41, v212
	v_add_u32_e32 v217, s92, v212
	s_waitcnt vmcnt(0)
	ds_write2st64_b32 v135, v132, v133 offset1:8
	s_waitcnt lgkmcnt(0)
	s_barrier
	s_and_saveexec_b64 s[10:11], s[6:7]
	s_cbranch_execz .LBB0_995
	v_add_u32_e32 v133, 0x810, v218
	v_mul_hi_u32 v134, v133, s59
	v_lshrrev_b32_e32 v134, 7, v134
	s_add_i32 s25, 0, 0x20000
	v_mul_u32_u24_e32 v134, 0x810, v134
	v_sub_u32_e32 v133, v133, v134
	v_add_u32_e32 v134, s25, v206
	ds_read_b128 v[140:143], v209
	ds_read_b128 v[144:147], v208
	ds_read_b128 v[148:151], v207
	ds_read_b128 v[152:155], v134
	ds_read_b128 v[168:171], v205
	ds_read_b128 v[160:163], v204
	ds_read_b128 v[156:159], v203
	v_add_u32_e32 v134, s25, v172
	ds_read_b128 v[164:167], v134
	v_add_u32_e32 v132, s25, v210
	v_cmp_eq_u32_e64 s[8:9], 0, v133
	v_cmp_lt_u32_e64 s[6:7], 1, v133
	s_waitcnt lgkmcnt(4)
	v_mov_b32_e32 v248, v155
	v_cndmask_b32_e64 v181, v129, 0, s[8:9]
	v_cndmask_b32_e64 v180, v131, 0, s[8:9]
	v_cndmask_b32_e64 v191, 0, v128, s[6:7]
	v_cndmask_b32_e64 v190, 0, v130, s[6:7]
	ds_read_b128 v[128:131], v132
	s_waitcnt lgkmcnt(1)
	v_mov_b32_e32 v249, v167
	v_mov_b32_e32 v250, v151
	v_mov_b32_e32 v251, v159
	v_mov_b32_e32 v182, v147
	v_mov_b32_e32 v183, v163
	v_pk_fma_f32 v[190:191], v[190:191], v[248:249], v[250:251]
	v_mov_b32_e32 v174, v119
	v_mov_b32_e32 v175, v127
	v_mov_b32_e32 v176, v143
	v_mov_b32_e32 v177, v171
	v_pk_fma_f32 v[180:181], v[180:181], v[182:183], v[190:191]
	v_mov_b32_e32 v147, v162
	v_pk_fma_f32 v[190:191], v[174:175], v[176:177], v[180:181]
	v_cndmask_b32_e64 v163, 0, v244, s[6:7]
	v_mul_f32_e32 v143, 0x3d372713, v191
	v_mul_f32_e32 v143, v191, v143
	v_fma_f32 v143, v191, v143, v191
	v_mul_f32_e32 v143, 0x3f4c422a, v143
	v_mul_f32_e32 v143, 0xc038aa3b, v143
	v_cndmask_b32_e64 v162, 0, v246, s[6:7]
	v_mov_b32_e32 v155, v166
	v_mov_b32_e32 v151, v158
	v_exp_f32_e32 v159, v143
	v_mov_b32_e32 v143, v170
	v_cndmask_b32_e64 v171, v245, 0, s[8:9]
	v_cndmask_b32_e64 v170, v247, 0, s[8:9]
	v_pk_fma_f32 v[150:151], v[162:163], v[154:155], v[150:151]
	v_mov_b32_e32 v174, v118
	v_mov_b32_e32 v175, v126
	v_pk_fma_f32 v[146:147], v[170:171], v[146:147], v[150:151]
	v_cndmask_b32_e64 v163, 0, v240, s[6:7]
	v_pk_fma_f32 v[142:143], v[174:175], v[142:143], v[146:147]
	v_add_f32_e32 v147, 1.0, v159
	v_mul_f32_e32 v146, 0x3d372713, v143
	v_mul_f32_e32 v146, v143, v146
	v_fma_f32 v146, v143, v146, v143
	v_mul_f32_e32 v146, 0x3f4c422a, v146
	v_mul_f32_e32 v146, 0xc038aa3b, v146
	v_exp_f32_e32 v146, v146
	v_rcp_f32_e32 v147, v147
	v_cndmask_b32_e64 v162, 0, v242, s[6:7]
	v_mov_b32_e32 v166, v153
	v_add_f32_e32 v146, 1.0, v146
	v_rcp_f32_e32 v146, v146
	v_mov_b32_e32 v167, v165
	v_mov_b32_e32 v170, v149
	v_mov_b32_e32 v171, v157
	v_mul_f32_e32 v147, v191, v147
	v_cndmask_b32_e64 v155, v241, 0, s[8:9]
	v_cndmask_b32_e64 v154, v243, 0, s[8:9]
	v_mov_b32_e32 v158, v145
	v_mov_b32_e32 v159, v161
	v_pk_fma_f32 v[162:163], v[162:163], v[166:167], v[170:171]
	v_mul_f32_e32 v180, v190, v147
	v_mul_f32_e32 v143, v143, v146
	v_mov_b32_e32 v146, v117
	v_mov_b32_e32 v147, v125
	v_mov_b32_e32 v150, v141
	v_mov_b32_e32 v151, v169
	v_pk_fma_f32 v[154:155], v[154:155], v[158:159], v[162:163]
	v_cndmask_b32_e64 v159, 0, v234, s[6:7]
	v_pk_fma_f32 v[150:151], v[146:147], v[150:151], v[154:155]
	v_cndmask_b32_e64 v158, 0, v238, s[6:7]
	v_mul_f32_e32 v141, 0x3d372713, v151
	v_mul_f32_e32 v141, v151, v141
	v_fma_f32 v141, v151, v141, v151
	v_mul_f32_e32 v141, 0x3f4c422a, v141
	v_mov_b32_e32 v153, v164
	v_mov_b32_e32 v149, v156
	v_mul_f32_e32 v141, 0xc038aa3b, v141
	v_cndmask_b32_e64 v155, v236, 0, s[8:9]
	v_cndmask_b32_e64 v154, v239, 0, s[8:9]
	v_mov_b32_e32 v145, v160
	v_pk_fma_f32 v[148:149], v[158:159], v[152:153], v[148:149]
	v_exp_f32_e32 v157, v141
	v_mov_b32_e32 v146, v116
	v_mov_b32_e32 v147, v124
	v_mov_b32_e32 v141, v168
	v_pk_fma_f32 v[144:145], v[154:155], v[144:145], v[148:149]
	v_add_u32_e32 v132, s25, v212
	v_pk_fma_f32 v[148:149], v[146:147], v[140:141], v[144:145]
	v_add_f32_e32 v141, 1.0, v157
	v_mul_f32_e32 v140, 0x3d372713, v149
	v_mul_f32_e32 v140, v149, v140
	v_fma_f32 v140, v149, v140, v149
	v_mul_f32_e32 v140, 0x3f4c422a, v140
	v_mul_f32_e32 v140, 0xc038aa3b, v140
	v_exp_f32_e32 v140, v140
	ds_read_b128 v[132:135], v132
	ds_read_b128 v[244:247], v213
	ds_read_b128 v[136:139], v216
	v_add_f32_e32 v140, 1.0, v140
	ds_read_b128 v[248:251], v211
	ds_read_b128 v[174:177], v214
	v_mul_f32_e32 v166, v142, v143
	v_rcp_f32_e32 v167, v141
	v_rcp_f32_e32 v168, v140
	ds_read_b128 v[140:143], v215
	ds_read_b128 v[144:147], v217
	v_cndmask_b32_e64 v161, 0, v235, s[6:7]
	v_cndmask_b32_e64 v160, 0, v232, s[6:7]
	s_waitcnt lgkmcnt(7)
	v_mov_b32_e32 v162, v131
	s_waitcnt lgkmcnt(6)
	v_mov_b32_e32 v163, v135
	s_waitcnt lgkmcnt(3)
	v_mov_b32_e32 v164, v251
	s_waitcnt lgkmcnt(0)
	v_mov_b32_e32 v165, v147
	v_cndmask_b32_e64 v157, v237, 0, s[8:9]
	v_cndmask_b32_e64 v156, v233, 0, s[8:9]
	v_mov_b32_e32 v158, v247
	v_mov_b32_e32 v159, v143
	v_pk_fma_f32 v[160:161], v[160:161], v[162:163], v[164:165]
	v_mov_b32_e32 v152, v123
	v_mov_b32_e32 v153, v115
	v_mov_b32_e32 v154, v177
	v_mov_b32_e32 v155, v139
	v_pk_fma_f32 v[156:157], v[156:157], v[158:159], v[160:161]
	v_mov_b32_e32 v247, v142
	v_pk_fma_f32 v[152:153], v[152:153], v[154:155], v[156:157]
	v_cndmask_b32_e64 v143, 0, v230, s[6:7]
	v_mul_f32_e32 v131, 0x3d372713, v152
	v_mul_f32_e32 v131, v152, v131
	v_fma_f32 v131, v152, v131, v152
	v_mul_f32_e32 v131, 0x3f4c422a, v131
	v_mul_f32_e32 v131, 0xc038aa3b, v131
	v_exp_f32_e32 v131, v131
	v_cndmask_b32_e64 v142, 0, v228, s[6:7]
	v_mov_b32_e32 v251, v146
	v_mul_f32_e32 v135, v151, v167
	v_add_f32_e32 v131, 1.0, v131
	v_rcp_f32_e32 v147, v131
	v_mov_b32_e32 v131, v134
	v_mov_b32_e32 v177, v138
	v_cndmask_b32_e64 v139, v231, 0, s[8:9]
	v_cndmask_b32_e64 v138, v229, 0, s[8:9]
	v_pk_fma_f32 v[130:131], v[142:143], v[130:131], v[250:251]
	v_mul_f32_e32 v154, v150, v135
	v_mov_b32_e32 v150, v122
	v_mov_b32_e32 v151, v114
	v_pk_fma_f32 v[130:131], v[138:139], v[246:247], v[130:131]
	v_mul_f32_e32 v135, v149, v168
	v_pk_fma_f32 v[130:131], v[150:151], v[176:177], v[130:131]
	v_mul_f32_e32 v155, v148, v135
	v_mul_f32_e32 v134, 0x3d372713, v130
	v_mul_f32_e32 v134, v130, v134
	v_fma_f32 v134, v130, v134, v130
	v_mul_f32_e32 v134, 0x3f4c422a, v134
	v_mul_f32_e32 v134, 0xc038aa3b, v134
	v_exp_f32_e32 v134, v134
	v_mul_f32_e32 v135, v152, v147
	v_mul_f32_e32 v156, v135, v153
	v_cndmask_b32_e64 v149, 0, v226, s[6:7]
	v_cndmask_b32_e64 v148, 0, v224, s[6:7]
	v_mov_b32_e32 v150, v129
	v_mov_b32_e32 v151, v133
	v_mov_b32_e32 v152, v249
	v_mov_b32_e32 v153, v145
	v_add_f32_e32 v134, 1.0, v134
	v_cndmask_b32_e64 v143, v227, 0, s[8:9]
	v_cndmask_b32_e64 v142, v225, 0, s[8:9]
	v_mov_b32_e32 v146, v245
	v_mov_b32_e32 v147, v141
	v_pk_fma_f32 v[148:149], v[148:149], v[150:151], v[152:153]
	v_rcp_f32_e32 v157, v134
	v_mov_b32_e32 v134, v121
	v_mov_b32_e32 v135, v113
	v_mov_b32_e32 v138, v175
	v_mov_b32_e32 v139, v137
	v_pk_fma_f32 v[142:143], v[142:143], v[146:147], v[148:149]
	v_mov_b32_e32 v245, v140
	v_pk_fma_f32 v[134:135], v[134:135], v[138:139], v[142:143]
	v_cndmask_b32_e64 v141, 0, v222, s[6:7]
	v_mul_f32_e32 v129, 0x3d372713, v134
	v_mul_f32_e32 v129, v134, v129
	v_fma_f32 v129, v134, v129, v134
	v_mul_f32_e32 v129, 0x3f4c422a, v129
	v_mul_f32_e32 v129, 0xc038aa3b, v129
	v_exp_f32_e32 v133, v129
	v_cndmask_b32_e64 v140, 0, v220, s[6:7]
	v_mov_b32_e32 v129, v132
	v_mov_b32_e32 v249, v144
	v_mov_b32_e32 v175, v136
	v_cndmask_b32_e64 v137, v223, 0, s[8:9]
	v_cndmask_b32_e64 v136, v221, 0, s[8:9]
	v_pk_fma_f32 v[128:129], v[140:141], v[128:129], v[248:249]
	v_mov_b32_e32 v138, v120
	v_mov_b32_e32 v139, v112
	v_pk_fma_f32 v[128:129], v[136:137], v[244:245], v[128:129]
	v_add_f32_e32 v133, 1.0, v133
	v_pk_fma_f32 v[128:129], v[138:139], v[174:175], v[128:129]
	v_rcp_f32_e32 v133, v133
	v_mul_f32_e32 v132, 0x3d372713, v128
	v_mul_f32_e32 v132, v128, v132
	v_fma_f32 v132, v128, v132, v128
	v_mul_f32_e32 v132, 0x3f4c422a, v132
	v_mul_f32_e32 v132, 0xc038aa3b, v132
	v_exp_f32_e32 v132, v132
	v_mul_f32_e32 v130, v130, v157
	v_mul_f32_e32 v131, v130, v131
	v_mul_f32_e32 v130, v134, v133
	v_add_f32_e32 v132, 1.0, v132
	v_rcp_f32_e32 v132, v132
	v_mul_f32_e32 v130, v130, v135
	v_mul_f32_e32 v128, v128, v132
	v_mul_f32_e32 v132, v128, v129
	v_cvt_pk_bf16_f32 v128, v155, v154
	v_cvt_pk_bf16_f32 v129, v166, v180
	v_cvt_pk_bf16_f32 v130, v132, v130
	v_mov_b64_e32 v[132:133], s[16:17]
	v_mad_i64_i32 v[132:133], s[6:7], v218, s79, v[132:133]
	v_lshl_add_u64 v[132:133], v[188:189], 1, v[132:133]
	v_cvt_pk_bf16_f32 v131, v131, v156
	global_store_dwordx4 v[132:133], v[128:131], off sc1
.LBB0_995:
	s_or_b64 exec, exec, s[10:11]
	v_cmp_eq_u32_e64 s[6:7], 0, v219
	v_add3_u32 v160, s0, v219, 16
	v_mov_b32_dpp v225, v124 row_mirror row_mask:0xf bank_mask:0xf bound_ctrl:1
	v_mov_b32_dpp v237, v125 row_mirror row_mask:0xf bank_mask:0xf bound_ctrl:1
	v_mov_b32_dpp v245, v126 row_mirror row_mask:0xf bank_mask:0xf bound_ctrl:1
	v_mov_b32_dpp v152, v127 row_mirror row_mask:0xf bank_mask:0xf bound_ctrl:1
	v_mov_b32_dpp v233, v116 row_mirror row_mask:0xf bank_mask:0xf bound_ctrl:1
	v_mov_b32_dpp v241, v117 row_mirror row_mask:0xf bank_mask:0xf bound_ctrl:1
	v_mov_b32_dpp v249, v118 row_mirror row_mask:0xf bank_mask:0xf bound_ctrl:1
	v_mov_b32_dpp v138, v119 row_mirror row_mask:0xf bank_mask:0xf bound_ctrl:1
	v_mov_b32_dpp v130, v120 row_mirror row_mask:0xf bank_mask:0xf bound_ctrl:1
	v_mov_b32_dpp v134, v121 row_mirror row_mask:0xf bank_mask:0xf bound_ctrl:1
	v_mov_b32_dpp v142, v122 row_mirror row_mask:0xf bank_mask:0xf bound_ctrl:1
	v_mov_b32_dpp v146, v123 row_mirror row_mask:0xf bank_mask:0xf bound_ctrl:1
	v_mov_b32_dpp v163, v112 row_mirror row_mask:0xf bank_mask:0xf bound_ctrl:1
	v_mov_b32_dpp v168, v113 row_mirror row_mask:0xf bank_mask:0xf bound_ctrl:1
	v_mov_b32_dpp v191, v114 row_mirror row_mask:0xf bank_mask:0xf bound_ctrl:1
	v_mov_b32_dpp v229, v115 row_mirror row_mask:0xf bank_mask:0xf bound_ctrl:1
	v_mov_b32_dpp v222, v225 quad_perm:[1,0,3,2] row_mask:0xf bank_mask:0xf bound_ctrl:1
	v_mov_b32_dpp v226, v108 row_shr:1 row_mask:0xf bank_mask:0xf bound_ctrl:1
	v_mov_b32_dpp v223, v108 row_shr:2 row_mask:0xf bank_mask:0xf bound_ctrl:1
	v_mov_b32_dpp v235, v237 quad_perm:[1,0,3,2] row_mask:0xf bank_mask:0xf bound_ctrl:1
	v_mov_b32_dpp v238, v109 row_shr:1 row_mask:0xf bank_mask:0xf bound_ctrl:1
	v_mov_b32_dpp v236, v109 row_shr:2 row_mask:0xf bank_mask:0xf bound_ctrl:1
	v_mov_b32_dpp v243, v245 quad_perm:[1,0,3,2] row_mask:0xf bank_mask:0xf bound_ctrl:1
	v_mov_b32_dpp v246, v110 row_shr:1 row_mask:0xf bank_mask:0xf bound_ctrl:1
	v_mov_b32_dpp v244, v110 row_shr:2 row_mask:0xf bank_mask:0xf bound_ctrl:1
	v_mov_b32_dpp v251, v152 quad_perm:[1,0,3,2] row_mask:0xf bank_mask:0xf bound_ctrl:1
	v_mov_b32_dpp v153, v111 row_shr:1 row_mask:0xf bank_mask:0xf bound_ctrl:1
	v_mov_b32_dpp v252, v111 row_shr:2 row_mask:0xf bank_mask:0xf bound_ctrl:1
	v_mov_b32_dpp v231, v233 quad_perm:[1,0,3,2] row_mask:0xf bank_mask:0xf bound_ctrl:1
	v_mov_b32_dpp v234, v100 row_shr:1 row_mask:0xf bank_mask:0xf bound_ctrl:1
	v_mov_b32_dpp v232, v100 row_shr:2 row_mask:0xf bank_mask:0xf bound_ctrl:1
	v_mov_b32_dpp v239, v241 quad_perm:[1,0,3,2] row_mask:0xf bank_mask:0xf bound_ctrl:1
	v_mov_b32_dpp v242, v101 row_shr:1 row_mask:0xf bank_mask:0xf bound_ctrl:1
	v_mov_b32_dpp v240, v101 row_shr:2 row_mask:0xf bank_mask:0xf bound_ctrl:1
	v_mov_b32_dpp v247, v249 quad_perm:[1,0,3,2] row_mask:0xf bank_mask:0xf bound_ctrl:1
	v_mov_b32_dpp v250, v102 row_shr:1 row_mask:0xf bank_mask:0xf bound_ctrl:1
	v_mov_b32_dpp v248, v102 row_shr:2 row_mask:0xf bank_mask:0xf bound_ctrl:1
	v_mov_b32_dpp v136, v138 quad_perm:[1,0,3,2] row_mask:0xf bank_mask:0xf bound_ctrl:1
	v_mov_b32_dpp v139, v103 row_shr:1 row_mask:0xf bank_mask:0xf bound_ctrl:1
	v_mov_b32_dpp v137, v103 row_shr:2 row_mask:0xf bank_mask:0xf bound_ctrl:1
	v_mov_b32_dpp v128, v130 quad_perm:[1,0,3,2] row_mask:0xf bank_mask:0xf bound_ctrl:1
	v_mov_b32_dpp v131, v104 row_shr:1 row_mask:0xf bank_mask:0xf bound_ctrl:1
	v_mov_b32_dpp v129, v104 row_shr:2 row_mask:0xf bank_mask:0xf bound_ctrl:1
	v_mov_b32_dpp v132, v134 quad_perm:[1,0,3,2] row_mask:0xf bank_mask:0xf bound_ctrl:1
	v_mov_b32_dpp v135, v105 row_shr:1 row_mask:0xf bank_mask:0xf bound_ctrl:1
	v_mov_b32_dpp v133, v105 row_shr:2 row_mask:0xf bank_mask:0xf bound_ctrl:1
	v_mov_b32_dpp v140, v142 quad_perm:[1,0,3,2] row_mask:0xf bank_mask:0xf bound_ctrl:1
	v_mov_b32_dpp v143, v106 row_shr:1 row_mask:0xf bank_mask:0xf bound_ctrl:1
	v_mov_b32_dpp v141, v106 row_shr:2 row_mask:0xf bank_mask:0xf bound_ctrl:1
	v_mov_b32_dpp v144, v146 quad_perm:[1,0,3,2] row_mask:0xf bank_mask:0xf bound_ctrl:1
	v_mov_b32_dpp v147, v107 row_shr:1 row_mask:0xf bank_mask:0xf bound_ctrl:1
	v_mov_b32_dpp v145, v107 row_shr:2 row_mask:0xf bank_mask:0xf bound_ctrl:1
	v_mov_b32_dpp v161, v163 quad_perm:[1,0,3,2] row_mask:0xf bank_mask:0xf bound_ctrl:1
	v_mov_b32_dpp v164, v96 row_shr:1 row_mask:0xf bank_mask:0xf bound_ctrl:1
	v_mov_b32_dpp v162, v96 row_shr:2 row_mask:0xf bank_mask:0xf bound_ctrl:1
	v_mov_b32_dpp v166, v168 quad_perm:[1,0,3,2] row_mask:0xf bank_mask:0xf bound_ctrl:1
	v_mov_b32_dpp v169, v97 row_shr:1 row_mask:0xf bank_mask:0xf bound_ctrl:1
	v_mov_b32_dpp v167, v97 row_shr:2 row_mask:0xf bank_mask:0xf bound_ctrl:1
	v_mov_b32_dpp v171, v191 quad_perm:[1,0,3,2] row_mask:0xf bank_mask:0xf bound_ctrl:1
	v_mov_b32_dpp v221, v98 row_shr:1 row_mask:0xf bank_mask:0xf bound_ctrl:1
	v_mov_b32_dpp v190, v98 row_shr:2 row_mask:0xf bank_mask:0xf bound_ctrl:1
	v_mov_b32_dpp v227, v229 quad_perm:[1,0,3,2] row_mask:0xf bank_mask:0xf bound_ctrl:1
	v_mov_b32_dpp v230, v99 row_shr:1 row_mask:0xf bank_mask:0xf bound_ctrl:1
	v_mov_b32_dpp v228, v99 row_shr:2 row_mask:0xf bank_mask:0xf bound_ctrl:1
	v_cmp_gt_i32_e64 s[8:9], s58, v160
	s_and_saveexec_b64 s[30:31], s[8:9]
	s_cbranch_execz .LBB0_997
	s_add_i32 s25, 0, 0x20000
	v_add_u32_e32 v158, 0x810, v160
	v_add_u32_e32 v120, s25, v212
	v_mul_hi_u32 v159, v158, s59
	ds_read_b128 v[112:115], v217
	ds_read_b128 v[116:119], v216
	ds_read_b128 v[124:127], v215
	ds_read_b128 v[120:123], v120
	ds_read_b128 v[148:151], v214
	ds_read_b128 v[154:157], v213
	v_lshrrev_b32_e32 v159, 7, v159
	v_mul_u32_u24_e32 v159, 0x810, v159
	v_sub_u32_e32 v165, v158, v159
	v_cmp_eq_u32_e64 s[8:9], 0, v165
	v_cndmask_b32_e64 v146, v147, v146, s[6:7]
	ds_read_b128 v[174:177], v211
	v_cndmask_b32_e64 v147, v146, 0, s[8:9]
	s_waitcnt lgkmcnt(2)
	v_mov_b32_e32 v146, v151
	v_add_u32_e32 v151, s25, v210
	ds_read_b128 v[180:183], v151
	v_cmp_lt_u32_e64 s[10:11], 1, v165
	v_cndmask_b32_e64 v142, v143, v142, s[6:7]
	v_cndmask_b32_e32 v140, v140, v141, vcc
	v_cndmask_b32_e64 v151, v142, 0, s[8:9]
	v_mov_b32_e32 v142, v106
	s_waitcnt lgkmcnt(2)
	v_mov_b32_e32 v143, v156
	v_cndmask_b32_e64 v140, 0, v140, s[10:11]
	v_pk_mul_f32 v[142:143], v[142:143], v[150:151]
	s_waitcnt lgkmcnt(0)
	v_fma_f32 v140, v140, v182, v176
	v_add_f32_e32 v140, v143, v140
	v_cndmask_b32_e64 v134, v135, v134, s[6:7]
	v_cndmask_b32_e32 v132, v132, v133, vcc
	v_cndmask_b32_e64 v130, v131, v130, s[6:7]
	v_cndmask_b32_e32 v128, v128, v129, vcc
	v_add_f32_e32 v220, v142, v140
	v_cndmask_b32_e64 v135, v134, 0, s[8:9]
	v_mov_b32_e32 v140, v105
	v_mov_b32_e32 v141, v155
	v_mov_b32_e32 v134, v149
	v_cndmask_b32_e64 v132, 0, v132, s[10:11]
	v_cndmask_b32_e64 v149, v130, 0, s[8:9]
	v_mov_b32_e32 v130, v104
	v_mov_b32_e32 v131, v154
	v_cndmask_b32_e64 v128, 0, v128, s[10:11]
	v_pk_mul_f32 v[134:135], v[140:141], v[134:135]
	v_fma_f32 v132, v132, v181, v175
	v_pk_mul_f32 v[130:131], v[130:131], v[148:149]
	v_fmac_f32_e32 v174, v128, v180
	v_add_f32_e32 v132, v135, v132
	v_add_f32_e32 v128, v131, v174
	v_add_f32_e32 v170, v134, v132
	v_add_f32_e32 v165, v130, v128
	ds_read_b128 v[128:131], v209
	ds_read_b128 v[132:135], v208
	v_cndmask_b32_e32 v144, v144, v145, vcc
	v_mov_b32_e32 v158, v107
	v_mov_b32_e32 v159, v157
	v_cndmask_b32_e64 v144, 0, v144, s[10:11]
	v_pk_mul_f32 v[146:147], v[158:159], v[146:147]
	v_fma_f32 v144, v144, v183, v177
	v_cndmask_b32_e64 v138, v139, v138, s[6:7]
	v_add_f32_e32 v144, v147, v144
	v_cndmask_b32_e64 v139, v138, 0, s[8:9]
	v_mov_b32_e32 v140, v103
	s_waitcnt lgkmcnt(0)
	v_mov_b32_e32 v141, v135
	v_mov_b32_e32 v138, v131
	v_add_u32_e32 v131, s25, v206
	v_add_f32_e32 v224, v146, v144
	v_pk_mul_f32 v[138:139], v[140:141], v[138:139]
	ds_read_b128 v[140:143], v207
	ds_read_b128 v[144:147], v131
	v_cndmask_b32_e32 v131, v136, v137, vcc
	v_cndmask_b32_e64 v131, 0, v131, s[10:11]
	v_cndmask_b32_e64 v135, v153, v152, s[6:7]
	v_cndmask_b32_e64 v153, v135, 0, s[8:9]
	s_waitcnt lgkmcnt(0)
	v_fma_f32 v131, v131, v147, v143
	v_add_f32_e32 v131, v139, v131
	v_add_f32_e32 v131, v138, v131
	ds_read_b128 v[136:139], v205
	ds_read_b128 v[148:151], v204
	v_mov_b32_e32 v154, v111
	v_add_u32_e32 v135, s25, v172
	ds_read_b128 v[156:159], v135
	s_waitcnt lgkmcnt(2)
	v_mov_b32_e32 v152, v139
	s_waitcnt lgkmcnt(1)
	v_mov_b32_e32 v155, v151
	v_pk_mul_f32 v[174:175], v[154:155], v[152:153]
	ds_read_b128 v[152:155], v203
	v_cndmask_b32_e32 v135, v251, v252, vcc
	v_cndmask_b32_e64 v135, 0, v135, s[10:11]
	s_waitcnt lgkmcnt(0)
	v_fma_f32 v135, v135, v159, v155
	v_add_f32_e32 v135, v175, v135
	v_add_f32_e32 v135, v174, v135
	v_mul_f32_e32 v139, 0x3d372713, v135
	v_mul_f32_e32 v139, v135, v139
	v_fma_f32 v139, v135, v139, v135
	v_mul_f32_e32 v139, 0x3f4c422a, v139
	v_mul_f32_e32 v139, 0xc038aa3b, v139
	v_exp_f32_e32 v139, v139
	v_mov_b32_e32 v175, v134
	v_cndmask_b32_e32 v134, v247, v248, vcc
	v_mov_b32_e32 v174, v102
	v_add_f32_e32 v139, 1.0, v139
	v_rcp_f32_e32 v139, v139
	v_cndmask_b32_e64 v134, 0, v134, s[10:11]
	v_fma_f32 v134, v134, v146, v142
	v_mul_f32_e32 v135, v135, v139
	v_mul_f32_e32 v135, v131, v135
	v_cndmask_b32_e64 v131, v250, v249, s[6:7]
	v_cndmask_b32_e64 v131, v131, 0, s[8:9]
	v_pk_mul_f32 v[130:131], v[174:175], v[130:131]
	s_nop 0
	v_add_f32_e32 v131, v131, v134
	v_add_f32_e32 v134, v130, v131
	v_cndmask_b32_e64 v130, v246, v245, s[6:7]
	v_cndmask_b32_e64 v139, v130, 0, s[8:9]
	v_mov_b32_e32 v130, v110
	v_mov_b32_e32 v131, v150
	v_pk_mul_f32 v[130:131], v[130:131], v[138:139]
	v_cndmask_b32_e32 v138, v243, v244, vcc
	v_cndmask_b32_e64 v138, 0, v138, s[10:11]
	v_fma_f32 v138, v138, v158, v154
	v_add_f32_e32 v131, v131, v138
	v_add_f32_e32 v130, v130, v131
	v_mul_f32_e32 v131, 0x3d372713, v130
	v_mul_f32_e32 v131, v130, v131
	v_fma_f32 v131, v130, v131, v130
	v_mul_f32_e32 v131, 0x3f4c422a, v131
	v_mul_f32_e32 v131, 0xc038aa3b, v131
	v_exp_f32_e32 v131, v131
	v_mov_b32_e32 v138, v101
	v_mov_b32_e32 v139, v133
	v_cndmask_b32_e32 v133, v235, v236, vcc
	v_add_f32_e32 v131, 1.0, v131
	v_rcp_f32_e32 v131, v131
	v_cndmask_b32_e64 v133, 0, v133, s[10:11]
	v_fma_f32 v133, v133, v157, v153
	v_mul_f32_e32 v130, v130, v131
	v_mul_f32_e32 v134, v134, v130
	v_cndmask_b32_e64 v130, v242, v241, s[6:7]
	v_cndmask_b32_e64 v131, v130, 0, s[8:9]
	v_mov_b32_e32 v130, v129
	v_cndmask_b32_e32 v129, v239, v240, vcc
	v_cndmask_b32_e64 v129, 0, v129, s[10:11]
	v_pk_mul_f32 v[130:131], v[138:139], v[130:131]
	v_fma_f32 v129, v129, v145, v141
	v_add_f32_e32 v129, v131, v129
	v_add_f32_e32 v129, v130, v129
	v_cndmask_b32_e64 v130, v238, v237, s[6:7]
	v_cndmask_b32_e64 v131, v130, 0, s[8:9]
	v_mov_b32_e32 v138, v109
	v_mov_b32_e32 v139, v149
	v_mov_b32_e32 v130, v137
	v_pk_mul_f32 v[130:131], v[138:139], v[130:131]
	s_nop 0
	v_add_f32_e32 v131, v131, v133
	v_add_f32_e32 v130, v130, v131
	v_mul_f32_e32 v131, 0x3d372713, v130
	v_mul_f32_e32 v131, v130, v131
	v_fma_f32 v131, v130, v131, v130
	v_mul_f32_e32 v131, 0x3f4c422a, v131
	v_mul_f32_e32 v131, 0xc038aa3b, v131
	v_exp_f32_e32 v131, v131
	s_nop 0
	v_add_f32_e32 v131, 1.0, v131
	v_rcp_f32_e32 v131, v131
	s_nop 0
	v_mul_f32_e32 v130, v130, v131
	v_mul_f32_e32 v133, v129, v130
	v_cndmask_b32_e64 v129, v234, v233, s[6:7]
	v_cndmask_b32_e64 v129, v129, 0, s[8:9]
	v_mov_b32_e32 v130, v100
	v_mov_b32_e32 v131, v132
	v_pk_mul_f32 v[128:129], v[130:131], v[128:129]
	v_cndmask_b32_e32 v130, v231, v232, vcc
	v_cndmask_b32_e64 v130, 0, v130, s[10:11]
	v_fmac_f32_e32 v140, v130, v144
	v_add_f32_e32 v129, v129, v140
	v_add_f32_e32 v130, v128, v129
	v_cndmask_b32_e64 v128, v226, v225, s[6:7]
	v_cndmask_b32_e32 v131, v222, v223, vcc
	v_cndmask_b32_e64 v137, v128, 0, s[8:9]
	v_mov_b32_e32 v128, v108
	v_mov_b32_e32 v129, v148
	v_cndmask_b32_e64 v131, 0, v131, s[10:11]
	v_pk_mul_f32 v[128:129], v[128:129], v[136:137]
	v_fmac_f32_e32 v152, v131, v156
	v_add_f32_e32 v129, v129, v152
	v_add_f32_e32 v128, v128, v129
	v_mul_f32_e32 v129, 0x3d372713, v128
	v_mul_f32_e32 v129, v128, v129
	v_fma_f32 v129, v128, v129, v128
	v_mul_f32_e32 v129, 0x3f4c422a, v129
	v_mul_f32_e32 v129, 0xc038aa3b, v129
	v_exp_f32_e32 v129, v129
	v_mov_b32_e32 v131, v127
	v_add_f32_e32 v129, 1.0, v129
	v_rcp_f32_e32 v129, v129
	s_nop 0
	v_mul_f32_e32 v128, v128, v129
	v_mul_f32_e32 v132, v130, v128
	v_cndmask_b32_e64 v128, v230, v229, s[6:7]
	v_cndmask_b32_e64 v129, v128, 0, s[8:9]
	v_mov_b32_e32 v128, v119
	v_cndmask_b32_e32 v119, v227, v228, vcc
	v_cndmask_b32_e64 v119, 0, v119, s[10:11]
	v_fma_f32 v115, v119, v123, v115
	v_mul_f32_e32 v119, 0x3d372713, v224
	v_mul_f32_e32 v119, v224, v119
	v_fma_f32 v119, v224, v119, v224
	v_mul_f32_e32 v119, 0x3f4c422a, v119
	v_mul_f32_e32 v119, 0xc038aa3b, v119
	v_exp_f32_e32 v119, v119
	v_mov_b32_e32 v130, v99
	v_pk_mul_f32 v[128:129], v[130:131], v[128:129]
	v_add_f32_e32 v119, 1.0, v119
	v_rcp_f32_e32 v119, v119
	v_add_f32_e32 v115, v129, v115
	v_add_f32_e32 v115, v128, v115
	v_mov_b32_e32 v128, v98
	v_mul_f32_e32 v119, v224, v119
	v_mul_f32_e32 v123, v115, v119
	v_cndmask_b32_e64 v115, v221, v191, s[6:7]
	v_cndmask_b32_e64 v119, v115, 0, s[8:9]
	v_cndmask_b32_e32 v115, v171, v190, vcc
	v_cndmask_b32_e64 v115, 0, v115, s[10:11]
	v_fma_f32 v114, v115, v122, v114
	v_mul_f32_e32 v115, 0x3d372713, v220
	v_mul_f32_e32 v115, v220, v115
	v_fma_f32 v115, v220, v115, v220
	v_mul_f32_e32 v115, 0x3f4c422a, v115
	v_mul_f32_e32 v115, 0xc038aa3b, v115
	v_exp_f32_e32 v115, v115
	v_mov_b32_e32 v129, v126
	v_pk_mul_f32 v[118:119], v[128:129], v[118:119]
	v_add_f32_e32 v115, 1.0, v115
	v_rcp_f32_e32 v115, v115
	v_add_f32_e32 v114, v119, v114
	v_add_f32_e32 v114, v118, v114
	v_mov_b32_e32 v118, v97
	v_mul_f32_e32 v115, v220, v115
	v_mul_f32_e32 v122, v114, v115
	v_cndmask_b32_e64 v114, v169, v168, s[6:7]
	v_cndmask_b32_e64 v115, v114, 0, s[8:9]
	v_mov_b32_e32 v114, v117
	v_cndmask_b32_e32 v117, v166, v167, vcc
	v_mov_b32_e32 v119, v125
	v_cndmask_b32_e64 v117, 0, v117, s[10:11]
	v_pk_mul_f32 v[114:115], v[118:119], v[114:115]
	v_fma_f32 v113, v117, v121, v113
	v_add_f32_e32 v113, v115, v113
	v_add_f32_e32 v113, v114, v113
	v_mul_f32_e32 v114, 0x3d372713, v170
	v_mul_f32_e32 v114, v170, v114
	v_fma_f32 v114, v170, v114, v170
	v_mul_f32_e32 v114, 0x3f4c422a, v114
	v_mul_f32_e32 v114, 0xc038aa3b, v114
	v_exp_f32_e32 v114, v114
	v_mov_b32_e32 v115, v124
	v_add_f32_e32 v114, 1.0, v114
	v_rcp_f32_e32 v114, v114
	s_nop 0
	v_mul_f32_e32 v114, v170, v114
	v_mul_f32_e32 v118, v113, v114
	v_cndmask_b32_e64 v113, v164, v163, s[6:7]
	v_cndmask_b32_e64 v117, v113, 0, s[8:9]
	v_cndmask_b32_e32 v113, v161, v162, vcc
	v_cndmask_b32_e64 v113, 0, v113, s[10:11]
	v_fmac_f32_e32 v112, v113, v120
	v_mul_f32_e32 v113, 0x3d372713, v165
	v_mul_f32_e32 v113, v165, v113
	v_fma_f32 v113, v165, v113, v165
	v_mul_f32_e32 v113, 0x3f4c422a, v113
	v_mul_f32_e32 v113, 0xc038aa3b, v113
	v_exp_f32_e32 v113, v113
	v_mov_b32_e32 v114, v96
	v_pk_mul_f32 v[114:115], v[114:115], v[116:117]
	v_mov_b64_e32 v[116:117], s[16:17]
	v_add_f32_e32 v113, 1.0, v113
	v_rcp_f32_e32 v113, v113
	v_add_f32_e32 v112, v115, v112
	v_add_f32_e32 v112, v114, v112
	v_mad_i64_i32 v[116:117], s[8:9], v160, s79, v[116:117]
	v_mul_f32_e32 v113, v165, v113
	v_mul_f32_e32 v114, v112, v113
	v_lshl_add_u64 v[116:117], v[188:189], 1, v[116:117]
	v_cvt_pk_bf16_f32 v112, v132, v133
	v_cvt_pk_bf16_f32 v113, v134, v135
	v_cvt_pk_bf16_f32 v114, v114, v118
	v_cvt_pk_bf16_f32 v115, v122, v123
	global_store_dwordx4 v[116:117], v[112:115], off sc1
.LBB0_997:
	s_or_b64 exec, exec, s[30:31]
	v_add3_u32 v144, s0, v219, 32
	v_mov_b32_dpp v163, v108 row_mirror row_mask:0xf bank_mask:0xf bound_ctrl:1
	v_mov_b32_dpp v221, v109 row_mirror row_mask:0xf bank_mask:0xf bound_ctrl:1
	v_mov_b32_dpp v229, v110 row_mirror row_mask:0xf bank_mask:0xf bound_ctrl:1
	v_mov_b32_dpp v136, v111 row_mirror row_mask:0xf bank_mask:0xf bound_ctrl:1
	v_mov_b32_dpp v171, v100 row_mirror row_mask:0xf bank_mask:0xf bound_ctrl:1
	v_mov_b32_dpp v225, v101 row_mirror row_mask:0xf bank_mask:0xf bound_ctrl:1
	v_mov_b32_dpp v233, v102 row_mirror row_mask:0xf bank_mask:0xf bound_ctrl:1
	v_mov_b32_dpp v122, v103 row_mirror row_mask:0xf bank_mask:0xf bound_ctrl:1
	v_mov_b32_dpp v114, v104 row_mirror row_mask:0xf bank_mask:0xf bound_ctrl:1
	v_mov_b32_dpp v118, v105 row_mirror row_mask:0xf bank_mask:0xf bound_ctrl:1
	v_mov_b32_dpp v126, v106 row_mirror row_mask:0xf bank_mask:0xf bound_ctrl:1
	v_mov_b32_dpp v130, v107 row_mirror row_mask:0xf bank_mask:0xf bound_ctrl:1
	v_mov_b32_dpp v147, v96 row_mirror row_mask:0xf bank_mask:0xf bound_ctrl:1
	v_mov_b32_dpp v152, v97 row_mirror row_mask:0xf bank_mask:0xf bound_ctrl:1
	v_mov_b32_dpp v157, v98 row_mirror row_mask:0xf bank_mask:0xf bound_ctrl:1
	v_mov_b32_dpp v167, v99 row_mirror row_mask:0xf bank_mask:0xf bound_ctrl:1
	v_mov_b32_dpp v160, v163 quad_perm:[1,0,3,2] row_mask:0xf bank_mask:0xf bound_ctrl:1
	v_mov_b32_dpp v164, v92 row_shr:1 row_mask:0xf bank_mask:0xf bound_ctrl:1
	v_mov_b32_dpp v161, v92 row_shr:2 row_mask:0xf bank_mask:0xf bound_ctrl:1
	v_mov_b32_dpp v191, v221 quad_perm:[1,0,3,2] row_mask:0xf bank_mask:0xf bound_ctrl:1
	v_mov_b32_dpp v222, v93 row_shr:1 row_mask:0xf bank_mask:0xf bound_ctrl:1
	v_mov_b32_dpp v220, v93 row_shr:2 row_mask:0xf bank_mask:0xf bound_ctrl:1
	v_mov_b32_dpp v227, v229 quad_perm:[1,0,3,2] row_mask:0xf bank_mask:0xf bound_ctrl:1
	v_mov_b32_dpp v230, v94 row_shr:1 row_mask:0xf bank_mask:0xf bound_ctrl:1
	v_mov_b32_dpp v228, v94 row_shr:2 row_mask:0xf bank_mask:0xf bound_ctrl:1
	v_mov_b32_dpp v235, v136 quad_perm:[1,0,3,2] row_mask:0xf bank_mask:0xf bound_ctrl:1
	v_mov_b32_dpp v137, v95 row_shr:1 row_mask:0xf bank_mask:0xf bound_ctrl:1
	v_mov_b32_dpp v236, v95 row_shr:2 row_mask:0xf bank_mask:0xf bound_ctrl:1
	v_mov_b32_dpp v169, v171 quad_perm:[1,0,3,2] row_mask:0xf bank_mask:0xf bound_ctrl:1
	v_mov_b32_dpp v190, v84 row_shr:1 row_mask:0xf bank_mask:0xf bound_ctrl:1
	v_mov_b32_dpp v170, v84 row_shr:2 row_mask:0xf bank_mask:0xf bound_ctrl:1
	v_mov_b32_dpp v223, v225 quad_perm:[1,0,3,2] row_mask:0xf bank_mask:0xf bound_ctrl:1
	v_mov_b32_dpp v226, v85 row_shr:1 row_mask:0xf bank_mask:0xf bound_ctrl:1
	v_mov_b32_dpp v224, v85 row_shr:2 row_mask:0xf bank_mask:0xf bound_ctrl:1
	v_mov_b32_dpp v231, v233 quad_perm:[1,0,3,2] row_mask:0xf bank_mask:0xf bound_ctrl:1
	v_mov_b32_dpp v234, v86 row_shr:1 row_mask:0xf bank_mask:0xf bound_ctrl:1
	v_mov_b32_dpp v232, v86 row_shr:2 row_mask:0xf bank_mask:0xf bound_ctrl:1
	v_mov_b32_dpp v120, v122 quad_perm:[1,0,3,2] row_mask:0xf bank_mask:0xf bound_ctrl:1
	v_mov_b32_dpp v123, v87 row_shr:1 row_mask:0xf bank_mask:0xf bound_ctrl:1
	v_mov_b32_dpp v121, v87 row_shr:2 row_mask:0xf bank_mask:0xf bound_ctrl:1
	v_mov_b32_dpp v112, v114 quad_perm:[1,0,3,2] row_mask:0xf bank_mask:0xf bound_ctrl:1
	v_mov_b32_dpp v115, v88 row_shr:1 row_mask:0xf bank_mask:0xf bound_ctrl:1
	v_mov_b32_dpp v113, v88 row_shr:2 row_mask:0xf bank_mask:0xf bound_ctrl:1
	v_mov_b32_dpp v116, v118 quad_perm:[1,0,3,2] row_mask:0xf bank_mask:0xf bound_ctrl:1
	v_mov_b32_dpp v119, v89 row_shr:1 row_mask:0xf bank_mask:0xf bound_ctrl:1
	v_mov_b32_dpp v117, v89 row_shr:2 row_mask:0xf bank_mask:0xf bound_ctrl:1
	v_mov_b32_dpp v124, v126 quad_perm:[1,0,3,2] row_mask:0xf bank_mask:0xf bound_ctrl:1
	v_mov_b32_dpp v127, v90 row_shr:1 row_mask:0xf bank_mask:0xf bound_ctrl:1
	v_mov_b32_dpp v125, v90 row_shr:2 row_mask:0xf bank_mask:0xf bound_ctrl:1
	v_mov_b32_dpp v128, v130 quad_perm:[1,0,3,2] row_mask:0xf bank_mask:0xf bound_ctrl:1
	v_mov_b32_dpp v131, v91 row_shr:1 row_mask:0xf bank_mask:0xf bound_ctrl:1
	v_mov_b32_dpp v129, v91 row_shr:2 row_mask:0xf bank_mask:0xf bound_ctrl:1
	v_mov_b32_dpp v145, v147 quad_perm:[1,0,3,2] row_mask:0xf bank_mask:0xf bound_ctrl:1
	v_mov_b32_dpp v148, v80 row_shr:1 row_mask:0xf bank_mask:0xf bound_ctrl:1
	v_mov_b32_dpp v146, v80 row_shr:2 row_mask:0xf bank_mask:0xf bound_ctrl:1
	v_mov_b32_dpp v150, v152 quad_perm:[1,0,3,2] row_mask:0xf bank_mask:0xf bound_ctrl:1
	v_mov_b32_dpp v153, v81 row_shr:1 row_mask:0xf bank_mask:0xf bound_ctrl:1
	v_mov_b32_dpp v151, v81 row_shr:2 row_mask:0xf bank_mask:0xf bound_ctrl:1
	v_mov_b32_dpp v155, v157 quad_perm:[1,0,3,2] row_mask:0xf bank_mask:0xf bound_ctrl:1
	v_mov_b32_dpp v159, v82 row_shr:1 row_mask:0xf bank_mask:0xf bound_ctrl:1
	v_mov_b32_dpp v156, v82 row_shr:2 row_mask:0xf bank_mask:0xf bound_ctrl:1
	v_mov_b32_dpp v165, v167 quad_perm:[1,0,3,2] row_mask:0xf bank_mask:0xf bound_ctrl:1
	v_mov_b32_dpp v168, v83 row_shr:1 row_mask:0xf bank_mask:0xf bound_ctrl:1
	v_mov_b32_dpp v166, v83 row_shr:2 row_mask:0xf bank_mask:0xf bound_ctrl:1
	v_cmp_gt_i32_e64 s[8:9], s58, v144
	s_and_saveexec_b64 s[30:31], s[8:9]
	s_cbranch_execz .LBB0_999
	s_add_i32 s25, 0, 0x20000
	v_add_u32_e32 v142, 0x810, v144
	v_add_u32_e32 v104, s25, v212
	v_mul_hi_u32 v143, v142, s59
	ds_read_b128 v[96:99], v217
	ds_read_b128 v[100:103], v216
	ds_read_b128 v[108:111], v215
	ds_read_b128 v[104:107], v104
	ds_read_b128 v[132:135], v214
	ds_read_b128 v[138:141], v213
	v_lshrrev_b32_e32 v143, 7, v143
	v_mul_u32_u24_e32 v143, 0x810, v143
	v_sub_u32_e32 v149, v142, v143
	v_cmp_eq_u32_e64 s[8:9], 0, v149
	v_cndmask_b32_e64 v130, v131, v130, s[6:7]
	ds_read_b128 v[174:177], v211
	v_cndmask_b32_e64 v131, v130, 0, s[8:9]
	s_waitcnt lgkmcnt(2)
	v_mov_b32_e32 v130, v135
	v_add_u32_e32 v135, s25, v210
	ds_read_b128 v[180:183], v135
	v_cmp_lt_u32_e64 s[10:11], 1, v149
	v_cndmask_b32_e64 v126, v127, v126, s[6:7]
	v_cndmask_b32_e32 v124, v124, v125, vcc
	v_cndmask_b32_e64 v135, v126, 0, s[8:9]
	v_mov_b32_e32 v126, v90
	s_waitcnt lgkmcnt(2)
	v_mov_b32_e32 v127, v140
	v_cndmask_b32_e64 v124, 0, v124, s[10:11]
	v_pk_mul_f32 v[126:127], v[126:127], v[134:135]
	s_waitcnt lgkmcnt(0)
	v_fma_f32 v124, v124, v182, v176
	v_add_f32_e32 v124, v127, v124
	v_cndmask_b32_e64 v118, v119, v118, s[6:7]
	v_cndmask_b32_e32 v116, v116, v117, vcc
	v_cndmask_b32_e64 v114, v115, v114, s[6:7]
	v_cndmask_b32_e32 v112, v112, v113, vcc
	v_add_f32_e32 v158, v126, v124
	v_cndmask_b32_e64 v119, v118, 0, s[8:9]
	v_mov_b32_e32 v124, v89
	v_mov_b32_e32 v125, v139
	v_mov_b32_e32 v118, v133
	v_cndmask_b32_e64 v116, 0, v116, s[10:11]
	v_cndmask_b32_e64 v133, v114, 0, s[8:9]
	v_mov_b32_e32 v114, v88
	v_mov_b32_e32 v115, v138
	v_cndmask_b32_e64 v112, 0, v112, s[10:11]
	v_pk_mul_f32 v[118:119], v[124:125], v[118:119]
	v_fma_f32 v116, v116, v181, v175
	v_pk_mul_f32 v[114:115], v[114:115], v[132:133]
	v_fmac_f32_e32 v174, v112, v180
	v_add_f32_e32 v116, v119, v116
	v_add_f32_e32 v112, v115, v174
	v_add_f32_e32 v154, v118, v116
	v_add_f32_e32 v149, v114, v112
	ds_read_b128 v[112:115], v209
	ds_read_b128 v[116:119], v208
	v_cndmask_b32_e32 v128, v128, v129, vcc
	v_mov_b32_e32 v142, v91
	v_mov_b32_e32 v143, v141
	v_cndmask_b32_e64 v128, 0, v128, s[10:11]
	v_pk_mul_f32 v[130:131], v[142:143], v[130:131]
	v_fma_f32 v128, v128, v183, v177
	v_cndmask_b32_e64 v122, v123, v122, s[6:7]
	v_add_f32_e32 v128, v131, v128
	v_cndmask_b32_e64 v123, v122, 0, s[8:9]
	v_mov_b32_e32 v124, v87
	s_waitcnt lgkmcnt(0)
	v_mov_b32_e32 v125, v119
	v_mov_b32_e32 v122, v115
	v_add_u32_e32 v115, s25, v206
	v_add_f32_e32 v162, v130, v128
	v_pk_mul_f32 v[122:123], v[124:125], v[122:123]
	ds_read_b128 v[124:127], v207
	ds_read_b128 v[128:131], v115
	v_cndmask_b32_e32 v115, v120, v121, vcc
	v_cndmask_b32_e64 v115, 0, v115, s[10:11]
	v_cndmask_b32_e64 v119, v137, v136, s[6:7]
	v_cndmask_b32_e64 v137, v119, 0, s[8:9]
	s_waitcnt lgkmcnt(0)
	v_fma_f32 v115, v115, v131, v127
	v_add_f32_e32 v115, v123, v115
	v_add_f32_e32 v115, v122, v115
	ds_read_b128 v[120:123], v205
	ds_read_b128 v[132:135], v204
	v_mov_b32_e32 v138, v95
	v_add_u32_e32 v119, s25, v172
	ds_read_b128 v[140:143], v119
	s_waitcnt lgkmcnt(2)
	v_mov_b32_e32 v136, v123
	s_waitcnt lgkmcnt(1)
	v_mov_b32_e32 v139, v135
	v_pk_mul_f32 v[174:175], v[138:139], v[136:137]
	ds_read_b128 v[136:139], v203
	v_cndmask_b32_e32 v119, v235, v236, vcc
	v_cndmask_b32_e64 v119, 0, v119, s[10:11]
	s_waitcnt lgkmcnt(0)
	v_fma_f32 v119, v119, v143, v139
	v_add_f32_e32 v119, v175, v119
	v_add_f32_e32 v119, v174, v119
	v_mul_f32_e32 v123, 0x3d372713, v119
	v_mul_f32_e32 v123, v119, v123
	v_fma_f32 v123, v119, v123, v119
	v_mul_f32_e32 v123, 0x3f4c422a, v123
	v_mul_f32_e32 v123, 0xc038aa3b, v123
	v_exp_f32_e32 v123, v123
	v_mov_b32_e32 v175, v118
	v_cndmask_b32_e32 v118, v231, v232, vcc
	v_mov_b32_e32 v174, v86
	v_add_f32_e32 v123, 1.0, v123
	v_rcp_f32_e32 v123, v123
	v_cndmask_b32_e64 v118, 0, v118, s[10:11]
	v_fma_f32 v118, v118, v130, v126
	v_mul_f32_e32 v119, v119, v123
	v_mul_f32_e32 v119, v115, v119
	v_cndmask_b32_e64 v115, v234, v233, s[6:7]
	v_cndmask_b32_e64 v115, v115, 0, s[8:9]
	v_pk_mul_f32 v[114:115], v[174:175], v[114:115]
	s_nop 0
	v_add_f32_e32 v115, v115, v118
	v_add_f32_e32 v118, v114, v115
	v_cndmask_b32_e64 v114, v230, v229, s[6:7]
	v_cndmask_b32_e64 v123, v114, 0, s[8:9]
	v_mov_b32_e32 v114, v94
	v_mov_b32_e32 v115, v134
	v_pk_mul_f32 v[114:115], v[114:115], v[122:123]
	v_cndmask_b32_e32 v122, v227, v228, vcc
	v_cndmask_b32_e64 v122, 0, v122, s[10:11]
	v_fma_f32 v122, v122, v142, v138
	v_add_f32_e32 v115, v115, v122
	v_add_f32_e32 v114, v114, v115
	v_mul_f32_e32 v115, 0x3d372713, v114
	v_mul_f32_e32 v115, v114, v115
	v_fma_f32 v115, v114, v115, v114
	v_mul_f32_e32 v115, 0x3f4c422a, v115
	v_mul_f32_e32 v115, 0xc038aa3b, v115
	v_exp_f32_e32 v115, v115
	v_mov_b32_e32 v122, v85
	v_mov_b32_e32 v123, v117
	v_cndmask_b32_e32 v117, v191, v220, vcc
	v_add_f32_e32 v115, 1.0, v115
	v_rcp_f32_e32 v115, v115
	v_cndmask_b32_e64 v117, 0, v117, s[10:11]
	v_fma_f32 v117, v117, v141, v137
	v_mul_f32_e32 v114, v114, v115
	v_mul_f32_e32 v118, v118, v114
	v_cndmask_b32_e64 v114, v226, v225, s[6:7]
	v_cndmask_b32_e64 v115, v114, 0, s[8:9]
	v_mov_b32_e32 v114, v113
	v_cndmask_b32_e32 v113, v223, v224, vcc
	v_cndmask_b32_e64 v113, 0, v113, s[10:11]
	v_pk_mul_f32 v[114:115], v[122:123], v[114:115]
	v_fma_f32 v113, v113, v129, v125
	v_add_f32_e32 v113, v115, v113
	v_add_f32_e32 v113, v114, v113
	v_cndmask_b32_e64 v114, v222, v221, s[6:7]
	v_cndmask_b32_e64 v115, v114, 0, s[8:9]
	v_mov_b32_e32 v122, v93
	v_mov_b32_e32 v123, v133
	v_mov_b32_e32 v114, v121
	v_pk_mul_f32 v[114:115], v[122:123], v[114:115]
	s_nop 0
	v_add_f32_e32 v115, v115, v117
	v_add_f32_e32 v114, v114, v115
	v_mul_f32_e32 v115, 0x3d372713, v114
	v_mul_f32_e32 v115, v114, v115
	v_fma_f32 v115, v114, v115, v114
	v_mul_f32_e32 v115, 0x3f4c422a, v115
	v_mul_f32_e32 v115, 0xc038aa3b, v115
	v_exp_f32_e32 v115, v115
	s_nop 0
	v_add_f32_e32 v115, 1.0, v115
	v_rcp_f32_e32 v115, v115
	s_nop 0
	v_mul_f32_e32 v114, v114, v115
	v_mul_f32_e32 v117, v113, v114
	v_cndmask_b32_e64 v113, v190, v171, s[6:7]
	v_cndmask_b32_e64 v113, v113, 0, s[8:9]
	v_mov_b32_e32 v114, v84
	v_mov_b32_e32 v115, v116
	v_pk_mul_f32 v[112:113], v[114:115], v[112:113]
	v_cndmask_b32_e32 v114, v169, v170, vcc
	v_cndmask_b32_e64 v114, 0, v114, s[10:11]
	v_fmac_f32_e32 v124, v114, v128
	v_add_f32_e32 v113, v113, v124
	v_add_f32_e32 v114, v112, v113
	v_cndmask_b32_e64 v112, v164, v163, s[6:7]
	v_cndmask_b32_e32 v115, v160, v161, vcc
	v_cndmask_b32_e64 v121, v112, 0, s[8:9]
	v_mov_b32_e32 v112, v92
	v_mov_b32_e32 v113, v132
	v_cndmask_b32_e64 v115, 0, v115, s[10:11]
	v_pk_mul_f32 v[112:113], v[112:113], v[120:121]
	v_fmac_f32_e32 v136, v115, v140
	v_add_f32_e32 v113, v113, v136
	v_add_f32_e32 v112, v112, v113
	v_mul_f32_e32 v113, 0x3d372713, v112
	v_mul_f32_e32 v113, v112, v113
	v_fma_f32 v113, v112, v113, v112
	v_mul_f32_e32 v113, 0x3f4c422a, v113
	v_mul_f32_e32 v113, 0xc038aa3b, v113
	v_exp_f32_e32 v113, v113
	v_mov_b32_e32 v115, v111
	v_add_f32_e32 v113, 1.0, v113
	v_rcp_f32_e32 v113, v113
	s_nop 0
	v_mul_f32_e32 v112, v112, v113
	v_mul_f32_e32 v116, v114, v112
	v_cndmask_b32_e64 v112, v168, v167, s[6:7]
	v_cndmask_b32_e64 v113, v112, 0, s[8:9]
	v_mov_b32_e32 v112, v103
	v_cndmask_b32_e32 v103, v165, v166, vcc
	v_cndmask_b32_e64 v103, 0, v103, s[10:11]
	v_fma_f32 v99, v103, v107, v99
	v_mul_f32_e32 v103, 0x3d372713, v162
	v_mul_f32_e32 v103, v162, v103
	v_fma_f32 v103, v162, v103, v162
	v_mul_f32_e32 v103, 0x3f4c422a, v103
	v_mul_f32_e32 v103, 0xc038aa3b, v103
	v_exp_f32_e32 v103, v103
	v_mov_b32_e32 v114, v83
	v_pk_mul_f32 v[112:113], v[114:115], v[112:113]
	v_add_f32_e32 v103, 1.0, v103
	v_rcp_f32_e32 v103, v103
	v_add_f32_e32 v99, v113, v99
	v_add_f32_e32 v99, v112, v99
	v_mov_b32_e32 v112, v82
	v_mul_f32_e32 v103, v162, v103
	v_mul_f32_e32 v107, v99, v103
	v_cndmask_b32_e64 v99, v159, v157, s[6:7]
	v_cndmask_b32_e64 v103, v99, 0, s[8:9]
	v_cndmask_b32_e32 v99, v155, v156, vcc
	v_cndmask_b32_e64 v99, 0, v99, s[10:11]
	v_fma_f32 v98, v99, v106, v98
	v_mul_f32_e32 v99, 0x3d372713, v158
	v_mul_f32_e32 v99, v158, v99
	v_fma_f32 v99, v158, v99, v158
	v_mul_f32_e32 v99, 0x3f4c422a, v99
	v_mul_f32_e32 v99, 0xc038aa3b, v99
	v_exp_f32_e32 v99, v99
	v_mov_b32_e32 v113, v110
	v_pk_mul_f32 v[102:103], v[112:113], v[102:103]
	v_add_f32_e32 v99, 1.0, v99
	v_rcp_f32_e32 v99, v99
	v_add_f32_e32 v98, v103, v98
	v_add_f32_e32 v98, v102, v98
	v_mov_b32_e32 v102, v81
	v_mul_f32_e32 v99, v158, v99
	v_mul_f32_e32 v106, v98, v99
	v_cndmask_b32_e64 v98, v153, v152, s[6:7]
	v_cndmask_b32_e64 v99, v98, 0, s[8:9]
	v_mov_b32_e32 v98, v101
	v_cndmask_b32_e32 v101, v150, v151, vcc
	v_mov_b32_e32 v103, v109
	v_cndmask_b32_e64 v101, 0, v101, s[10:11]
	v_pk_mul_f32 v[98:99], v[102:103], v[98:99]
	v_fma_f32 v97, v101, v105, v97
	v_add_f32_e32 v97, v99, v97
	v_add_f32_e32 v97, v98, v97
	v_mul_f32_e32 v98, 0x3d372713, v154
	v_mul_f32_e32 v98, v154, v98
	v_fma_f32 v98, v154, v98, v154
	v_mul_f32_e32 v98, 0x3f4c422a, v98
	v_mul_f32_e32 v98, 0xc038aa3b, v98
	v_exp_f32_e32 v98, v98
	v_mov_b32_e32 v99, v108
	v_add_f32_e32 v98, 1.0, v98
	v_rcp_f32_e32 v98, v98
	s_nop 0
	v_mul_f32_e32 v98, v154, v98
	v_mul_f32_e32 v102, v97, v98
	v_cndmask_b32_e64 v97, v148, v147, s[6:7]
	v_cndmask_b32_e64 v101, v97, 0, s[8:9]
	v_cndmask_b32_e32 v97, v145, v146, vcc
	v_cndmask_b32_e64 v97, 0, v97, s[10:11]
	v_fmac_f32_e32 v96, v97, v104
	v_mul_f32_e32 v97, 0x3d372713, v149
	v_mul_f32_e32 v97, v149, v97
	v_fma_f32 v97, v149, v97, v149
	v_mul_f32_e32 v97, 0x3f4c422a, v97
	v_mul_f32_e32 v97, 0xc038aa3b, v97
	v_exp_f32_e32 v97, v97
	v_mov_b32_e32 v98, v80
	v_pk_mul_f32 v[98:99], v[98:99], v[100:101]
	v_mov_b64_e32 v[100:101], s[16:17]
	v_add_f32_e32 v97, 1.0, v97
	v_rcp_f32_e32 v97, v97
	v_add_f32_e32 v96, v99, v96
	v_add_f32_e32 v96, v98, v96
	v_mad_i64_i32 v[100:101], s[8:9], v144, s79, v[100:101]
	v_mul_f32_e32 v97, v149, v97
	v_mul_f32_e32 v98, v96, v97
	v_lshl_add_u64 v[100:101], v[188:189], 1, v[100:101]
	v_cvt_pk_bf16_f32 v96, v116, v117
	v_cvt_pk_bf16_f32 v97, v118, v119
	v_cvt_pk_bf16_f32 v98, v98, v102
	v_cvt_pk_bf16_f32 v99, v106, v107
	global_store_dwordx4 v[100:101], v[96:99], off sc1
.LBB0_999:
	s_or_b64 exec, exec, s[30:31]
	v_add3_u32 v128, s0, v219, 48
	v_mov_b32_dpp v147, v92 row_mirror row_mask:0xf bank_mask:0xf bound_ctrl:1
	v_mov_b32_dpp v159, v93 row_mirror row_mask:0xf bank_mask:0xf bound_ctrl:1
	v_mov_b32_dpp v167, v94 row_mirror row_mask:0xf bank_mask:0xf bound_ctrl:1
	v_mov_b32_dpp v120, v95 row_mirror row_mask:0xf bank_mask:0xf bound_ctrl:1
	v_mov_b32_dpp v155, v84 row_mirror row_mask:0xf bank_mask:0xf bound_ctrl:1
	v_mov_b32_dpp v163, v85 row_mirror row_mask:0xf bank_mask:0xf bound_ctrl:1
	v_mov_b32_dpp v171, v86 row_mirror row_mask:0xf bank_mask:0xf bound_ctrl:1
	v_mov_b32_dpp v106, v87 row_mirror row_mask:0xf bank_mask:0xf bound_ctrl:1
	v_mov_b32_dpp v98, v88 row_mirror row_mask:0xf bank_mask:0xf bound_ctrl:1
	v_mov_b32_dpp v102, v89 row_mirror row_mask:0xf bank_mask:0xf bound_ctrl:1
	v_mov_b32_dpp v110, v90 row_mirror row_mask:0xf bank_mask:0xf bound_ctrl:1
	v_mov_b32_dpp v114, v91 row_mirror row_mask:0xf bank_mask:0xf bound_ctrl:1
	v_mov_b32_dpp v131, v80 row_mirror row_mask:0xf bank_mask:0xf bound_ctrl:1
	v_mov_b32_dpp v136, v81 row_mirror row_mask:0xf bank_mask:0xf bound_ctrl:1
	v_mov_b32_dpp v141, v82 row_mirror row_mask:0xf bank_mask:0xf bound_ctrl:1
	v_mov_b32_dpp v151, v83 row_mirror row_mask:0xf bank_mask:0xf bound_ctrl:1
	v_mov_b32_dpp v144, v147 quad_perm:[1,0,3,2] row_mask:0xf bank_mask:0xf bound_ctrl:1
	v_mov_b32_dpp v148, v76 row_shr:1 row_mask:0xf bank_mask:0xf bound_ctrl:1
	v_mov_b32_dpp v145, v76 row_shr:2 row_mask:0xf bank_mask:0xf bound_ctrl:1
	v_mov_b32_dpp v157, v159 quad_perm:[1,0,3,2] row_mask:0xf bank_mask:0xf bound_ctrl:1
	v_mov_b32_dpp v160, v77 row_shr:1 row_mask:0xf bank_mask:0xf bound_ctrl:1
	v_mov_b32_dpp v158, v77 row_shr:2 row_mask:0xf bank_mask:0xf bound_ctrl:1
	v_mov_b32_dpp v165, v167 quad_perm:[1,0,3,2] row_mask:0xf bank_mask:0xf bound_ctrl:1
	v_mov_b32_dpp v168, v78 row_shr:1 row_mask:0xf bank_mask:0xf bound_ctrl:1
	v_mov_b32_dpp v166, v78 row_shr:2 row_mask:0xf bank_mask:0xf bound_ctrl:1
	v_mov_b32_dpp v191, v120 quad_perm:[1,0,3,2] row_mask:0xf bank_mask:0xf bound_ctrl:1
	v_mov_b32_dpp v121, v79 row_shr:1 row_mask:0xf bank_mask:0xf bound_ctrl:1
	v_mov_b32_dpp v220, v79 row_shr:2 row_mask:0xf bank_mask:0xf bound_ctrl:1
	v_mov_b32_dpp v153, v155 quad_perm:[1,0,3,2] row_mask:0xf bank_mask:0xf bound_ctrl:1
	v_mov_b32_dpp v156, v68 row_shr:1 row_mask:0xf bank_mask:0xf bound_ctrl:1
	v_mov_b32_dpp v154, v68 row_shr:2 row_mask:0xf bank_mask:0xf bound_ctrl:1
	v_mov_b32_dpp v161, v163 quad_perm:[1,0,3,2] row_mask:0xf bank_mask:0xf bound_ctrl:1
	v_mov_b32_dpp v164, v69 row_shr:1 row_mask:0xf bank_mask:0xf bound_ctrl:1
	v_mov_b32_dpp v162, v69 row_shr:2 row_mask:0xf bank_mask:0xf bound_ctrl:1
	v_mov_b32_dpp v169, v171 quad_perm:[1,0,3,2] row_mask:0xf bank_mask:0xf bound_ctrl:1
	v_mov_b32_dpp v190, v70 row_shr:1 row_mask:0xf bank_mask:0xf bound_ctrl:1
	v_mov_b32_dpp v170, v70 row_shr:2 row_mask:0xf bank_mask:0xf bound_ctrl:1
	v_mov_b32_dpp v104, v106 quad_perm:[1,0,3,2] row_mask:0xf bank_mask:0xf bound_ctrl:1
	v_mov_b32_dpp v107, v71 row_shr:1 row_mask:0xf bank_mask:0xf bound_ctrl:1
	v_mov_b32_dpp v105, v71 row_shr:2 row_mask:0xf bank_mask:0xf bound_ctrl:1
	v_mov_b32_dpp v96, v98 quad_perm:[1,0,3,2] row_mask:0xf bank_mask:0xf bound_ctrl:1
	v_mov_b32_dpp v99, v72 row_shr:1 row_mask:0xf bank_mask:0xf bound_ctrl:1
	v_mov_b32_dpp v97, v72 row_shr:2 row_mask:0xf bank_mask:0xf bound_ctrl:1
	v_mov_b32_dpp v100, v102 quad_perm:[1,0,3,2] row_mask:0xf bank_mask:0xf bound_ctrl:1
	v_mov_b32_dpp v103, v73 row_shr:1 row_mask:0xf bank_mask:0xf bound_ctrl:1
	v_mov_b32_dpp v101, v73 row_shr:2 row_mask:0xf bank_mask:0xf bound_ctrl:1
	v_mov_b32_dpp v108, v110 quad_perm:[1,0,3,2] row_mask:0xf bank_mask:0xf bound_ctrl:1
	v_mov_b32_dpp v111, v74 row_shr:1 row_mask:0xf bank_mask:0xf bound_ctrl:1
	v_mov_b32_dpp v109, v74 row_shr:2 row_mask:0xf bank_mask:0xf bound_ctrl:1
	v_mov_b32_dpp v112, v114 quad_perm:[1,0,3,2] row_mask:0xf bank_mask:0xf bound_ctrl:1
	v_mov_b32_dpp v115, v75 row_shr:1 row_mask:0xf bank_mask:0xf bound_ctrl:1
	v_mov_b32_dpp v113, v75 row_shr:2 row_mask:0xf bank_mask:0xf bound_ctrl:1
	v_mov_b32_dpp v129, v131 quad_perm:[1,0,3,2] row_mask:0xf bank_mask:0xf bound_ctrl:1
	v_mov_b32_dpp v132, v64 row_shr:1 row_mask:0xf bank_mask:0xf bound_ctrl:1
	v_mov_b32_dpp v130, v64 row_shr:2 row_mask:0xf bank_mask:0xf bound_ctrl:1
	v_mov_b32_dpp v134, v136 quad_perm:[1,0,3,2] row_mask:0xf bank_mask:0xf bound_ctrl:1
	v_mov_b32_dpp v137, v65 row_shr:1 row_mask:0xf bank_mask:0xf bound_ctrl:1
	v_mov_b32_dpp v135, v65 row_shr:2 row_mask:0xf bank_mask:0xf bound_ctrl:1
	v_mov_b32_dpp v139, v141 quad_perm:[1,0,3,2] row_mask:0xf bank_mask:0xf bound_ctrl:1
	v_mov_b32_dpp v143, v66 row_shr:1 row_mask:0xf bank_mask:0xf bound_ctrl:1
	v_mov_b32_dpp v140, v66 row_shr:2 row_mask:0xf bank_mask:0xf bound_ctrl:1
	v_mov_b32_dpp v149, v151 quad_perm:[1,0,3,2] row_mask:0xf bank_mask:0xf bound_ctrl:1
	v_mov_b32_dpp v152, v67 row_shr:1 row_mask:0xf bank_mask:0xf bound_ctrl:1
	v_mov_b32_dpp v150, v67 row_shr:2 row_mask:0xf bank_mask:0xf bound_ctrl:1
	v_cmp_gt_i32_e64 s[8:9], s58, v128
	s_and_saveexec_b64 s[30:31], s[8:9]
	s_cbranch_execz .LBB0_1001
	s_add_i32 s25, 0, 0x20000
	v_add_u32_e32 v126, 0x810, v128
	v_add_u32_e32 v88, s25, v212
	v_mul_hi_u32 v127, v126, s59
	ds_read_b128 v[80:83], v217
	ds_read_b128 v[84:87], v216
	ds_read_b128 v[92:95], v215
	ds_read_b128 v[88:91], v88
	ds_read_b128 v[116:119], v214
	ds_read_b128 v[122:125], v213
	v_lshrrev_b32_e32 v127, 7, v127
	v_mul_u32_u24_e32 v127, 0x810, v127
	v_sub_u32_e32 v133, v126, v127
	v_cmp_eq_u32_e64 s[8:9], 0, v133
	v_cndmask_b32_e64 v114, v115, v114, s[6:7]
	ds_read_b128 v[174:177], v211
	v_cndmask_b32_e64 v115, v114, 0, s[8:9]
	s_waitcnt lgkmcnt(2)
	v_mov_b32_e32 v114, v119
	v_add_u32_e32 v119, s25, v210
	ds_read_b128 v[180:183], v119
	v_cmp_lt_u32_e64 s[10:11], 1, v133
	v_cndmask_b32_e64 v110, v111, v110, s[6:7]
	v_cndmask_b32_e32 v108, v108, v109, vcc
	v_cndmask_b32_e64 v119, v110, 0, s[8:9]
	v_mov_b32_e32 v110, v74
	s_waitcnt lgkmcnt(2)
	v_mov_b32_e32 v111, v124
	v_cndmask_b32_e64 v108, 0, v108, s[10:11]
	v_pk_mul_f32 v[110:111], v[110:111], v[118:119]
	s_waitcnt lgkmcnt(0)
	v_fma_f32 v108, v108, v182, v176
	v_add_f32_e32 v108, v111, v108
	v_cndmask_b32_e64 v102, v103, v102, s[6:7]
	v_cndmask_b32_e32 v100, v100, v101, vcc
	v_cndmask_b32_e64 v98, v99, v98, s[6:7]
	v_cndmask_b32_e32 v96, v96, v97, vcc
	v_add_f32_e32 v142, v110, v108
	v_cndmask_b32_e64 v103, v102, 0, s[8:9]
	v_mov_b32_e32 v108, v73
	v_mov_b32_e32 v109, v123
	v_mov_b32_e32 v102, v117
	v_cndmask_b32_e64 v100, 0, v100, s[10:11]
	v_cndmask_b32_e64 v117, v98, 0, s[8:9]
	v_mov_b32_e32 v98, v72
	v_mov_b32_e32 v99, v122
	v_cndmask_b32_e64 v96, 0, v96, s[10:11]
	v_pk_mul_f32 v[102:103], v[108:109], v[102:103]
	v_fma_f32 v100, v100, v181, v175
	v_pk_mul_f32 v[98:99], v[98:99], v[116:117]
	v_fmac_f32_e32 v174, v96, v180
	v_add_f32_e32 v100, v103, v100
	v_add_f32_e32 v96, v99, v174
	v_add_f32_e32 v138, v102, v100
	v_add_f32_e32 v133, v98, v96
	ds_read_b128 v[96:99], v209
	ds_read_b128 v[100:103], v208
	v_cndmask_b32_e32 v112, v112, v113, vcc
	v_mov_b32_e32 v126, v75
	v_mov_b32_e32 v127, v125
	v_cndmask_b32_e64 v112, 0, v112, s[10:11]
	v_pk_mul_f32 v[114:115], v[126:127], v[114:115]
	v_fma_f32 v112, v112, v183, v177
	v_cndmask_b32_e64 v106, v107, v106, s[6:7]
	v_add_f32_e32 v112, v115, v112
	v_cndmask_b32_e64 v107, v106, 0, s[8:9]
	v_mov_b32_e32 v108, v71
	s_waitcnt lgkmcnt(0)
	v_mov_b32_e32 v109, v103
	v_mov_b32_e32 v106, v99
	v_add_u32_e32 v99, s25, v206
	v_add_f32_e32 v146, v114, v112
	v_pk_mul_f32 v[106:107], v[108:109], v[106:107]
	ds_read_b128 v[108:111], v207
	ds_read_b128 v[112:115], v99
	v_cndmask_b32_e32 v99, v104, v105, vcc
	v_cndmask_b32_e64 v99, 0, v99, s[10:11]
	v_cndmask_b32_e64 v103, v121, v120, s[6:7]
	v_cndmask_b32_e64 v121, v103, 0, s[8:9]
	s_waitcnt lgkmcnt(0)
	v_fma_f32 v99, v99, v115, v111
	v_add_f32_e32 v99, v107, v99
	v_add_f32_e32 v99, v106, v99
	ds_read_b128 v[104:107], v205
	ds_read_b128 v[116:119], v204
	v_mov_b32_e32 v122, v79
	v_add_u32_e32 v103, s25, v172
	ds_read_b128 v[124:127], v103
	s_waitcnt lgkmcnt(2)
	v_mov_b32_e32 v120, v107
	s_waitcnt lgkmcnt(1)
	v_mov_b32_e32 v123, v119
	v_pk_mul_f32 v[174:175], v[122:123], v[120:121]
	ds_read_b128 v[120:123], v203
	v_cndmask_b32_e32 v103, v191, v220, vcc
	v_cndmask_b32_e64 v103, 0, v103, s[10:11]
	s_waitcnt lgkmcnt(0)
	v_fma_f32 v103, v103, v127, v123
	v_add_f32_e32 v103, v175, v103
	v_add_f32_e32 v103, v174, v103
	v_mul_f32_e32 v107, 0x3d372713, v103
	v_mul_f32_e32 v107, v103, v107
	v_fma_f32 v107, v103, v107, v103
	v_mul_f32_e32 v107, 0x3f4c422a, v107
	v_mul_f32_e32 v107, 0xc038aa3b, v107
	v_exp_f32_e32 v107, v107
	v_mov_b32_e32 v175, v102
	v_cndmask_b32_e32 v102, v169, v170, vcc
	v_mov_b32_e32 v174, v70
	v_add_f32_e32 v107, 1.0, v107
	v_rcp_f32_e32 v107, v107
	v_cndmask_b32_e64 v102, 0, v102, s[10:11]
	v_fma_f32 v102, v102, v114, v110
	v_mul_f32_e32 v103, v103, v107
	v_mul_f32_e32 v103, v99, v103
	v_cndmask_b32_e64 v99, v190, v171, s[6:7]
	v_cndmask_b32_e64 v99, v99, 0, s[8:9]
	v_pk_mul_f32 v[98:99], v[174:175], v[98:99]
	s_nop 0
	v_add_f32_e32 v99, v99, v102
	v_add_f32_e32 v102, v98, v99
	v_cndmask_b32_e64 v98, v168, v167, s[6:7]
	v_cndmask_b32_e64 v107, v98, 0, s[8:9]
	v_mov_b32_e32 v98, v78
	v_mov_b32_e32 v99, v118
	v_pk_mul_f32 v[98:99], v[98:99], v[106:107]
	v_cndmask_b32_e32 v106, v165, v166, vcc
	v_cndmask_b32_e64 v106, 0, v106, s[10:11]
	v_fma_f32 v106, v106, v126, v122
	v_add_f32_e32 v99, v99, v106
	v_add_f32_e32 v98, v98, v99
	v_mul_f32_e32 v99, 0x3d372713, v98
	v_mul_f32_e32 v99, v98, v99
	v_fma_f32 v99, v98, v99, v98
	v_mul_f32_e32 v99, 0x3f4c422a, v99
	v_mul_f32_e32 v99, 0xc038aa3b, v99
	v_exp_f32_e32 v99, v99
	v_mov_b32_e32 v106, v69
	v_mov_b32_e32 v107, v101
	v_cndmask_b32_e32 v101, v157, v158, vcc
	v_add_f32_e32 v99, 1.0, v99
	v_rcp_f32_e32 v99, v99
	v_cndmask_b32_e64 v101, 0, v101, s[10:11]
	v_fma_f32 v101, v101, v125, v121
	v_mul_f32_e32 v98, v98, v99
	v_mul_f32_e32 v102, v102, v98
	v_cndmask_b32_e64 v98, v164, v163, s[6:7]
	v_cndmask_b32_e64 v99, v98, 0, s[8:9]
	v_mov_b32_e32 v98, v97
	v_cndmask_b32_e32 v97, v161, v162, vcc
	v_cndmask_b32_e64 v97, 0, v97, s[10:11]
	v_pk_mul_f32 v[98:99], v[106:107], v[98:99]
	v_fma_f32 v97, v97, v113, v109
	v_add_f32_e32 v97, v99, v97
	v_add_f32_e32 v97, v98, v97
	v_cndmask_b32_e64 v98, v160, v159, s[6:7]
	v_cndmask_b32_e64 v99, v98, 0, s[8:9]
	v_mov_b32_e32 v106, v77
	v_mov_b32_e32 v107, v117
	v_mov_b32_e32 v98, v105
	v_pk_mul_f32 v[98:99], v[106:107], v[98:99]
	s_nop 0
	v_add_f32_e32 v99, v99, v101
	v_add_f32_e32 v98, v98, v99
	v_mul_f32_e32 v99, 0x3d372713, v98
	v_mul_f32_e32 v99, v98, v99
	v_fma_f32 v99, v98, v99, v98
	v_mul_f32_e32 v99, 0x3f4c422a, v99
	v_mul_f32_e32 v99, 0xc038aa3b, v99
	v_exp_f32_e32 v99, v99
	s_nop 0
	v_add_f32_e32 v99, 1.0, v99
	v_rcp_f32_e32 v99, v99
	s_nop 0
	v_mul_f32_e32 v98, v98, v99
	v_mul_f32_e32 v101, v97, v98
	v_cndmask_b32_e64 v97, v156, v155, s[6:7]
	v_cndmask_b32_e64 v97, v97, 0, s[8:9]
	v_mov_b32_e32 v98, v68
	v_mov_b32_e32 v99, v100
	v_pk_mul_f32 v[96:97], v[98:99], v[96:97]
	v_cndmask_b32_e32 v98, v153, v154, vcc
	v_cndmask_b32_e64 v98, 0, v98, s[10:11]
	v_fmac_f32_e32 v108, v98, v112
	v_add_f32_e32 v97, v97, v108
	v_add_f32_e32 v98, v96, v97
	v_cndmask_b32_e64 v96, v148, v147, s[6:7]
	v_cndmask_b32_e32 v99, v144, v145, vcc
	v_cndmask_b32_e64 v105, v96, 0, s[8:9]
	v_mov_b32_e32 v96, v76
	v_mov_b32_e32 v97, v116
	v_cndmask_b32_e64 v99, 0, v99, s[10:11]
	v_pk_mul_f32 v[96:97], v[96:97], v[104:105]
	v_fmac_f32_e32 v120, v99, v124
	v_add_f32_e32 v97, v97, v120
	v_add_f32_e32 v96, v96, v97
	v_mul_f32_e32 v97, 0x3d372713, v96
	v_mul_f32_e32 v97, v96, v97
	v_fma_f32 v97, v96, v97, v96
	v_mul_f32_e32 v97, 0x3f4c422a, v97
	v_mul_f32_e32 v97, 0xc038aa3b, v97
	v_exp_f32_e32 v97, v97
	v_mov_b32_e32 v99, v95
	v_add_f32_e32 v97, 1.0, v97
	v_rcp_f32_e32 v97, v97
	s_nop 0
	v_mul_f32_e32 v96, v96, v97
	v_mul_f32_e32 v100, v98, v96
	v_cndmask_b32_e64 v96, v152, v151, s[6:7]
	v_cndmask_b32_e64 v97, v96, 0, s[8:9]
	v_mov_b32_e32 v96, v87
	v_cndmask_b32_e32 v87, v149, v150, vcc
	v_cndmask_b32_e64 v87, 0, v87, s[10:11]
	v_fma_f32 v83, v87, v91, v83
	v_mul_f32_e32 v87, 0x3d372713, v146
	v_mul_f32_e32 v87, v146, v87
	v_fma_f32 v87, v146, v87, v146
	v_mul_f32_e32 v87, 0x3f4c422a, v87
	v_mul_f32_e32 v87, 0xc038aa3b, v87
	v_exp_f32_e32 v87, v87
	v_mov_b32_e32 v98, v67
	v_pk_mul_f32 v[96:97], v[98:99], v[96:97]
	v_add_f32_e32 v87, 1.0, v87
	v_rcp_f32_e32 v87, v87
	v_add_f32_e32 v83, v97, v83
	v_add_f32_e32 v83, v96, v83
	v_mov_b32_e32 v96, v66
	v_mul_f32_e32 v87, v146, v87
	v_mul_f32_e32 v91, v83, v87
	v_cndmask_b32_e64 v83, v143, v141, s[6:7]
	v_cndmask_b32_e64 v87, v83, 0, s[8:9]
	v_cndmask_b32_e32 v83, v139, v140, vcc
	v_cndmask_b32_e64 v83, 0, v83, s[10:11]
	v_fma_f32 v82, v83, v90, v82
	v_mul_f32_e32 v83, 0x3d372713, v142
	v_mul_f32_e32 v83, v142, v83
	v_fma_f32 v83, v142, v83, v142
	v_mul_f32_e32 v83, 0x3f4c422a, v83
	v_mul_f32_e32 v83, 0xc038aa3b, v83
	v_exp_f32_e32 v83, v83
	v_mov_b32_e32 v97, v94
	v_pk_mul_f32 v[86:87], v[96:97], v[86:87]
	v_add_f32_e32 v83, 1.0, v83
	v_rcp_f32_e32 v83, v83
	v_add_f32_e32 v82, v87, v82
	v_add_f32_e32 v82, v86, v82
	v_mov_b32_e32 v86, v65
	v_mul_f32_e32 v83, v142, v83
	v_mul_f32_e32 v90, v82, v83
	v_cndmask_b32_e64 v82, v137, v136, s[6:7]
	v_cndmask_b32_e64 v83, v82, 0, s[8:9]
	v_mov_b32_e32 v82, v85
	v_cndmask_b32_e32 v85, v134, v135, vcc
	v_mov_b32_e32 v87, v93
	v_cndmask_b32_e64 v85, 0, v85, s[10:11]
	v_pk_mul_f32 v[82:83], v[86:87], v[82:83]
	v_fma_f32 v81, v85, v89, v81
	v_add_f32_e32 v81, v83, v81
	v_add_f32_e32 v81, v82, v81
	v_mul_f32_e32 v82, 0x3d372713, v138
	v_mul_f32_e32 v82, v138, v82
	v_fma_f32 v82, v138, v82, v138
	v_mul_f32_e32 v82, 0x3f4c422a, v82
	v_mul_f32_e32 v82, 0xc038aa3b, v82
	v_exp_f32_e32 v82, v82
	v_mov_b32_e32 v83, v92
	v_add_f32_e32 v82, 1.0, v82
	v_rcp_f32_e32 v82, v82
	s_nop 0
	v_mul_f32_e32 v82, v138, v82
	v_mul_f32_e32 v86, v81, v82
	v_cndmask_b32_e64 v81, v132, v131, s[6:7]
	v_cndmask_b32_e64 v85, v81, 0, s[8:9]
	v_cndmask_b32_e32 v81, v129, v130, vcc
	v_cndmask_b32_e64 v81, 0, v81, s[10:11]
	v_fmac_f32_e32 v80, v81, v88
	v_mul_f32_e32 v81, 0x3d372713, v133
	v_mul_f32_e32 v81, v133, v81
	v_fma_f32 v81, v133, v81, v133
	v_mul_f32_e32 v81, 0x3f4c422a, v81
	v_mul_f32_e32 v81, 0xc038aa3b, v81
	v_exp_f32_e32 v81, v81
	v_mov_b32_e32 v82, v64
	v_pk_mul_f32 v[82:83], v[82:83], v[84:85]
	v_mov_b64_e32 v[84:85], s[16:17]
	v_add_f32_e32 v81, 1.0, v81
	v_rcp_f32_e32 v81, v81
	v_add_f32_e32 v80, v83, v80
	v_add_f32_e32 v80, v82, v80
	v_mad_i64_i32 v[84:85], s[8:9], v128, s79, v[84:85]
	v_mul_f32_e32 v81, v133, v81
	v_mul_f32_e32 v82, v80, v81
	v_lshl_add_u64 v[84:85], v[188:189], 1, v[84:85]
	v_cvt_pk_bf16_f32 v80, v100, v101
	v_cvt_pk_bf16_f32 v81, v102, v103
	v_cvt_pk_bf16_f32 v82, v82, v86
	v_cvt_pk_bf16_f32 v83, v90, v91
	global_store_dwordx4 v[84:85], v[80:83], off sc1
.LBB0_1001:
	s_or_b64 exec, exec, s[30:31]
	v_add3_u32 v112, s0, v219, 64
	v_mov_b32_dpp v131, v76 row_mirror row_mask:0xf bank_mask:0xf bound_ctrl:1
	v_mov_b32_dpp v143, v77 row_mirror row_mask:0xf bank_mask:0xf bound_ctrl:1
	v_mov_b32_dpp v151, v78 row_mirror row_mask:0xf bank_mask:0xf bound_ctrl:1
	v_mov_b32_dpp v104, v79 row_mirror row_mask:0xf bank_mask:0xf bound_ctrl:1
	v_mov_b32_dpp v139, v68 row_mirror row_mask:0xf bank_mask:0xf bound_ctrl:1
	v_mov_b32_dpp v147, v69 row_mirror row_mask:0xf bank_mask:0xf bound_ctrl:1
	v_mov_b32_dpp v155, v70 row_mirror row_mask:0xf bank_mask:0xf bound_ctrl:1
	v_mov_b32_dpp v90, v71 row_mirror row_mask:0xf bank_mask:0xf bound_ctrl:1
	v_mov_b32_dpp v82, v72 row_mirror row_mask:0xf bank_mask:0xf bound_ctrl:1
	v_mov_b32_dpp v86, v73 row_mirror row_mask:0xf bank_mask:0xf bound_ctrl:1
	v_mov_b32_dpp v94, v74 row_mirror row_mask:0xf bank_mask:0xf bound_ctrl:1
	v_mov_b32_dpp v98, v75 row_mirror row_mask:0xf bank_mask:0xf bound_ctrl:1
	v_mov_b32_dpp v115, v64 row_mirror row_mask:0xf bank_mask:0xf bound_ctrl:1
	v_mov_b32_dpp v120, v65 row_mirror row_mask:0xf bank_mask:0xf bound_ctrl:1
	v_mov_b32_dpp v125, v66 row_mirror row_mask:0xf bank_mask:0xf bound_ctrl:1
	v_mov_b32_dpp v135, v67 row_mirror row_mask:0xf bank_mask:0xf bound_ctrl:1
	v_mov_b32_dpp v128, v131 quad_perm:[1,0,3,2] row_mask:0xf bank_mask:0xf bound_ctrl:1
	v_mov_b32_dpp v132, v60 row_shr:1 row_mask:0xf bank_mask:0xf bound_ctrl:1
	v_mov_b32_dpp v129, v60 row_shr:2 row_mask:0xf bank_mask:0xf bound_ctrl:1
	v_mov_b32_dpp v141, v143 quad_perm:[1,0,3,2] row_mask:0xf bank_mask:0xf bound_ctrl:1
	v_mov_b32_dpp v144, v61 row_shr:1 row_mask:0xf bank_mask:0xf bound_ctrl:1
	v_mov_b32_dpp v142, v61 row_shr:2 row_mask:0xf bank_mask:0xf bound_ctrl:1
	v_mov_b32_dpp v149, v151 quad_perm:[1,0,3,2] row_mask:0xf bank_mask:0xf bound_ctrl:1
	v_mov_b32_dpp v152, v62 row_shr:1 row_mask:0xf bank_mask:0xf bound_ctrl:1
	v_mov_b32_dpp v150, v62 row_shr:2 row_mask:0xf bank_mask:0xf bound_ctrl:1
	v_mov_b32_dpp v157, v104 quad_perm:[1,0,3,2] row_mask:0xf bank_mask:0xf bound_ctrl:1
	v_mov_b32_dpp v105, v63 row_shr:1 row_mask:0xf bank_mask:0xf bound_ctrl:1
	v_mov_b32_dpp v158, v63 row_shr:2 row_mask:0xf bank_mask:0xf bound_ctrl:1
	v_mov_b32_dpp v137, v139 quad_perm:[1,0,3,2] row_mask:0xf bank_mask:0xf bound_ctrl:1
	v_mov_b32_dpp v140, v52 row_shr:1 row_mask:0xf bank_mask:0xf bound_ctrl:1
	v_mov_b32_dpp v138, v52 row_shr:2 row_mask:0xf bank_mask:0xf bound_ctrl:1
	v_mov_b32_dpp v145, v147 quad_perm:[1,0,3,2] row_mask:0xf bank_mask:0xf bound_ctrl:1
	v_mov_b32_dpp v148, v53 row_shr:1 row_mask:0xf bank_mask:0xf bound_ctrl:1
	v_mov_b32_dpp v146, v53 row_shr:2 row_mask:0xf bank_mask:0xf bound_ctrl:1
	v_mov_b32_dpp v153, v155 quad_perm:[1,0,3,2] row_mask:0xf bank_mask:0xf bound_ctrl:1
	v_mov_b32_dpp v156, v54 row_shr:1 row_mask:0xf bank_mask:0xf bound_ctrl:1
	v_mov_b32_dpp v154, v54 row_shr:2 row_mask:0xf bank_mask:0xf bound_ctrl:1
	v_mov_b32_dpp v88, v90 quad_perm:[1,0,3,2] row_mask:0xf bank_mask:0xf bound_ctrl:1
	v_mov_b32_dpp v91, v55 row_shr:1 row_mask:0xf bank_mask:0xf bound_ctrl:1
	v_mov_b32_dpp v89, v55 row_shr:2 row_mask:0xf bank_mask:0xf bound_ctrl:1
	v_mov_b32_dpp v80, v82 quad_perm:[1,0,3,2] row_mask:0xf bank_mask:0xf bound_ctrl:1
	v_mov_b32_dpp v83, v56 row_shr:1 row_mask:0xf bank_mask:0xf bound_ctrl:1
	v_mov_b32_dpp v81, v56 row_shr:2 row_mask:0xf bank_mask:0xf bound_ctrl:1
	v_mov_b32_dpp v84, v86 quad_perm:[1,0,3,2] row_mask:0xf bank_mask:0xf bound_ctrl:1
	v_mov_b32_dpp v87, v57 row_shr:1 row_mask:0xf bank_mask:0xf bound_ctrl:1
	v_mov_b32_dpp v85, v57 row_shr:2 row_mask:0xf bank_mask:0xf bound_ctrl:1
	v_mov_b32_dpp v92, v94 quad_perm:[1,0,3,2] row_mask:0xf bank_mask:0xf bound_ctrl:1
	v_mov_b32_dpp v95, v58 row_shr:1 row_mask:0xf bank_mask:0xf bound_ctrl:1
	v_mov_b32_dpp v93, v58 row_shr:2 row_mask:0xf bank_mask:0xf bound_ctrl:1
	v_mov_b32_dpp v96, v98 quad_perm:[1,0,3,2] row_mask:0xf bank_mask:0xf bound_ctrl:1
	v_mov_b32_dpp v99, v59 row_shr:1 row_mask:0xf bank_mask:0xf bound_ctrl:1
	v_mov_b32_dpp v97, v59 row_shr:2 row_mask:0xf bank_mask:0xf bound_ctrl:1
	v_mov_b32_dpp v113, v115 quad_perm:[1,0,3,2] row_mask:0xf bank_mask:0xf bound_ctrl:1
	v_mov_b32_dpp v116, v48 row_shr:1 row_mask:0xf bank_mask:0xf bound_ctrl:1
	v_mov_b32_dpp v114, v48 row_shr:2 row_mask:0xf bank_mask:0xf bound_ctrl:1
	v_mov_b32_dpp v118, v120 quad_perm:[1,0,3,2] row_mask:0xf bank_mask:0xf bound_ctrl:1
	v_mov_b32_dpp v121, v49 row_shr:1 row_mask:0xf bank_mask:0xf bound_ctrl:1
	v_mov_b32_dpp v119, v49 row_shr:2 row_mask:0xf bank_mask:0xf bound_ctrl:1
	v_mov_b32_dpp v123, v125 quad_perm:[1,0,3,2] row_mask:0xf bank_mask:0xf bound_ctrl:1
	v_mov_b32_dpp v127, v50 row_shr:1 row_mask:0xf bank_mask:0xf bound_ctrl:1
	v_mov_b32_dpp v124, v50 row_shr:2 row_mask:0xf bank_mask:0xf bound_ctrl:1
	v_mov_b32_dpp v133, v135 quad_perm:[1,0,3,2] row_mask:0xf bank_mask:0xf bound_ctrl:1
	v_mov_b32_dpp v136, v51 row_shr:1 row_mask:0xf bank_mask:0xf bound_ctrl:1
	v_mov_b32_dpp v134, v51 row_shr:2 row_mask:0xf bank_mask:0xf bound_ctrl:1
	v_cmp_gt_i32_e64 s[8:9], s58, v112
	s_and_saveexec_b64 s[30:31], s[8:9]
	s_cbranch_execz .LBB0_1003
	s_add_i32 s0, 0, 0x20000
	v_add_u32_e32 v110, 0x810, v112
	v_add_u32_e32 v72, s0, v212
	v_mul_hi_u32 v111, v110, s59
	ds_read_b128 v[64:67], v217
	ds_read_b128 v[68:71], v216
	ds_read_b128 v[76:79], v215
	ds_read_b128 v[72:75], v72
	ds_read_b128 v[100:103], v214
	ds_read_b128 v[106:109], v213
	v_lshrrev_b32_e32 v111, 7, v111
	v_mul_u32_u24_e32 v111, 0x810, v111
	v_sub_u32_e32 v117, v110, v111
	v_cmp_eq_u32_e64 s[8:9], 0, v117
	v_cndmask_b32_e64 v98, v99, v98, s[6:7]
	ds_read_b128 v[160:163], v211
	v_cndmask_b32_e64 v99, v98, 0, s[8:9]
	s_waitcnt lgkmcnt(2)
	v_mov_b32_e32 v98, v103
	v_add_u32_e32 v103, s0, v210
	ds_read_b128 v[164:167], v103
	v_cmp_lt_u32_e64 s[10:11], 1, v117
	v_cndmask_b32_e64 v94, v95, v94, s[6:7]
	v_cndmask_b32_e32 v92, v92, v93, vcc
	v_cndmask_b32_e64 v103, v94, 0, s[8:9]
	v_mov_b32_e32 v94, v58
	s_waitcnt lgkmcnt(2)
	v_mov_b32_e32 v95, v108
	v_cndmask_b32_e64 v92, 0, v92, s[10:11]
	v_pk_mul_f32 v[94:95], v[94:95], v[102:103]
	s_waitcnt lgkmcnt(0)
	v_fma_f32 v92, v92, v166, v162
	v_add_f32_e32 v92, v95, v92
	v_cndmask_b32_e64 v86, v87, v86, s[6:7]
	v_cndmask_b32_e32 v84, v84, v85, vcc
	v_cndmask_b32_e64 v82, v83, v82, s[6:7]
	v_cndmask_b32_e32 v80, v80, v81, vcc
	v_add_f32_e32 v126, v94, v92
	v_cndmask_b32_e64 v87, v86, 0, s[8:9]
	v_mov_b32_e32 v92, v57
	v_mov_b32_e32 v93, v107
	v_mov_b32_e32 v86, v101
	v_cndmask_b32_e64 v84, 0, v84, s[10:11]
	v_cndmask_b32_e64 v101, v82, 0, s[8:9]
	v_mov_b32_e32 v82, v56
	v_mov_b32_e32 v83, v106
	v_cndmask_b32_e64 v80, 0, v80, s[10:11]
	v_pk_mul_f32 v[86:87], v[92:93], v[86:87]
	v_fma_f32 v84, v84, v165, v161
	v_pk_mul_f32 v[82:83], v[82:83], v[100:101]
	v_fmac_f32_e32 v160, v80, v164
	v_add_f32_e32 v84, v87, v84
	v_add_f32_e32 v80, v83, v160
	v_add_f32_e32 v122, v86, v84
	v_add_f32_e32 v117, v82, v80
	ds_read_b128 v[80:83], v209
	ds_read_b128 v[84:87], v208
	v_cndmask_b32_e32 v96, v96, v97, vcc
	v_mov_b32_e32 v110, v59
	v_mov_b32_e32 v111, v109
	v_cndmask_b32_e64 v96, 0, v96, s[10:11]
	v_pk_mul_f32 v[98:99], v[110:111], v[98:99]
	v_fma_f32 v96, v96, v167, v163
	v_cndmask_b32_e64 v90, v91, v90, s[6:7]
	v_add_f32_e32 v96, v99, v96
	v_cndmask_b32_e64 v91, v90, 0, s[8:9]
	v_mov_b32_e32 v92, v55
	s_waitcnt lgkmcnt(0)
	v_mov_b32_e32 v93, v87
	v_mov_b32_e32 v90, v83
	v_add_u32_e32 v83, s0, v206
	v_add_f32_e32 v130, v98, v96
	v_pk_mul_f32 v[90:91], v[92:93], v[90:91]
	ds_read_b128 v[92:95], v207
	ds_read_b128 v[96:99], v83
	v_cndmask_b32_e32 v83, v88, v89, vcc
	v_cndmask_b32_e64 v83, 0, v83, s[10:11]
	v_cndmask_b32_e64 v87, v105, v104, s[6:7]
	v_cndmask_b32_e64 v105, v87, 0, s[8:9]
	s_waitcnt lgkmcnt(0)
	v_fma_f32 v83, v83, v99, v95
	v_add_f32_e32 v83, v91, v83
	v_add_f32_e32 v83, v90, v83
	ds_read_b128 v[88:91], v205
	ds_read_b128 v[100:103], v204
	v_mov_b32_e32 v106, v63
	v_add_u32_e32 v87, s0, v172
	ds_read_b128 v[108:111], v87
	s_waitcnt lgkmcnt(2)
	v_mov_b32_e32 v104, v91
	s_waitcnt lgkmcnt(1)
	v_mov_b32_e32 v107, v103
	v_pk_mul_f32 v[160:161], v[106:107], v[104:105]
	ds_read_b128 v[104:107], v203
	v_cndmask_b32_e32 v87, v157, v158, vcc
	v_cndmask_b32_e64 v87, 0, v87, s[10:11]
	v_mov_b32_e32 v157, v86
	v_cndmask_b32_e32 v86, v153, v154, vcc
	s_waitcnt lgkmcnt(0)
	v_fma_f32 v87, v87, v111, v107
	v_add_f32_e32 v87, v161, v87
	v_add_f32_e32 v87, v160, v87
	v_mul_f32_e32 v91, 0x3d372713, v87
	v_mul_f32_e32 v91, v87, v91
	v_fma_f32 v91, v87, v91, v87
	v_mul_f32_e32 v91, 0x3f4c422a, v91
	v_mul_f32_e32 v91, 0xc038aa3b, v91
	v_exp_f32_e32 v91, v91
	v_cndmask_b32_e64 v86, 0, v86, s[10:11]
	v_fma_f32 v86, v86, v98, v94
	v_add_f32_e32 v91, 1.0, v91
	v_rcp_f32_e32 v91, v91
	s_nop 0
	v_mul_f32_e32 v87, v87, v91
	v_mul_f32_e32 v87, v83, v87
	v_cndmask_b32_e64 v83, v156, v155, s[6:7]
	v_cndmask_b32_e64 v83, v83, 0, s[8:9]
	v_mov_b32_e32 v156, v54
	v_pk_mul_f32 v[82:83], v[156:157], v[82:83]
	s_nop 0
	v_add_f32_e32 v83, v83, v86
	v_add_f32_e32 v86, v82, v83
	v_cndmask_b32_e64 v82, v152, v151, s[6:7]
	v_cndmask_b32_e64 v91, v82, 0, s[8:9]
	v_mov_b32_e32 v82, v62
	v_mov_b32_e32 v83, v102
	v_pk_mul_f32 v[82:83], v[82:83], v[90:91]
	v_cndmask_b32_e32 v90, v149, v150, vcc
	v_cndmask_b32_e64 v90, 0, v90, s[10:11]
	v_fma_f32 v90, v90, v110, v106
	v_add_f32_e32 v83, v83, v90
	v_add_f32_e32 v82, v82, v83
	v_mul_f32_e32 v83, 0x3d372713, v82
	v_mul_f32_e32 v83, v82, v83
	v_fma_f32 v83, v82, v83, v82
	v_mul_f32_e32 v83, 0x3f4c422a, v83
	v_mul_f32_e32 v83, 0xc038aa3b, v83
	v_exp_f32_e32 v83, v83
	v_mov_b32_e32 v90, v53
	v_mov_b32_e32 v91, v85
	v_cndmask_b32_e32 v85, v141, v142, vcc
	v_add_f32_e32 v83, 1.0, v83
	v_rcp_f32_e32 v83, v83
	v_cndmask_b32_e64 v85, 0, v85, s[10:11]
	v_fma_f32 v85, v85, v109, v105
	v_mul_f32_e32 v82, v82, v83
	v_mul_f32_e32 v86, v86, v82
	v_cndmask_b32_e64 v82, v148, v147, s[6:7]
	v_cndmask_b32_e64 v83, v82, 0, s[8:9]
	v_mov_b32_e32 v82, v81
	v_cndmask_b32_e32 v81, v145, v146, vcc
	v_cndmask_b32_e64 v81, 0, v81, s[10:11]
	v_pk_mul_f32 v[82:83], v[90:91], v[82:83]
	v_fma_f32 v81, v81, v97, v93
	v_add_f32_e32 v81, v83, v81
	v_add_f32_e32 v81, v82, v81
	v_cndmask_b32_e64 v82, v144, v143, s[6:7]
	v_cndmask_b32_e64 v83, v82, 0, s[8:9]
	v_mov_b32_e32 v90, v61
	v_mov_b32_e32 v91, v101
	v_mov_b32_e32 v82, v89
	v_pk_mul_f32 v[82:83], v[90:91], v[82:83]
	s_nop 0
	v_add_f32_e32 v83, v83, v85
	v_add_f32_e32 v82, v82, v83
	v_mul_f32_e32 v83, 0x3d372713, v82
	v_mul_f32_e32 v83, v82, v83
	v_fma_f32 v83, v82, v83, v82
	v_mul_f32_e32 v83, 0x3f4c422a, v83
	v_mul_f32_e32 v83, 0xc038aa3b, v83
	v_exp_f32_e32 v83, v83
	s_nop 0
	v_add_f32_e32 v83, 1.0, v83
	v_rcp_f32_e32 v83, v83
	s_nop 0
	v_mul_f32_e32 v82, v82, v83
	v_mul_f32_e32 v85, v81, v82
	v_cndmask_b32_e64 v81, v140, v139, s[6:7]
	v_cndmask_b32_e64 v81, v81, 0, s[8:9]
	v_mov_b32_e32 v82, v52
	v_mov_b32_e32 v83, v84
	v_pk_mul_f32 v[80:81], v[82:83], v[80:81]
	v_cndmask_b32_e32 v82, v137, v138, vcc
	v_cndmask_b32_e64 v82, 0, v82, s[10:11]
	v_fmac_f32_e32 v92, v82, v96
	v_add_f32_e32 v81, v81, v92
	v_add_f32_e32 v82, v80, v81
	v_cndmask_b32_e64 v80, v132, v131, s[6:7]
	v_cndmask_b32_e32 v83, v128, v129, vcc
	v_cndmask_b32_e64 v89, v80, 0, s[8:9]
	v_mov_b32_e32 v80, v60
	v_mov_b32_e32 v81, v100
	v_cndmask_b32_e64 v83, 0, v83, s[10:11]
	v_pk_mul_f32 v[80:81], v[80:81], v[88:89]
	v_fmac_f32_e32 v104, v83, v108
	v_add_f32_e32 v81, v81, v104
	v_add_f32_e32 v80, v80, v81
	v_mul_f32_e32 v81, 0x3d372713, v80
	v_mul_f32_e32 v81, v80, v81
	v_fma_f32 v81, v80, v81, v80
	v_mul_f32_e32 v81, 0x3f4c422a, v81
	v_mul_f32_e32 v81, 0xc038aa3b, v81
	v_exp_f32_e32 v81, v81
	v_mov_b32_e32 v83, v79
	v_add_f32_e32 v81, 1.0, v81
	v_rcp_f32_e32 v81, v81
	s_nop 0
	v_mul_f32_e32 v80, v80, v81
	v_mul_f32_e32 v84, v82, v80
	v_cndmask_b32_e64 v80, v136, v135, s[6:7]
	v_cndmask_b32_e64 v81, v80, 0, s[8:9]
	v_mov_b32_e32 v80, v71
	v_cndmask_b32_e32 v71, v133, v134, vcc
	v_cndmask_b32_e64 v71, 0, v71, s[10:11]
	v_fma_f32 v67, v71, v75, v67
	v_mul_f32_e32 v71, 0x3d372713, v130
	v_mul_f32_e32 v71, v130, v71
	v_fma_f32 v71, v130, v71, v130
	v_mul_f32_e32 v71, 0x3f4c422a, v71
	v_mul_f32_e32 v71, 0xc038aa3b, v71
	v_exp_f32_e32 v71, v71
	v_mov_b32_e32 v82, v51
	v_pk_mul_f32 v[80:81], v[82:83], v[80:81]
	v_add_f32_e32 v71, 1.0, v71
	v_rcp_f32_e32 v71, v71
	v_add_f32_e32 v67, v81, v67
	v_add_f32_e32 v67, v80, v67
	v_mov_b32_e32 v80, v50
	v_mul_f32_e32 v71, v130, v71
	v_mul_f32_e32 v75, v67, v71
	v_cndmask_b32_e64 v67, v127, v125, s[6:7]
	v_cndmask_b32_e64 v71, v67, 0, s[8:9]
	v_cndmask_b32_e32 v67, v123, v124, vcc
	v_cndmask_b32_e64 v67, 0, v67, s[10:11]
	v_fma_f32 v66, v67, v74, v66
	v_mul_f32_e32 v67, 0x3d372713, v126
	v_mul_f32_e32 v67, v126, v67
	v_fma_f32 v67, v126, v67, v126
	v_mul_f32_e32 v67, 0x3f4c422a, v67
	v_mul_f32_e32 v67, 0xc038aa3b, v67
	v_exp_f32_e32 v67, v67
	v_mov_b32_e32 v81, v78
	v_pk_mul_f32 v[70:71], v[80:81], v[70:71]
	v_add_f32_e32 v67, 1.0, v67
	v_rcp_f32_e32 v67, v67
	v_add_f32_e32 v66, v71, v66
	v_add_f32_e32 v66, v70, v66
	v_mov_b32_e32 v70, v49
	v_mul_f32_e32 v67, v126, v67
	v_mul_f32_e32 v74, v66, v67
	v_cndmask_b32_e64 v66, v121, v120, s[6:7]
	v_cndmask_b32_e64 v67, v66, 0, s[8:9]
	v_mov_b32_e32 v66, v69
	v_cndmask_b32_e32 v69, v118, v119, vcc
	v_mov_b32_e32 v71, v77
	v_cndmask_b32_e64 v69, 0, v69, s[10:11]
	v_pk_mul_f32 v[66:67], v[70:71], v[66:67]
	v_fma_f32 v65, v69, v73, v65
	v_add_f32_e32 v65, v67, v65
	v_add_f32_e32 v65, v66, v65
	v_mul_f32_e32 v66, 0x3d372713, v122
	v_mul_f32_e32 v66, v122, v66
	v_fma_f32 v66, v122, v66, v122
	v_mul_f32_e32 v66, 0x3f4c422a, v66
	v_mul_f32_e32 v66, 0xc038aa3b, v66
	v_exp_f32_e32 v66, v66
	v_mov_b32_e32 v67, v76
	v_add_f32_e32 v66, 1.0, v66
	v_rcp_f32_e32 v66, v66
	s_nop 0
	v_mul_f32_e32 v66, v122, v66
	v_mul_f32_e32 v70, v65, v66
	v_cndmask_b32_e64 v65, v116, v115, s[6:7]
	v_cndmask_b32_e64 v69, v65, 0, s[8:9]
	v_cndmask_b32_e32 v65, v113, v114, vcc
	v_cndmask_b32_e64 v65, 0, v65, s[10:11]
	v_fmac_f32_e32 v64, v65, v72
	v_mul_f32_e32 v65, 0x3d372713, v117
	v_mul_f32_e32 v65, v117, v65
	v_fma_f32 v65, v117, v65, v117
	v_mul_f32_e32 v65, 0x3f4c422a, v65
	v_mul_f32_e32 v65, 0xc038aa3b, v65
	v_exp_f32_e32 v65, v65
	v_mov_b32_e32 v66, v48
	v_pk_mul_f32 v[66:67], v[66:67], v[68:69]
	v_mov_b64_e32 v[68:69], s[16:17]
	v_add_f32_e32 v65, 1.0, v65
	v_rcp_f32_e32 v65, v65
	v_add_f32_e32 v64, v67, v64
	v_add_f32_e32 v64, v66, v64
	v_mad_i64_i32 v[68:69], s[8:9], v112, s79, v[68:69]
	v_mul_f32_e32 v65, v117, v65
	v_mul_f32_e32 v66, v64, v65
	v_lshl_add_u64 v[68:69], v[188:189], 1, v[68:69]
	v_cvt_pk_bf16_f32 v64, v84, v85
	v_cvt_pk_bf16_f32 v65, v86, v87
	v_cvt_pk_bf16_f32 v66, v66, v70
	v_cvt_pk_bf16_f32 v67, v74, v75
	global_store_dwordx4 v[68:69], v[64:67], off sc1
.LBB0_1003:
	s_or_b64 exec, exec, s[30:31]
	v_add_u32_e32 v96, 0x50, v218
	v_mov_b32_dpp v115, v60 row_mirror row_mask:0xf bank_mask:0xf bound_ctrl:1
	v_mov_b32_dpp v127, v61 row_mirror row_mask:0xf bank_mask:0xf bound_ctrl:1
	v_mov_b32_dpp v135, v62 row_mirror row_mask:0xf bank_mask:0xf bound_ctrl:1
	v_mov_b32_dpp v88, v63 row_mirror row_mask:0xf bank_mask:0xf bound_ctrl:1
	v_mov_b32_dpp v123, v52 row_mirror row_mask:0xf bank_mask:0xf bound_ctrl:1
	v_mov_b32_dpp v131, v53 row_mirror row_mask:0xf bank_mask:0xf bound_ctrl:1
	v_mov_b32_dpp v139, v54 row_mirror row_mask:0xf bank_mask:0xf bound_ctrl:1
	v_mov_b32_dpp v74, v55 row_mirror row_mask:0xf bank_mask:0xf bound_ctrl:1
	v_mov_b32_dpp v66, v56 row_mirror row_mask:0xf bank_mask:0xf bound_ctrl:1
	v_mov_b32_dpp v70, v57 row_mirror row_mask:0xf bank_mask:0xf bound_ctrl:1
	v_mov_b32_dpp v78, v58 row_mirror row_mask:0xf bank_mask:0xf bound_ctrl:1
	v_mov_b32_dpp v82, v59 row_mirror row_mask:0xf bank_mask:0xf bound_ctrl:1
	v_mov_b32_dpp v99, v48 row_mirror row_mask:0xf bank_mask:0xf bound_ctrl:1
	v_mov_b32_dpp v104, v49 row_mirror row_mask:0xf bank_mask:0xf bound_ctrl:1
	v_mov_b32_dpp v109, v50 row_mirror row_mask:0xf bank_mask:0xf bound_ctrl:1
	v_mov_b32_dpp v119, v51 row_mirror row_mask:0xf bank_mask:0xf bound_ctrl:1
	v_mov_b32_dpp v112, v115 quad_perm:[1,0,3,2] row_mask:0xf bank_mask:0xf bound_ctrl:1
	v_mov_b32_dpp v116, v44 row_shr:1 row_mask:0xf bank_mask:0xf bound_ctrl:1
	v_mov_b32_dpp v113, v44 row_shr:2 row_mask:0xf bank_mask:0xf bound_ctrl:1
	v_mov_b32_dpp v125, v127 quad_perm:[1,0,3,2] row_mask:0xf bank_mask:0xf bound_ctrl:1
	v_mov_b32_dpp v128, v45 row_shr:1 row_mask:0xf bank_mask:0xf bound_ctrl:1
	v_mov_b32_dpp v126, v45 row_shr:2 row_mask:0xf bank_mask:0xf bound_ctrl:1
	v_mov_b32_dpp v133, v135 quad_perm:[1,0,3,2] row_mask:0xf bank_mask:0xf bound_ctrl:1
	v_mov_b32_dpp v136, v46 row_shr:1 row_mask:0xf bank_mask:0xf bound_ctrl:1
	v_mov_b32_dpp v134, v46 row_shr:2 row_mask:0xf bank_mask:0xf bound_ctrl:1
	v_mov_b32_dpp v141, v88 quad_perm:[1,0,3,2] row_mask:0xf bank_mask:0xf bound_ctrl:1
	v_mov_b32_dpp v89, v47 row_shr:1 row_mask:0xf bank_mask:0xf bound_ctrl:1
	v_mov_b32_dpp v142, v47 row_shr:2 row_mask:0xf bank_mask:0xf bound_ctrl:1
	v_mov_b32_dpp v121, v123 quad_perm:[1,0,3,2] row_mask:0xf bank_mask:0xf bound_ctrl:1
	v_mov_b32_dpp v124, v36 row_shr:1 row_mask:0xf bank_mask:0xf bound_ctrl:1
	v_mov_b32_dpp v122, v36 row_shr:2 row_mask:0xf bank_mask:0xf bound_ctrl:1
	v_mov_b32_dpp v129, v131 quad_perm:[1,0,3,2] row_mask:0xf bank_mask:0xf bound_ctrl:1
	v_mov_b32_dpp v132, v37 row_shr:1 row_mask:0xf bank_mask:0xf bound_ctrl:1
	v_mov_b32_dpp v130, v37 row_shr:2 row_mask:0xf bank_mask:0xf bound_ctrl:1
	v_mov_b32_dpp v137, v139 quad_perm:[1,0,3,2] row_mask:0xf bank_mask:0xf bound_ctrl:1
	v_mov_b32_dpp v140, v38 row_shr:1 row_mask:0xf bank_mask:0xf bound_ctrl:1
	v_mov_b32_dpp v138, v38 row_shr:2 row_mask:0xf bank_mask:0xf bound_ctrl:1
	v_mov_b32_dpp v72, v74 quad_perm:[1,0,3,2] row_mask:0xf bank_mask:0xf bound_ctrl:1
	v_mov_b32_dpp v75, v39 row_shr:1 row_mask:0xf bank_mask:0xf bound_ctrl:1
	v_mov_b32_dpp v73, v39 row_shr:2 row_mask:0xf bank_mask:0xf bound_ctrl:1
	v_mov_b32_dpp v64, v66 quad_perm:[1,0,3,2] row_mask:0xf bank_mask:0xf bound_ctrl:1
	v_mov_b32_dpp v67, v40 row_shr:1 row_mask:0xf bank_mask:0xf bound_ctrl:1
	v_mov_b32_dpp v65, v40 row_shr:2 row_mask:0xf bank_mask:0xf bound_ctrl:1
	v_mov_b32_dpp v68, v70 quad_perm:[1,0,3,2] row_mask:0xf bank_mask:0xf bound_ctrl:1
	v_mov_b32_dpp v71, v41 row_shr:1 row_mask:0xf bank_mask:0xf bound_ctrl:1
	v_mov_b32_dpp v69, v41 row_shr:2 row_mask:0xf bank_mask:0xf bound_ctrl:1
	v_mov_b32_dpp v76, v78 quad_perm:[1,0,3,2] row_mask:0xf bank_mask:0xf bound_ctrl:1
	v_mov_b32_dpp v79, v42 row_shr:1 row_mask:0xf bank_mask:0xf bound_ctrl:1
	v_mov_b32_dpp v77, v42 row_shr:2 row_mask:0xf bank_mask:0xf bound_ctrl:1
	v_mov_b32_dpp v80, v82 quad_perm:[1,0,3,2] row_mask:0xf bank_mask:0xf bound_ctrl:1
	v_mov_b32_dpp v83, v43 row_shr:1 row_mask:0xf bank_mask:0xf bound_ctrl:1
	v_mov_b32_dpp v81, v43 row_shr:2 row_mask:0xf bank_mask:0xf bound_ctrl:1
	v_mov_b32_dpp v97, v99 quad_perm:[1,0,3,2] row_mask:0xf bank_mask:0xf bound_ctrl:1
	v_mov_b32_dpp v100, v32 row_shr:1 row_mask:0xf bank_mask:0xf bound_ctrl:1
	v_mov_b32_dpp v98, v32 row_shr:2 row_mask:0xf bank_mask:0xf bound_ctrl:1
	v_mov_b32_dpp v102, v104 quad_perm:[1,0,3,2] row_mask:0xf bank_mask:0xf bound_ctrl:1
	v_mov_b32_dpp v105, v33 row_shr:1 row_mask:0xf bank_mask:0xf bound_ctrl:1
	v_mov_b32_dpp v103, v33 row_shr:2 row_mask:0xf bank_mask:0xf bound_ctrl:1
	v_mov_b32_dpp v107, v109 quad_perm:[1,0,3,2] row_mask:0xf bank_mask:0xf bound_ctrl:1
	v_mov_b32_dpp v111, v34 row_shr:1 row_mask:0xf bank_mask:0xf bound_ctrl:1
	v_mov_b32_dpp v108, v34 row_shr:2 row_mask:0xf bank_mask:0xf bound_ctrl:1
	v_mov_b32_dpp v117, v119 quad_perm:[1,0,3,2] row_mask:0xf bank_mask:0xf bound_ctrl:1
	v_mov_b32_dpp v120, v35 row_shr:1 row_mask:0xf bank_mask:0xf bound_ctrl:1
	v_mov_b32_dpp v118, v35 row_shr:2 row_mask:0xf bank_mask:0xf bound_ctrl:1
	v_cmp_gt_i32_e64 s[8:9], s58, v96
	s_and_saveexec_b64 s[30:31], s[8:9]
	s_cbranch_execz .LBB0_1005
	s_add_i32 s0, 0, 0x20000
	v_add_u32_e32 v94, 0x810, v96
	v_add_u32_e32 v56, s0, v212
	v_mul_hi_u32 v95, v94, s59
	ds_read_b128 v[48:51], v217
	ds_read_b128 v[52:55], v216
	ds_read_b128 v[60:63], v215
	ds_read_b128 v[56:59], v56
	ds_read_b128 v[84:87], v214
	ds_read_b128 v[90:93], v213
	v_lshrrev_b32_e32 v95, 7, v95
	v_mul_u32_u24_e32 v95, 0x810, v95
	v_sub_u32_e32 v101, v94, v95
	v_cmp_eq_u32_e64 s[8:9], 0, v101
	v_cndmask_b32_e64 v82, v83, v82, s[6:7]
	ds_read_b128 v[144:147], v211
	v_cndmask_b32_e64 v83, v82, 0, s[8:9]
	s_waitcnt lgkmcnt(2)
	v_mov_b32_e32 v82, v87
	v_add_u32_e32 v87, s0, v210
	ds_read_b128 v[148:151], v87
	v_cmp_lt_u32_e64 s[10:11], 1, v101
	v_cndmask_b32_e64 v78, v79, v78, s[6:7]
	v_cndmask_b32_e32 v76, v76, v77, vcc
	v_cndmask_b32_e64 v87, v78, 0, s[8:9]
	v_mov_b32_e32 v78, v42
	s_waitcnt lgkmcnt(2)
	v_mov_b32_e32 v79, v92
	v_cndmask_b32_e64 v76, 0, v76, s[10:11]
	v_pk_mul_f32 v[78:79], v[78:79], v[86:87]
	s_waitcnt lgkmcnt(0)
	v_fma_f32 v76, v76, v150, v146
	v_add_f32_e32 v76, v79, v76
	v_cndmask_b32_e64 v70, v71, v70, s[6:7]
	v_cndmask_b32_e32 v68, v68, v69, vcc
	v_cndmask_b32_e64 v66, v67, v66, s[6:7]
	v_cndmask_b32_e32 v64, v64, v65, vcc
	v_add_f32_e32 v110, v78, v76
	v_cndmask_b32_e64 v71, v70, 0, s[8:9]
	v_mov_b32_e32 v76, v41
	v_mov_b32_e32 v77, v91
	v_mov_b32_e32 v70, v85
	v_cndmask_b32_e64 v68, 0, v68, s[10:11]
	v_cndmask_b32_e64 v85, v66, 0, s[8:9]
	v_mov_b32_e32 v66, v40
	v_mov_b32_e32 v67, v90
	v_cndmask_b32_e64 v64, 0, v64, s[10:11]
	v_pk_mul_f32 v[70:71], v[76:77], v[70:71]
	v_fma_f32 v68, v68, v149, v145
	v_pk_mul_f32 v[66:67], v[66:67], v[84:85]
	v_fmac_f32_e32 v144, v64, v148
	v_add_f32_e32 v68, v71, v68
	v_add_f32_e32 v64, v67, v144
	v_add_f32_e32 v106, v70, v68
	v_add_f32_e32 v101, v66, v64
	ds_read_b128 v[64:67], v209
	ds_read_b128 v[68:71], v208
	v_cndmask_b32_e32 v80, v80, v81, vcc
	v_mov_b32_e32 v94, v43
	v_mov_b32_e32 v95, v93
	v_cndmask_b32_e64 v80, 0, v80, s[10:11]
	v_pk_mul_f32 v[82:83], v[94:95], v[82:83]
	v_fma_f32 v80, v80, v151, v147
	v_cndmask_b32_e64 v74, v75, v74, s[6:7]
	v_add_f32_e32 v80, v83, v80
	v_cndmask_b32_e64 v75, v74, 0, s[8:9]
	v_mov_b32_e32 v76, v39
	s_waitcnt lgkmcnt(0)
	v_mov_b32_e32 v77, v71
	v_mov_b32_e32 v74, v67
	v_add_u32_e32 v67, s0, v206
	v_add_f32_e32 v114, v82, v80
	v_pk_mul_f32 v[74:75], v[76:77], v[74:75]
	ds_read_b128 v[76:79], v207
	ds_read_b128 v[80:83], v67
	v_cndmask_b32_e32 v67, v72, v73, vcc
	v_cndmask_b32_e64 v67, 0, v67, s[10:11]
	v_cndmask_b32_e64 v71, v89, v88, s[6:7]
	v_cndmask_b32_e64 v89, v71, 0, s[8:9]
	s_waitcnt lgkmcnt(0)
	v_fma_f32 v67, v67, v83, v79
	v_add_f32_e32 v67, v75, v67
	v_add_f32_e32 v67, v74, v67
	ds_read_b128 v[72:75], v205
	ds_read_b128 v[84:87], v204
	v_mov_b32_e32 v90, v47
	v_add_u32_e32 v71, s0, v172
	ds_read_b128 v[92:95], v71
	s_waitcnt lgkmcnt(2)
	v_mov_b32_e32 v88, v75
	s_waitcnt lgkmcnt(1)
	v_mov_b32_e32 v91, v87
	v_pk_mul_f32 v[144:145], v[90:91], v[88:89]
	ds_read_b128 v[88:91], v203
	v_cndmask_b32_e32 v71, v141, v142, vcc
	v_cndmask_b32_e64 v71, 0, v71, s[10:11]
	v_mov_b32_e32 v141, v70
	v_cndmask_b32_e32 v70, v137, v138, vcc
	s_waitcnt lgkmcnt(0)
	v_fma_f32 v71, v71, v95, v91
	v_add_f32_e32 v71, v145, v71
	v_add_f32_e32 v71, v144, v71
	v_mul_f32_e32 v75, 0x3d372713, v71
	v_mul_f32_e32 v75, v71, v75
	v_fma_f32 v75, v71, v75, v71
	v_mul_f32_e32 v75, 0x3f4c422a, v75
	v_mul_f32_e32 v75, 0xc038aa3b, v75
	v_exp_f32_e32 v75, v75
	v_cndmask_b32_e64 v70, 0, v70, s[10:11]
	v_fma_f32 v70, v70, v82, v78
	v_add_f32_e32 v75, 1.0, v75
	v_rcp_f32_e32 v75, v75
	s_nop 0
	v_mul_f32_e32 v71, v71, v75
	v_mul_f32_e32 v71, v67, v71
	v_cndmask_b32_e64 v67, v140, v139, s[6:7]
	v_cndmask_b32_e64 v67, v67, 0, s[8:9]
	v_mov_b32_e32 v140, v38
	v_pk_mul_f32 v[66:67], v[140:141], v[66:67]
	s_nop 0
	v_add_f32_e32 v67, v67, v70
	v_add_f32_e32 v70, v66, v67
	v_cndmask_b32_e64 v66, v136, v135, s[6:7]
	v_cndmask_b32_e64 v75, v66, 0, s[8:9]
	v_mov_b32_e32 v66, v46
	v_mov_b32_e32 v67, v86
	v_pk_mul_f32 v[66:67], v[66:67], v[74:75]
	v_cndmask_b32_e32 v74, v133, v134, vcc
	v_cndmask_b32_e64 v74, 0, v74, s[10:11]
	v_fma_f32 v74, v74, v94, v90
	v_add_f32_e32 v67, v67, v74
	v_add_f32_e32 v66, v66, v67
	v_mul_f32_e32 v67, 0x3d372713, v66
	v_mul_f32_e32 v67, v66, v67
	v_fma_f32 v67, v66, v67, v66
	v_mul_f32_e32 v67, 0x3f4c422a, v67
	v_mul_f32_e32 v67, 0xc038aa3b, v67
	v_exp_f32_e32 v67, v67
	v_mov_b32_e32 v74, v37
	v_mov_b32_e32 v75, v69
	v_cndmask_b32_e32 v69, v125, v126, vcc
	v_add_f32_e32 v67, 1.0, v67
	v_rcp_f32_e32 v67, v67
	v_cndmask_b32_e64 v69, 0, v69, s[10:11]
	v_fma_f32 v69, v69, v93, v89
	v_mul_f32_e32 v66, v66, v67
	v_mul_f32_e32 v70, v70, v66
	v_cndmask_b32_e64 v66, v132, v131, s[6:7]
	v_cndmask_b32_e64 v67, v66, 0, s[8:9]
	v_mov_b32_e32 v66, v65
	v_cndmask_b32_e32 v65, v129, v130, vcc
	v_cndmask_b32_e64 v65, 0, v65, s[10:11]
	v_pk_mul_f32 v[66:67], v[74:75], v[66:67]
	v_fma_f32 v65, v65, v81, v77
	v_add_f32_e32 v65, v67, v65
	v_add_f32_e32 v65, v66, v65
	v_cndmask_b32_e64 v66, v128, v127, s[6:7]
	v_cndmask_b32_e64 v67, v66, 0, s[8:9]
	v_mov_b32_e32 v74, v45
	v_mov_b32_e32 v75, v85
	v_mov_b32_e32 v66, v73
	v_pk_mul_f32 v[66:67], v[74:75], v[66:67]
	s_nop 0
	v_add_f32_e32 v67, v67, v69
	v_add_f32_e32 v66, v66, v67
	v_mul_f32_e32 v67, 0x3d372713, v66
	v_mul_f32_e32 v67, v66, v67
	v_fma_f32 v67, v66, v67, v66
	v_mul_f32_e32 v67, 0x3f4c422a, v67
	v_mul_f32_e32 v67, 0xc038aa3b, v67
	v_exp_f32_e32 v67, v67
	s_nop 0
	v_add_f32_e32 v67, 1.0, v67
	v_rcp_f32_e32 v67, v67
	s_nop 0
	v_mul_f32_e32 v66, v66, v67
	v_mul_f32_e32 v69, v65, v66
	v_cndmask_b32_e64 v65, v124, v123, s[6:7]
	v_cndmask_b32_e64 v65, v65, 0, s[8:9]
	v_mov_b32_e32 v66, v36
	v_mov_b32_e32 v67, v68
	v_pk_mul_f32 v[64:65], v[66:67], v[64:65]
	v_cndmask_b32_e32 v66, v121, v122, vcc
	v_cndmask_b32_e64 v66, 0, v66, s[10:11]
	v_fmac_f32_e32 v76, v66, v80
	v_add_f32_e32 v65, v65, v76
	v_add_f32_e32 v66, v64, v65
	v_cndmask_b32_e64 v64, v116, v115, s[6:7]
	v_cndmask_b32_e32 v67, v112, v113, vcc
	v_cndmask_b32_e64 v73, v64, 0, s[8:9]
	v_mov_b32_e32 v64, v44
	v_mov_b32_e32 v65, v84
	v_cndmask_b32_e64 v67, 0, v67, s[10:11]
	v_pk_mul_f32 v[64:65], v[64:65], v[72:73]
	v_fmac_f32_e32 v88, v67, v92
	v_add_f32_e32 v65, v65, v88
	v_add_f32_e32 v64, v64, v65
	v_mul_f32_e32 v65, 0x3d372713, v64
	v_mul_f32_e32 v65, v64, v65
	v_fma_f32 v65, v64, v65, v64
	v_mul_f32_e32 v65, 0x3f4c422a, v65
	v_mul_f32_e32 v65, 0xc038aa3b, v65
	v_exp_f32_e32 v65, v65
	v_mov_b32_e32 v67, v63
	v_add_f32_e32 v65, 1.0, v65
	v_rcp_f32_e32 v65, v65
	s_nop 0
	v_mul_f32_e32 v64, v64, v65
	v_mul_f32_e32 v68, v66, v64
	v_cndmask_b32_e64 v64, v120, v119, s[6:7]
	v_cndmask_b32_e64 v65, v64, 0, s[8:9]
	v_mov_b32_e32 v64, v55
	v_cndmask_b32_e32 v55, v117, v118, vcc
	v_cndmask_b32_e64 v55, 0, v55, s[10:11]
	v_fma_f32 v51, v55, v59, v51
	v_mul_f32_e32 v55, 0x3d372713, v114
	v_mul_f32_e32 v55, v114, v55
	v_fma_f32 v55, v114, v55, v114
	v_mul_f32_e32 v55, 0x3f4c422a, v55
	v_mul_f32_e32 v55, 0xc038aa3b, v55
	v_exp_f32_e32 v55, v55
	v_mov_b32_e32 v66, v35
	v_pk_mul_f32 v[64:65], v[66:67], v[64:65]
	v_add_f32_e32 v55, 1.0, v55
	v_rcp_f32_e32 v55, v55
	v_add_f32_e32 v51, v65, v51
	v_add_f32_e32 v51, v64, v51
	v_mov_b32_e32 v64, v34
	v_mul_f32_e32 v55, v114, v55
	v_mul_f32_e32 v59, v51, v55
	v_cndmask_b32_e64 v51, v111, v109, s[6:7]
	v_cndmask_b32_e64 v55, v51, 0, s[8:9]
	v_cndmask_b32_e32 v51, v107, v108, vcc
	v_cndmask_b32_e64 v51, 0, v51, s[10:11]
	v_fma_f32 v50, v51, v58, v50
	v_mul_f32_e32 v51, 0x3d372713, v110
	v_mul_f32_e32 v51, v110, v51
	v_fma_f32 v51, v110, v51, v110
	v_mul_f32_e32 v51, 0x3f4c422a, v51
	v_mul_f32_e32 v51, 0xc038aa3b, v51
	v_exp_f32_e32 v51, v51
	v_mov_b32_e32 v65, v62
	v_pk_mul_f32 v[54:55], v[64:65], v[54:55]
	v_add_f32_e32 v51, 1.0, v51
	v_rcp_f32_e32 v51, v51
	v_add_f32_e32 v50, v55, v50
	v_add_f32_e32 v50, v54, v50
	v_mov_b32_e32 v54, v33
	v_mul_f32_e32 v51, v110, v51
	v_mul_f32_e32 v58, v50, v51
	v_cndmask_b32_e64 v50, v105, v104, s[6:7]
	v_cndmask_b32_e64 v51, v50, 0, s[8:9]
	v_mov_b32_e32 v50, v53
	v_cndmask_b32_e32 v53, v102, v103, vcc
	v_mov_b32_e32 v55, v61
	v_cndmask_b32_e64 v53, 0, v53, s[10:11]
	v_pk_mul_f32 v[50:51], v[54:55], v[50:51]
	v_fma_f32 v49, v53, v57, v49
	v_add_f32_e32 v49, v51, v49
	v_add_f32_e32 v49, v50, v49
	v_mul_f32_e32 v50, 0x3d372713, v106
	v_mul_f32_e32 v50, v106, v50
	v_fma_f32 v50, v106, v50, v106
	v_mul_f32_e32 v50, 0x3f4c422a, v50
	v_mul_f32_e32 v50, 0xc038aa3b, v50
	v_exp_f32_e32 v50, v50
	v_mov_b32_e32 v51, v60
	v_add_f32_e32 v50, 1.0, v50
	v_rcp_f32_e32 v50, v50
	s_nop 0
	v_mul_f32_e32 v50, v106, v50
	v_mul_f32_e32 v54, v49, v50
	v_cndmask_b32_e64 v49, v100, v99, s[6:7]
	v_cndmask_b32_e64 v53, v49, 0, s[8:9]
	v_cndmask_b32_e32 v49, v97, v98, vcc
	v_cndmask_b32_e64 v49, 0, v49, s[10:11]
	v_fmac_f32_e32 v48, v49, v56
	v_mul_f32_e32 v49, 0x3d372713, v101
	v_mul_f32_e32 v49, v101, v49
	v_fma_f32 v49, v101, v49, v101
	v_mul_f32_e32 v49, 0x3f4c422a, v49
	v_mul_f32_e32 v49, 0xc038aa3b, v49
	v_exp_f32_e32 v49, v49
	v_mov_b32_e32 v50, v32
	v_pk_mul_f32 v[50:51], v[50:51], v[52:53]
	v_mov_b64_e32 v[52:53], s[16:17]
	v_add_f32_e32 v49, 1.0, v49
	v_rcp_f32_e32 v49, v49
	v_add_f32_e32 v48, v51, v48
	v_add_f32_e32 v48, v50, v48
	v_mad_i64_i32 v[52:53], s[8:9], v96, s79, v[52:53]
	v_mul_f32_e32 v49, v101, v49
	v_mul_f32_e32 v50, v48, v49
	v_lshl_add_u64 v[52:53], v[188:189], 1, v[52:53]
	v_cvt_pk_bf16_f32 v48, v68, v69
	v_cvt_pk_bf16_f32 v49, v70, v71
	v_cvt_pk_bf16_f32 v50, v50, v54
	v_cvt_pk_bf16_f32 v51, v58, v59
	global_store_dwordx4 v[52:53], v[48:51], off sc1
.LBB0_1005:
	s_or_b64 exec, exec, s[30:31]
	v_add_u32_e32 v80, 0x60, v218
	v_mov_b32_dpp v99, v44 row_mirror row_mask:0xf bank_mask:0xf bound_ctrl:1
	v_mov_b32_dpp v111, v45 row_mirror row_mask:0xf bank_mask:0xf bound_ctrl:1
	v_mov_b32_dpp v119, v46 row_mirror row_mask:0xf bank_mask:0xf bound_ctrl:1
	v_mov_b32_dpp v72, v47 row_mirror row_mask:0xf bank_mask:0xf bound_ctrl:1
	v_mov_b32_dpp v107, v36 row_mirror row_mask:0xf bank_mask:0xf bound_ctrl:1
	v_mov_b32_dpp v115, v37 row_mirror row_mask:0xf bank_mask:0xf bound_ctrl:1
	v_mov_b32_dpp v123, v38 row_mirror row_mask:0xf bank_mask:0xf bound_ctrl:1
	v_mov_b32_dpp v58, v39 row_mirror row_mask:0xf bank_mask:0xf bound_ctrl:1
	v_mov_b32_dpp v50, v40 row_mirror row_mask:0xf bank_mask:0xf bound_ctrl:1
	v_mov_b32_dpp v54, v41 row_mirror row_mask:0xf bank_mask:0xf bound_ctrl:1
	v_mov_b32_dpp v62, v42 row_mirror row_mask:0xf bank_mask:0xf bound_ctrl:1
	v_mov_b32_dpp v66, v43 row_mirror row_mask:0xf bank_mask:0xf bound_ctrl:1
	v_mov_b32_dpp v83, v32 row_mirror row_mask:0xf bank_mask:0xf bound_ctrl:1
	v_mov_b32_dpp v88, v33 row_mirror row_mask:0xf bank_mask:0xf bound_ctrl:1
	v_mov_b32_dpp v93, v34 row_mirror row_mask:0xf bank_mask:0xf bound_ctrl:1
	v_mov_b32_dpp v103, v35 row_mirror row_mask:0xf bank_mask:0xf bound_ctrl:1
	v_mov_b32_dpp v96, v99 quad_perm:[1,0,3,2] row_mask:0xf bank_mask:0xf bound_ctrl:1
	v_mov_b32_dpp v100, v28 row_shr:1 row_mask:0xf bank_mask:0xf bound_ctrl:1
	v_mov_b32_dpp v97, v28 row_shr:2 row_mask:0xf bank_mask:0xf bound_ctrl:1
	v_mov_b32_dpp v109, v111 quad_perm:[1,0,3,2] row_mask:0xf bank_mask:0xf bound_ctrl:1
	v_mov_b32_dpp v112, v29 row_shr:1 row_mask:0xf bank_mask:0xf bound_ctrl:1
	v_mov_b32_dpp v110, v29 row_shr:2 row_mask:0xf bank_mask:0xf bound_ctrl:1
	v_mov_b32_dpp v117, v119 quad_perm:[1,0,3,2] row_mask:0xf bank_mask:0xf bound_ctrl:1
	v_mov_b32_dpp v120, v30 row_shr:1 row_mask:0xf bank_mask:0xf bound_ctrl:1
	v_mov_b32_dpp v118, v30 row_shr:2 row_mask:0xf bank_mask:0xf bound_ctrl:1
	v_mov_b32_dpp v125, v72 quad_perm:[1,0,3,2] row_mask:0xf bank_mask:0xf bound_ctrl:1
	v_mov_b32_dpp v73, v31 row_shr:1 row_mask:0xf bank_mask:0xf bound_ctrl:1
	v_mov_b32_dpp v126, v31 row_shr:2 row_mask:0xf bank_mask:0xf bound_ctrl:1
	v_mov_b32_dpp v105, v107 quad_perm:[1,0,3,2] row_mask:0xf bank_mask:0xf bound_ctrl:1
	v_mov_b32_dpp v108, v20 row_shr:1 row_mask:0xf bank_mask:0xf bound_ctrl:1
	v_mov_b32_dpp v106, v20 row_shr:2 row_mask:0xf bank_mask:0xf bound_ctrl:1
	v_mov_b32_dpp v113, v115 quad_perm:[1,0,3,2] row_mask:0xf bank_mask:0xf bound_ctrl:1
	v_mov_b32_dpp v116, v21 row_shr:1 row_mask:0xf bank_mask:0xf bound_ctrl:1
	v_mov_b32_dpp v114, v21 row_shr:2 row_mask:0xf bank_mask:0xf bound_ctrl:1
	v_mov_b32_dpp v121, v123 quad_perm:[1,0,3,2] row_mask:0xf bank_mask:0xf bound_ctrl:1
	v_mov_b32_dpp v124, v22 row_shr:1 row_mask:0xf bank_mask:0xf bound_ctrl:1
	v_mov_b32_dpp v122, v22 row_shr:2 row_mask:0xf bank_mask:0xf bound_ctrl:1
	v_mov_b32_dpp v56, v58 quad_perm:[1,0,3,2] row_mask:0xf bank_mask:0xf bound_ctrl:1
	v_mov_b32_dpp v59, v23 row_shr:1 row_mask:0xf bank_mask:0xf bound_ctrl:1
	v_mov_b32_dpp v57, v23 row_shr:2 row_mask:0xf bank_mask:0xf bound_ctrl:1
	v_mov_b32_dpp v48, v50 quad_perm:[1,0,3,2] row_mask:0xf bank_mask:0xf bound_ctrl:1
	v_mov_b32_dpp v51, v24 row_shr:1 row_mask:0xf bank_mask:0xf bound_ctrl:1
	v_mov_b32_dpp v49, v24 row_shr:2 row_mask:0xf bank_mask:0xf bound_ctrl:1
	v_mov_b32_dpp v52, v54 quad_perm:[1,0,3,2] row_mask:0xf bank_mask:0xf bound_ctrl:1
	v_mov_b32_dpp v55, v25 row_shr:1 row_mask:0xf bank_mask:0xf bound_ctrl:1
	v_mov_b32_dpp v53, v25 row_shr:2 row_mask:0xf bank_mask:0xf bound_ctrl:1
	v_mov_b32_dpp v60, v62 quad_perm:[1,0,3,2] row_mask:0xf bank_mask:0xf bound_ctrl:1
	v_mov_b32_dpp v63, v26 row_shr:1 row_mask:0xf bank_mask:0xf bound_ctrl:1
	v_mov_b32_dpp v61, v26 row_shr:2 row_mask:0xf bank_mask:0xf bound_ctrl:1
	v_mov_b32_dpp v64, v66 quad_perm:[1,0,3,2] row_mask:0xf bank_mask:0xf bound_ctrl:1
	v_mov_b32_dpp v67, v27 row_shr:1 row_mask:0xf bank_mask:0xf bound_ctrl:1
	v_mov_b32_dpp v65, v27 row_shr:2 row_mask:0xf bank_mask:0xf bound_ctrl:1
	v_mov_b32_dpp v81, v83 quad_perm:[1,0,3,2] row_mask:0xf bank_mask:0xf bound_ctrl:1
	v_mov_b32_dpp v84, v16 row_shr:1 row_mask:0xf bank_mask:0xf bound_ctrl:1
	v_mov_b32_dpp v82, v16 row_shr:2 row_mask:0xf bank_mask:0xf bound_ctrl:1
	v_mov_b32_dpp v86, v88 quad_perm:[1,0,3,2] row_mask:0xf bank_mask:0xf bound_ctrl:1
	v_mov_b32_dpp v89, v17 row_shr:1 row_mask:0xf bank_mask:0xf bound_ctrl:1
	v_mov_b32_dpp v87, v17 row_shr:2 row_mask:0xf bank_mask:0xf bound_ctrl:1
	v_mov_b32_dpp v91, v93 quad_perm:[1,0,3,2] row_mask:0xf bank_mask:0xf bound_ctrl:1
	v_mov_b32_dpp v95, v18 row_shr:1 row_mask:0xf bank_mask:0xf bound_ctrl:1
	v_mov_b32_dpp v92, v18 row_shr:2 row_mask:0xf bank_mask:0xf bound_ctrl:1
	v_mov_b32_dpp v101, v103 quad_perm:[1,0,3,2] row_mask:0xf bank_mask:0xf bound_ctrl:1
	v_mov_b32_dpp v104, v19 row_shr:1 row_mask:0xf bank_mask:0xf bound_ctrl:1
	v_mov_b32_dpp v102, v19 row_shr:2 row_mask:0xf bank_mask:0xf bound_ctrl:1
	v_cmp_gt_i32_e64 s[8:9], s58, v80
	s_and_saveexec_b64 s[30:31], s[8:9]
	s_cbranch_execz .LBB0_1007
	s_add_i32 s0, 0, 0x20000
	v_add_u32_e32 v78, 0x810, v80
	v_add_u32_e32 v40, s0, v212
	v_mul_hi_u32 v79, v78, s59
	ds_read_b128 v[32:35], v217
	ds_read_b128 v[36:39], v216
	ds_read_b128 v[44:47], v215
	ds_read_b128 v[40:43], v40
	ds_read_b128 v[68:71], v214
	ds_read_b128 v[74:77], v213
	v_lshrrev_b32_e32 v79, 7, v79
	v_mul_u32_u24_e32 v79, 0x810, v79
	v_sub_u32_e32 v85, v78, v79
	v_cmp_eq_u32_e64 s[8:9], 0, v85
	v_cndmask_b32_e64 v66, v67, v66, s[6:7]
	ds_read_b128 v[128:131], v211
	v_cndmask_b32_e64 v67, v66, 0, s[8:9]
	s_waitcnt lgkmcnt(2)
	v_mov_b32_e32 v66, v71
	v_add_u32_e32 v71, s0, v210
	ds_read_b128 v[132:135], v71
	v_cmp_lt_u32_e64 s[10:11], 1, v85
	v_cndmask_b32_e64 v62, v63, v62, s[6:7]
	v_cndmask_b32_e32 v60, v60, v61, vcc
	v_cndmask_b32_e64 v71, v62, 0, s[8:9]
	v_mov_b32_e32 v62, v26
	s_waitcnt lgkmcnt(2)
	v_mov_b32_e32 v63, v76
	v_cndmask_b32_e64 v60, 0, v60, s[10:11]
	v_pk_mul_f32 v[62:63], v[62:63], v[70:71]
	s_waitcnt lgkmcnt(0)
	v_fma_f32 v60, v60, v134, v130
	v_add_f32_e32 v60, v63, v60
	v_cndmask_b32_e64 v54, v55, v54, s[6:7]
	v_cndmask_b32_e32 v52, v52, v53, vcc
	v_cndmask_b32_e64 v50, v51, v50, s[6:7]
	v_cndmask_b32_e32 v48, v48, v49, vcc
	v_add_f32_e32 v94, v62, v60
	v_cndmask_b32_e64 v55, v54, 0, s[8:9]
	v_mov_b32_e32 v60, v25
	v_mov_b32_e32 v61, v75
	v_mov_b32_e32 v54, v69
	v_cndmask_b32_e64 v52, 0, v52, s[10:11]
	v_cndmask_b32_e64 v69, v50, 0, s[8:9]
	v_mov_b32_e32 v50, v24
	v_mov_b32_e32 v51, v74
	v_cndmask_b32_e64 v48, 0, v48, s[10:11]
	v_pk_mul_f32 v[54:55], v[60:61], v[54:55]
	v_fma_f32 v52, v52, v133, v129
	v_pk_mul_f32 v[50:51], v[50:51], v[68:69]
	v_fmac_f32_e32 v128, v48, v132
	v_add_f32_e32 v52, v55, v52
	v_add_f32_e32 v48, v51, v128
	v_add_f32_e32 v90, v54, v52
	v_add_f32_e32 v85, v50, v48
	ds_read_b128 v[48:51], v209
	ds_read_b128 v[52:55], v208
	v_cndmask_b32_e32 v64, v64, v65, vcc
	v_mov_b32_e32 v78, v27
	v_mov_b32_e32 v79, v77
	v_cndmask_b32_e64 v64, 0, v64, s[10:11]
	v_pk_mul_f32 v[66:67], v[78:79], v[66:67]
	v_fma_f32 v64, v64, v135, v131
	v_cndmask_b32_e64 v58, v59, v58, s[6:7]
	v_add_f32_e32 v64, v67, v64
	v_cndmask_b32_e64 v59, v58, 0, s[8:9]
	v_mov_b32_e32 v60, v23
	s_waitcnt lgkmcnt(0)
	v_mov_b32_e32 v61, v55
	v_mov_b32_e32 v58, v51
	v_add_u32_e32 v51, s0, v206
	v_add_f32_e32 v98, v66, v64
	v_pk_mul_f32 v[58:59], v[60:61], v[58:59]
	ds_read_b128 v[60:63], v207
	ds_read_b128 v[64:67], v51
	v_cndmask_b32_e32 v51, v56, v57, vcc
	v_cndmask_b32_e64 v51, 0, v51, s[10:11]
	v_cndmask_b32_e64 v55, v73, v72, s[6:7]
	v_cndmask_b32_e64 v73, v55, 0, s[8:9]
	s_waitcnt lgkmcnt(0)
	v_fma_f32 v51, v51, v67, v63
	v_add_f32_e32 v51, v59, v51
	v_add_f32_e32 v51, v58, v51
	ds_read_b128 v[56:59], v205
	ds_read_b128 v[68:71], v204
	v_mov_b32_e32 v74, v31
	v_add_u32_e32 v55, s0, v172
	ds_read_b128 v[76:79], v55
	s_waitcnt lgkmcnt(2)
	v_mov_b32_e32 v72, v59
	s_waitcnt lgkmcnt(1)
	v_mov_b32_e32 v75, v71
	v_pk_mul_f32 v[128:129], v[74:75], v[72:73]
	ds_read_b128 v[72:75], v203
	v_cndmask_b32_e32 v55, v125, v126, vcc
	v_cndmask_b32_e64 v55, 0, v55, s[10:11]
	v_mov_b32_e32 v125, v54
	v_cndmask_b32_e32 v54, v121, v122, vcc
	s_waitcnt lgkmcnt(0)
	v_fma_f32 v55, v55, v79, v75
	v_add_f32_e32 v55, v129, v55
	v_add_f32_e32 v55, v128, v55
	v_mul_f32_e32 v59, 0x3d372713, v55
	v_mul_f32_e32 v59, v55, v59
	v_fma_f32 v59, v55, v59, v55
	v_mul_f32_e32 v59, 0x3f4c422a, v59
	v_mul_f32_e32 v59, 0xc038aa3b, v59
	v_exp_f32_e32 v59, v59
	v_cndmask_b32_e64 v54, 0, v54, s[10:11]
	v_fma_f32 v54, v54, v66, v62
	v_add_f32_e32 v59, 1.0, v59
	v_rcp_f32_e32 v59, v59
	s_nop 0
	v_mul_f32_e32 v55, v55, v59
	v_mul_f32_e32 v55, v51, v55
	v_cndmask_b32_e64 v51, v124, v123, s[6:7]
	v_cndmask_b32_e64 v51, v51, 0, s[8:9]
	v_mov_b32_e32 v124, v22
	v_pk_mul_f32 v[50:51], v[124:125], v[50:51]
	s_nop 0
	v_add_f32_e32 v51, v51, v54
	v_add_f32_e32 v54, v50, v51
	v_cndmask_b32_e64 v50, v120, v119, s[6:7]
	v_cndmask_b32_e64 v59, v50, 0, s[8:9]
	v_mov_b32_e32 v50, v30
	v_mov_b32_e32 v51, v70
	v_pk_mul_f32 v[50:51], v[50:51], v[58:59]
	v_cndmask_b32_e32 v58, v117, v118, vcc
	v_cndmask_b32_e64 v58, 0, v58, s[10:11]
	v_fma_f32 v58, v58, v78, v74
	v_add_f32_e32 v51, v51, v58
	v_add_f32_e32 v50, v50, v51
	v_mul_f32_e32 v51, 0x3d372713, v50
	v_mul_f32_e32 v51, v50, v51
	v_fma_f32 v51, v50, v51, v50
	v_mul_f32_e32 v51, 0x3f4c422a, v51
	v_mul_f32_e32 v51, 0xc038aa3b, v51
	v_exp_f32_e32 v51, v51
	v_mov_b32_e32 v58, v21
	v_mov_b32_e32 v59, v53
	v_cndmask_b32_e32 v53, v109, v110, vcc
	v_add_f32_e32 v51, 1.0, v51
	v_rcp_f32_e32 v51, v51
	v_cndmask_b32_e64 v53, 0, v53, s[10:11]
	v_fma_f32 v53, v53, v77, v73
	v_mul_f32_e32 v50, v50, v51
	v_mul_f32_e32 v54, v54, v50
	v_cndmask_b32_e64 v50, v116, v115, s[6:7]
	v_cndmask_b32_e64 v51, v50, 0, s[8:9]
	v_mov_b32_e32 v50, v49
	v_cndmask_b32_e32 v49, v113, v114, vcc
	v_cndmask_b32_e64 v49, 0, v49, s[10:11]
	v_pk_mul_f32 v[50:51], v[58:59], v[50:51]
	v_fma_f32 v49, v49, v65, v61
	v_add_f32_e32 v49, v51, v49
	v_add_f32_e32 v49, v50, v49
	v_cndmask_b32_e64 v50, v112, v111, s[6:7]
	v_cndmask_b32_e64 v51, v50, 0, s[8:9]
	v_mov_b32_e32 v58, v29
	v_mov_b32_e32 v59, v69
	v_mov_b32_e32 v50, v57
	v_pk_mul_f32 v[50:51], v[58:59], v[50:51]
	s_nop 0
	v_add_f32_e32 v51, v51, v53
	v_add_f32_e32 v50, v50, v51
	v_mul_f32_e32 v51, 0x3d372713, v50
	v_mul_f32_e32 v51, v50, v51
	v_fma_f32 v51, v50, v51, v50
	v_mul_f32_e32 v51, 0x3f4c422a, v51
	v_mul_f32_e32 v51, 0xc038aa3b, v51
	v_exp_f32_e32 v51, v51
	s_nop 0
	v_add_f32_e32 v51, 1.0, v51
	v_rcp_f32_e32 v51, v51
	s_nop 0
	v_mul_f32_e32 v50, v50, v51
	v_mul_f32_e32 v53, v49, v50
	v_cndmask_b32_e64 v49, v108, v107, s[6:7]
	v_cndmask_b32_e64 v49, v49, 0, s[8:9]
	v_mov_b32_e32 v50, v20
	v_mov_b32_e32 v51, v52
	v_pk_mul_f32 v[48:49], v[50:51], v[48:49]
	v_cndmask_b32_e32 v50, v105, v106, vcc
	v_cndmask_b32_e64 v50, 0, v50, s[10:11]
	v_fmac_f32_e32 v60, v50, v64
	v_add_f32_e32 v49, v49, v60
	v_add_f32_e32 v50, v48, v49
	v_cndmask_b32_e64 v48, v100, v99, s[6:7]
	v_cndmask_b32_e32 v51, v96, v97, vcc
	v_cndmask_b32_e64 v57, v48, 0, s[8:9]
	v_mov_b32_e32 v48, v28
	v_mov_b32_e32 v49, v68
	v_cndmask_b32_e64 v51, 0, v51, s[10:11]
	v_pk_mul_f32 v[48:49], v[48:49], v[56:57]
	v_fmac_f32_e32 v72, v51, v76
	v_add_f32_e32 v49, v49, v72
	v_add_f32_e32 v48, v48, v49
	v_mul_f32_e32 v49, 0x3d372713, v48
	v_mul_f32_e32 v49, v48, v49
	v_fma_f32 v49, v48, v49, v48
	v_mul_f32_e32 v49, 0x3f4c422a, v49
	v_mul_f32_e32 v49, 0xc038aa3b, v49
	v_exp_f32_e32 v49, v49
	v_mov_b32_e32 v51, v47
	v_add_f32_e32 v49, 1.0, v49
	v_rcp_f32_e32 v49, v49
	s_nop 0
	v_mul_f32_e32 v48, v48, v49
	v_mul_f32_e32 v52, v50, v48
	v_cndmask_b32_e64 v48, v104, v103, s[6:7]
	v_cndmask_b32_e64 v49, v48, 0, s[8:9]
	v_mov_b32_e32 v48, v39
	v_cndmask_b32_e32 v39, v101, v102, vcc
	v_cndmask_b32_e64 v39, 0, v39, s[10:11]
	v_fma_f32 v35, v39, v43, v35
	v_mul_f32_e32 v39, 0x3d372713, v98
	v_mul_f32_e32 v39, v98, v39
	v_fma_f32 v39, v98, v39, v98
	v_mul_f32_e32 v39, 0x3f4c422a, v39
	v_mul_f32_e32 v39, 0xc038aa3b, v39
	v_exp_f32_e32 v39, v39
	v_mov_b32_e32 v50, v19
	v_pk_mul_f32 v[48:49], v[50:51], v[48:49]
	v_add_f32_e32 v39, 1.0, v39
	v_rcp_f32_e32 v39, v39
	v_add_f32_e32 v35, v49, v35
	v_add_f32_e32 v35, v48, v35
	v_mov_b32_e32 v48, v18
	v_mul_f32_e32 v39, v98, v39
	v_mul_f32_e32 v43, v35, v39
	v_cndmask_b32_e64 v35, v95, v93, s[6:7]
	v_cndmask_b32_e64 v39, v35, 0, s[8:9]
	v_cndmask_b32_e32 v35, v91, v92, vcc
	v_cndmask_b32_e64 v35, 0, v35, s[10:11]
	v_fma_f32 v34, v35, v42, v34
	v_mul_f32_e32 v35, 0x3d372713, v94
	v_mul_f32_e32 v35, v94, v35
	v_fma_f32 v35, v94, v35, v94
	v_mul_f32_e32 v35, 0x3f4c422a, v35
	v_mul_f32_e32 v35, 0xc038aa3b, v35
	v_exp_f32_e32 v35, v35
	v_mov_b32_e32 v49, v46
	v_pk_mul_f32 v[38:39], v[48:49], v[38:39]
	v_add_f32_e32 v35, 1.0, v35
	v_rcp_f32_e32 v35, v35
	v_add_f32_e32 v34, v39, v34
	v_add_f32_e32 v34, v38, v34
	v_mov_b32_e32 v38, v17
	v_mul_f32_e32 v35, v94, v35
	v_mul_f32_e32 v42, v34, v35
	v_cndmask_b32_e64 v34, v89, v88, s[6:7]
	v_cndmask_b32_e64 v35, v34, 0, s[8:9]
	v_mov_b32_e32 v34, v37
	v_cndmask_b32_e32 v37, v86, v87, vcc
	v_mov_b32_e32 v39, v45
	v_cndmask_b32_e64 v37, 0, v37, s[10:11]
	v_pk_mul_f32 v[34:35], v[38:39], v[34:35]
	v_fma_f32 v33, v37, v41, v33
	v_add_f32_e32 v33, v35, v33
	v_add_f32_e32 v33, v34, v33
	v_mul_f32_e32 v34, 0x3d372713, v90
	v_mul_f32_e32 v34, v90, v34
	v_fma_f32 v34, v90, v34, v90
	v_mul_f32_e32 v34, 0x3f4c422a, v34
	v_mul_f32_e32 v34, 0xc038aa3b, v34
	v_exp_f32_e32 v34, v34
	v_mov_b32_e32 v35, v44
	v_add_f32_e32 v34, 1.0, v34
	v_rcp_f32_e32 v34, v34
	s_nop 0
	v_mul_f32_e32 v34, v90, v34
	v_mul_f32_e32 v38, v33, v34
	v_cndmask_b32_e64 v33, v84, v83, s[6:7]
	v_cndmask_b32_e64 v37, v33, 0, s[8:9]
	v_cndmask_b32_e32 v33, v81, v82, vcc
	v_cndmask_b32_e64 v33, 0, v33, s[10:11]
	v_fmac_f32_e32 v32, v33, v40
	v_mul_f32_e32 v33, 0x3d372713, v85
	v_mul_f32_e32 v33, v85, v33
	v_fma_f32 v33, v85, v33, v85
	v_mul_f32_e32 v33, 0x3f4c422a, v33
	v_mul_f32_e32 v33, 0xc038aa3b, v33
	v_exp_f32_e32 v33, v33
	v_mov_b32_e32 v34, v16
	v_pk_mul_f32 v[34:35], v[34:35], v[36:37]
	v_mov_b64_e32 v[36:37], s[16:17]
	v_add_f32_e32 v33, 1.0, v33
	v_rcp_f32_e32 v33, v33
	v_add_f32_e32 v32, v35, v32
	v_add_f32_e32 v32, v34, v32
	v_mad_i64_i32 v[36:37], s[8:9], v80, s79, v[36:37]
	v_mul_f32_e32 v33, v85, v33
	v_mul_f32_e32 v34, v32, v33
	v_lshl_add_u64 v[36:37], v[188:189], 1, v[36:37]
	v_cvt_pk_bf16_f32 v32, v52, v53
	v_cvt_pk_bf16_f32 v33, v54, v55
	v_cvt_pk_bf16_f32 v34, v34, v38
	v_cvt_pk_bf16_f32 v35, v42, v43
	global_store_dwordx4 v[36:37], v[32:35], off sc1
.LBB0_1007:
	s_or_b64 exec, exec, s[30:31]
	v_add_u32_e32 v60, 0x70, v218
	v_mov_b32_dpp v79, v28 row_mirror row_mask:0xf bank_mask:0xf bound_ctrl:1
	v_mov_b32_dpp v91, v29 row_mirror row_mask:0xf bank_mask:0xf bound_ctrl:1
	v_mov_b32_dpp v99, v30 row_mirror row_mask:0xf bank_mask:0xf bound_ctrl:1
	v_mov_b32_dpp v52, v31 row_mirror row_mask:0xf bank_mask:0xf bound_ctrl:1
	v_mov_b32_dpp v87, v20 row_mirror row_mask:0xf bank_mask:0xf bound_ctrl:1
	v_mov_b32_dpp v95, v21 row_mirror row_mask:0xf bank_mask:0xf bound_ctrl:1
	v_mov_b32_dpp v103, v22 row_mirror row_mask:0xf bank_mask:0xf bound_ctrl:1
	v_mov_b32_dpp v38, v23 row_mirror row_mask:0xf bank_mask:0xf bound_ctrl:1
	v_mov_b32_dpp v34, v24 row_mirror row_mask:0xf bank_mask:0xf bound_ctrl:1
	v_mov_b32_dpp v42, v25 row_mirror row_mask:0xf bank_mask:0xf bound_ctrl:1
	v_mov_b32_dpp v46, v26 row_mirror row_mask:0xf bank_mask:0xf bound_ctrl:1
	v_mov_b32_dpp v50, v27 row_mirror row_mask:0xf bank_mask:0xf bound_ctrl:1
	v_mov_b32_dpp v63, v16 row_mirror row_mask:0xf bank_mask:0xf bound_ctrl:1
	v_mov_b32_dpp v68, v17 row_mirror row_mask:0xf bank_mask:0xf bound_ctrl:1
	v_mov_b32_dpp v73, v18 row_mirror row_mask:0xf bank_mask:0xf bound_ctrl:1
	v_mov_b32_dpp v83, v19 row_mirror row_mask:0xf bank_mask:0xf bound_ctrl:1
	v_mov_b32_dpp v76, v79 quad_perm:[1,0,3,2] row_mask:0xf bank_mask:0xf bound_ctrl:1
	v_mov_b32_dpp v80, v4 row_shr:1 row_mask:0xf bank_mask:0xf bound_ctrl:1
	v_mov_b32_dpp v77, v4 row_shr:2 row_mask:0xf bank_mask:0xf bound_ctrl:1
	v_mov_b32_dpp v89, v91 quad_perm:[1,0,3,2] row_mask:0xf bank_mask:0xf bound_ctrl:1
	v_mov_b32_dpp v92, v5 row_shr:1 row_mask:0xf bank_mask:0xf bound_ctrl:1
	v_mov_b32_dpp v90, v5 row_shr:2 row_mask:0xf bank_mask:0xf bound_ctrl:1
	v_mov_b32_dpp v97, v99 quad_perm:[1,0,3,2] row_mask:0xf bank_mask:0xf bound_ctrl:1
	v_mov_b32_dpp v100, v6 row_shr:1 row_mask:0xf bank_mask:0xf bound_ctrl:1
	v_mov_b32_dpp v98, v6 row_shr:2 row_mask:0xf bank_mask:0xf bound_ctrl:1
	v_mov_b32_dpp v105, v52 quad_perm:[1,0,3,2] row_mask:0xf bank_mask:0xf bound_ctrl:1
	v_mov_b32_dpp v53, v7 row_shr:1 row_mask:0xf bank_mask:0xf bound_ctrl:1
	v_mov_b32_dpp v106, v7 row_shr:2 row_mask:0xf bank_mask:0xf bound_ctrl:1
	v_mov_b32_dpp v85, v87 quad_perm:[1,0,3,2] row_mask:0xf bank_mask:0xf bound_ctrl:1
	v_mov_b32_dpp v88, v8 row_shr:1 row_mask:0xf bank_mask:0xf bound_ctrl:1
	v_mov_b32_dpp v86, v8 row_shr:2 row_mask:0xf bank_mask:0xf bound_ctrl:1
	v_mov_b32_dpp v93, v95 quad_perm:[1,0,3,2] row_mask:0xf bank_mask:0xf bound_ctrl:1
	v_mov_b32_dpp v96, v9 row_shr:1 row_mask:0xf bank_mask:0xf bound_ctrl:1
	v_mov_b32_dpp v94, v9 row_shr:2 row_mask:0xf bank_mask:0xf bound_ctrl:1
	v_mov_b32_dpp v101, v103 quad_perm:[1,0,3,2] row_mask:0xf bank_mask:0xf bound_ctrl:1
	v_mov_b32_dpp v104, v10 row_shr:1 row_mask:0xf bank_mask:0xf bound_ctrl:1
	v_mov_b32_dpp v102, v10 row_shr:2 row_mask:0xf bank_mask:0xf bound_ctrl:1
	v_mov_b32_dpp v36, v38 quad_perm:[1,0,3,2] row_mask:0xf bank_mask:0xf bound_ctrl:1
	v_mov_b32_dpp v39, v11 row_shr:1 row_mask:0xf bank_mask:0xf bound_ctrl:1
	v_mov_b32_dpp v37, v11 row_shr:2 row_mask:0xf bank_mask:0xf bound_ctrl:1
	v_mov_b32_dpp v32, v34 quad_perm:[1,0,3,2] row_mask:0xf bank_mask:0xf bound_ctrl:1
	v_mov_b32_dpp v35, v12 row_shr:1 row_mask:0xf bank_mask:0xf bound_ctrl:1
	v_mov_b32_dpp v33, v12 row_shr:2 row_mask:0xf bank_mask:0xf bound_ctrl:1
	v_mov_b32_dpp v40, v42 quad_perm:[1,0,3,2] row_mask:0xf bank_mask:0xf bound_ctrl:1
	v_mov_b32_dpp v43, v13 row_shr:1 row_mask:0xf bank_mask:0xf bound_ctrl:1
	v_mov_b32_dpp v41, v13 row_shr:2 row_mask:0xf bank_mask:0xf bound_ctrl:1
	v_mov_b32_dpp v44, v46 quad_perm:[1,0,3,2] row_mask:0xf bank_mask:0xf bound_ctrl:1
	v_mov_b32_dpp v47, v14 row_shr:1 row_mask:0xf bank_mask:0xf bound_ctrl:1
	v_mov_b32_dpp v45, v14 row_shr:2 row_mask:0xf bank_mask:0xf bound_ctrl:1
	v_mov_b32_dpp v48, v50 quad_perm:[1,0,3,2] row_mask:0xf bank_mask:0xf bound_ctrl:1
	v_mov_b32_dpp v51, v15 row_shr:1 row_mask:0xf bank_mask:0xf bound_ctrl:1
	v_mov_b32_dpp v49, v15 row_shr:2 row_mask:0xf bank_mask:0xf bound_ctrl:1
	v_mov_b32_dpp v61, v63 quad_perm:[1,0,3,2] row_mask:0xf bank_mask:0xf bound_ctrl:1
	v_mov_b32_dpp v64, v0 row_shr:1 row_mask:0xf bank_mask:0xf bound_ctrl:1
	v_mov_b32_dpp v62, v0 row_shr:2 row_mask:0xf bank_mask:0xf bound_ctrl:1
	v_mov_b32_dpp v66, v68 quad_perm:[1,0,3,2] row_mask:0xf bank_mask:0xf bound_ctrl:1
	v_mov_b32_dpp v69, v1 row_shr:1 row_mask:0xf bank_mask:0xf bound_ctrl:1
	v_mov_b32_dpp v67, v1 row_shr:2 row_mask:0xf bank_mask:0xf bound_ctrl:1
	v_mov_b32_dpp v71, v73 quad_perm:[1,0,3,2] row_mask:0xf bank_mask:0xf bound_ctrl:1
	v_mov_b32_dpp v75, v2 row_shr:1 row_mask:0xf bank_mask:0xf bound_ctrl:1
	v_mov_b32_dpp v72, v2 row_shr:2 row_mask:0xf bank_mask:0xf bound_ctrl:1
	v_mov_b32_dpp v81, v83 quad_perm:[1,0,3,2] row_mask:0xf bank_mask:0xf bound_ctrl:1
	v_mov_b32_dpp v84, v3 row_shr:1 row_mask:0xf bank_mask:0xf bound_ctrl:1
	v_mov_b32_dpp v82, v3 row_shr:2 row_mask:0xf bank_mask:0xf bound_ctrl:1
	v_cmp_gt_i32_e64 s[8:9], s58, v60
	s_and_saveexec_b64 s[30:31], s[8:9]
	s_cbranch_execz .LBB0_1009
	v_add_u32_e32 v58, 0x810, v60
	v_mul_hi_u32 v59, v58, s59
	s_add_i32 s0, 0, 0x20000
	v_lshrrev_b32_e32 v59, 7, v59
	v_add_u32_e32 v24, s0, v212
	v_mul_u32_u24_e32 v59, 0x810, v59
	ds_read_b128 v[16:19], v217
	ds_read_b128 v[20:23], v216
	ds_read_b128 v[28:31], v215
	ds_read_b128 v[24:27], v24
	ds_read_b128 v[54:57], v214
	ds_read_b128 v[108:111], v213
	v_sub_u32_e32 v65, v58, v59
	v_mov_b32_e32 v58, v15
	v_add_u32_e32 v15, s0, v210
	ds_read_b128 v[112:115], v211
	ds_read_b128 v[116:119], v15
	v_cmp_eq_u32_e64 s[8:9], 0, v65
	v_cndmask_b32_e64 v50, v51, v50, s[6:7]
	v_cmp_lt_u32_e64 s[10:11], 1, v65
	v_cndmask_b32_e32 v15, v48, v49, vcc
	v_cndmask_b32_e64 v51, v50, 0, s[8:9]
	s_waitcnt lgkmcnt(2)
	v_mov_b32_e32 v59, v111
	v_mov_b32_e32 v50, v57
	v_cndmask_b32_e64 v15, 0, v15, s[10:11]
	v_pk_mul_f32 v[50:51], v[58:59], v[50:51]
	s_waitcnt lgkmcnt(0)
	v_fma_f32 v15, v15, v119, v115
	v_add_f32_e32 v15, v51, v15
	v_add_f32_e32 v78, v50, v15
	v_cndmask_b32_e64 v15, v47, v46, s[6:7]
	v_cndmask_b32_e32 v44, v44, v45, vcc
	v_cndmask_b32_e64 v57, v15, 0, s[8:9]
	v_mov_b32_e32 v15, v110
	v_cndmask_b32_e64 v44, 0, v44, s[10:11]
	v_pk_mul_f32 v[14:15], v[14:15], v[56:57]
	v_fma_f32 v44, v44, v118, v114
	v_add_f32_e32 v15, v15, v44
	v_add_f32_e32 v74, v14, v15
	v_cndmask_b32_e64 v14, v43, v42, s[6:7]
	v_mov_b32_e32 v42, v13
	v_cndmask_b32_e32 v13, v40, v41, vcc
	v_cndmask_b32_e64 v15, v14, 0, s[8:9]
	v_mov_b32_e32 v43, v109
	v_mov_b32_e32 v14, v55
	v_cndmask_b32_e64 v13, 0, v13, s[10:11]
	v_pk_mul_f32 v[14:15], v[42:43], v[14:15]
	v_fma_f32 v13, v13, v117, v113
	v_add_f32_e32 v13, v15, v13
	v_add_f32_e32 v70, v14, v13
	v_cndmask_b32_e64 v13, v35, v34, s[6:7]
	v_cndmask_b32_e32 v14, v32, v33, vcc
	v_cndmask_b32_e64 v55, v13, 0, s[8:9]
	v_mov_b32_e32 v13, v108
	v_cndmask_b32_e64 v14, 0, v14, s[10:11]
	v_pk_mul_f32 v[12:13], v[12:13], v[54:55]
	v_fmac_f32_e32 v112, v14, v116
	v_add_f32_e32 v13, v13, v112
	v_add_f32_e32 v65, v12, v13
	ds_read_b128 v[12:15], v209
	ds_read_b128 v[32:35], v208
	v_cndmask_b32_e64 v38, v39, v38, s[6:7]
	v_cndmask_b32_e64 v39, v38, 0, s[8:9]
	v_mov_b32_e32 v40, v11
	s_waitcnt lgkmcnt(1)
	v_mov_b32_e32 v38, v15
	s_waitcnt lgkmcnt(0)
	v_mov_b32_e32 v41, v35
	v_add_u32_e32 v11, s0, v206
	v_pk_mul_f32 v[38:39], v[40:41], v[38:39]
	ds_read_b128 v[40:43], v207
	ds_read_b128 v[44:47], v11
	v_cndmask_b32_e32 v11, v36, v37, vcc
	v_cndmask_b32_e64 v11, 0, v11, s[10:11]
	v_cndmask_b32_e64 v15, v53, v52, s[6:7]
	v_cndmask_b32_e64 v53, v15, 0, s[8:9]
	s_waitcnt lgkmcnt(0)
	v_fma_f32 v11, v11, v47, v43
	v_add_f32_e32 v11, v39, v11
	v_add_f32_e32 v11, v38, v11
	ds_read_b128 v[36:39], v205
	ds_read_b128 v[48:51], v204
	v_mov_b32_e32 v54, v7
	v_add_u32_e32 v7, s0, v172
	ds_read_b128 v[56:59], v7
	s_waitcnt lgkmcnt(2)
	v_mov_b32_e32 v52, v39
	s_waitcnt lgkmcnt(1)
	v_mov_b32_e32 v55, v51
	v_pk_mul_f32 v[108:109], v[54:55], v[52:53]
	ds_read_b128 v[52:55], v203
	v_cndmask_b32_e32 v7, v105, v106, vcc
	v_cndmask_b32_e64 v7, 0, v7, s[10:11]
	s_waitcnt lgkmcnt(0)
	v_fma_f32 v7, v7, v59, v55
	v_add_f32_e32 v7, v109, v7
	v_add_f32_e32 v7, v108, v7
	v_mul_f32_e32 v15, 0x3d372713, v7
	v_mul_f32_e32 v15, v7, v15
	v_fma_f32 v15, v7, v15, v7
	v_mul_f32_e32 v15, 0x3f4c422a, v15
	v_mul_f32_e32 v15, 0xc038aa3b, v15
	v_exp_f32_e32 v15, v15
	s_nop 0
	v_add_f32_e32 v15, 1.0, v15
	v_rcp_f32_e32 v15, v15
	s_nop 0
	v_mul_f32_e32 v7, v7, v15
	v_mul_f32_e32 v35, v11, v7
	v_cndmask_b32_e64 v7, v104, v103, s[6:7]
	v_cndmask_b32_e64 v15, v7, 0, s[8:9]
	v_cndmask_b32_e32 v7, v101, v102, vcc
	v_mov_b32_e32 v11, v34
	v_cndmask_b32_e64 v7, 0, v7, s[10:11]
	v_pk_mul_f32 v[10:11], v[10:11], v[14:15]
	v_fma_f32 v7, v7, v46, v42
	v_add_f32_e32 v7, v11, v7
	v_add_f32_e32 v10, v10, v7
	v_cndmask_b32_e64 v7, v100, v99, s[6:7]
	v_cndmask_b32_e32 v11, v97, v98, vcc
	v_cndmask_b32_e64 v39, v7, 0, s[8:9]
	v_mov_b32_e32 v7, v50
	v_cndmask_b32_e64 v11, 0, v11, s[10:11]
	v_pk_mul_f32 v[6:7], v[6:7], v[38:39]
	v_fma_f32 v11, v11, v58, v54
	v_add_f32_e32 v7, v7, v11
	v_add_f32_e32 v6, v6, v7
	v_mul_f32_e32 v7, 0x3d372713, v6
	v_mul_f32_e32 v7, v6, v7
	v_fma_f32 v7, v6, v7, v6
	v_mul_f32_e32 v7, 0x3f4c422a, v7
	v_mul_f32_e32 v7, 0xc038aa3b, v7
	v_exp_f32_e32 v7, v7
	v_mov_b32_e32 v11, v33
	v_add_f32_e32 v7, 1.0, v7
	v_rcp_f32_e32 v7, v7
	s_nop 0
	v_mul_f32_e32 v6, v6, v7
	v_mul_f32_e32 v14, v10, v6
	v_cndmask_b32_e64 v6, v96, v95, s[6:7]
	v_mov_b32_e32 v10, v9
	v_cndmask_b32_e32 v9, v93, v94, vcc
	v_cndmask_b32_e64 v7, v6, 0, s[8:9]
	v_mov_b32_e32 v6, v13
	v_cndmask_b32_e64 v9, 0, v9, s[10:11]
	v_pk_mul_f32 v[6:7], v[10:11], v[6:7]
	v_fma_f32 v9, v9, v45, v41
	v_add_f32_e32 v7, v7, v9
	v_add_f32_e32 v9, v6, v7
	v_cndmask_b32_e64 v6, v92, v91, s[6:7]
	v_mov_b32_e32 v10, v5
	v_cndmask_b32_e32 v5, v89, v90, vcc
	v_cndmask_b32_e64 v7, v6, 0, s[8:9]
	v_mov_b32_e32 v11, v49
	v_mov_b32_e32 v6, v37
	v_cndmask_b32_e64 v5, 0, v5, s[10:11]
	v_pk_mul_f32 v[6:7], v[10:11], v[6:7]
	v_fma_f32 v5, v5, v57, v53
	v_add_f32_e32 v5, v7, v5
	v_add_f32_e32 v5, v6, v5
	v_mul_f32_e32 v6, 0x3d372713, v5
	v_mul_f32_e32 v6, v5, v6
	v_fma_f32 v6, v5, v6, v5
	v_mul_f32_e32 v6, 0x3f4c422a, v6
	v_mul_f32_e32 v6, 0xc038aa3b, v6
	v_exp_f32_e32 v6, v6
	s_nop 0
	v_add_f32_e32 v6, 1.0, v6
	v_rcp_f32_e32 v6, v6
	s_nop 0
	v_mul_f32_e32 v5, v5, v6
	v_mul_f32_e32 v10, v9, v5
	v_cndmask_b32_e64 v5, v88, v87, s[6:7]
	v_cndmask_b32_e64 v13, v5, 0, s[8:9]
	v_cndmask_b32_e32 v5, v85, v86, vcc
	v_mov_b32_e32 v9, v32
	v_cndmask_b32_e64 v5, 0, v5, s[10:11]
	v_pk_mul_f32 v[6:7], v[8:9], v[12:13]
	v_fmac_f32_e32 v40, v5, v44
	v_add_f32_e32 v5, v7, v40
	v_add_f32_e32 v6, v6, v5
	v_cndmask_b32_e64 v5, v80, v79, s[6:7]
	v_cndmask_b32_e32 v7, v76, v77, vcc
	v_cndmask_b32_e64 v37, v5, 0, s[8:9]
	v_mov_b32_e32 v5, v48
	v_cndmask_b32_e64 v7, 0, v7, s[10:11]
	v_pk_mul_f32 v[4:5], v[4:5], v[36:37]
	v_fmac_f32_e32 v52, v7, v56
	v_add_f32_e32 v5, v5, v52
	v_add_f32_e32 v4, v4, v5
	v_mul_f32_e32 v5, 0x3d372713, v4
	v_mul_f32_e32 v5, v4, v5
	v_fma_f32 v5, v4, v5, v4
	v_mul_f32_e32 v5, 0x3f4c422a, v5
	v_mul_f32_e32 v5, 0xc038aa3b, v5
	v_exp_f32_e32 v5, v5
	v_mov_b32_e32 v7, v31
	v_add_f32_e32 v5, 1.0, v5
	v_rcp_f32_e32 v5, v5
	s_nop 0
	v_mul_f32_e32 v4, v4, v5
	v_mul_f32_e32 v8, v6, v4
	v_cndmask_b32_e64 v4, v84, v83, s[6:7]
	v_mov_b32_e32 v6, v3
	v_cndmask_b32_e32 v3, v81, v82, vcc
	v_cndmask_b32_e64 v5, v4, 0, s[8:9]
	v_mov_b32_e32 v4, v23
	v_cndmask_b32_e64 v3, 0, v3, s[10:11]
	v_pk_mul_f32 v[4:5], v[6:7], v[4:5]
	v_fma_f32 v3, v3, v27, v19
	v_add_f32_e32 v3, v5, v3
	v_add_f32_e32 v3, v4, v3
	v_mul_f32_e32 v4, 0x3d372713, v78
	v_mul_f32_e32 v4, v78, v4
	v_fma_f32 v4, v78, v4, v78
	v_mul_f32_e32 v4, 0x3f4c422a, v4
	v_mul_f32_e32 v4, 0xc038aa3b, v4
	v_exp_f32_e32 v4, v4
	v_mov_b32_e32 v5, v29
	v_add_f32_e32 v4, 1.0, v4
	v_rcp_f32_e32 v4, v4
	s_nop 0
	v_mul_f32_e32 v4, v78, v4
	v_mul_f32_e32 v6, v3, v4
	v_cndmask_b32_e64 v3, v75, v73, s[6:7]
	v_cndmask_b32_e32 v4, v71, v72, vcc
	v_cndmask_b32_e64 v23, v3, 0, s[8:9]
	v_mov_b32_e32 v3, v30
	v_cndmask_b32_e64 v4, 0, v4, s[10:11]
	v_pk_mul_f32 v[2:3], v[2:3], v[22:23]
	v_fma_f32 v4, v4, v26, v18
	v_add_f32_e32 v3, v3, v4
	v_add_f32_e32 v2, v2, v3
	v_mul_f32_e32 v3, 0x3d372713, v74
	v_mul_f32_e32 v3, v74, v3
	v_fma_f32 v3, v74, v3, v74
	v_mul_f32_e32 v3, 0x3f4c422a, v3
	v_mul_f32_e32 v3, 0xc038aa3b, v3
	v_exp_f32_e32 v3, v3
	v_mov_b32_e32 v4, v1
	v_cndmask_b32_e32 v1, v66, v67, vcc
	v_cndmask_b32_e64 v1, 0, v1, s[10:11]
	v_add_f32_e32 v3, 1.0, v3
	v_rcp_f32_e32 v3, v3
	v_fma_f32 v1, v1, v25, v17
	v_mul_f32_e32 v3, v74, v3
	v_mul_f32_e32 v7, v2, v3
	v_cndmask_b32_e64 v2, v69, v68, s[6:7]
	v_cndmask_b32_e64 v3, v2, 0, s[8:9]
	v_mov_b32_e32 v2, v21
	v_pk_mul_f32 v[2:3], v[4:5], v[2:3]
	v_mov_b64_e32 v[4:5], s[16:17]
	v_add_f32_e32 v1, v3, v1
	v_add_f32_e32 v1, v2, v1
	v_mul_f32_e32 v2, 0x3d372713, v70
	v_mul_f32_e32 v2, v70, v2
	v_fma_f32 v2, v70, v2, v70
	v_mul_f32_e32 v2, 0x3f4c422a, v2
	v_mul_f32_e32 v2, 0xc038aa3b, v2
	v_exp_f32_e32 v2, v2
	v_cndmask_b32_e32 v3, v61, v62, vcc
	v_cndmask_b32_e64 v3, 0, v3, s[10:11]
	v_fmac_f32_e32 v16, v3, v24
	v_add_f32_e32 v2, 1.0, v2
	v_rcp_f32_e32 v2, v2
	s_nop 0
	v_mul_f32_e32 v2, v70, v2
	v_mul_f32_e32 v2, v1, v2
	v_cndmask_b32_e64 v1, v64, v63, s[6:7]
	v_cndmask_b32_e64 v21, v1, 0, s[8:9]
	v_mov_b32_e32 v1, v28
	v_pk_mul_f32 v[0:1], v[0:1], v[20:21]
	v_mad_i64_i32 v[4:5], s[6:7], v60, s79, v[4:5]
	v_add_f32_e32 v1, v1, v16
	v_add_f32_e32 v0, v0, v1
	v_mul_f32_e32 v1, 0x3d372713, v65
	v_mul_f32_e32 v1, v65, v1
	v_fma_f32 v1, v65, v1, v65
	v_mul_f32_e32 v1, 0x3f4c422a, v1
	v_mul_f32_e32 v1, 0xc038aa3b, v1
	v_exp_f32_e32 v1, v1
	v_lshl_add_u64 v[4:5], v[188:189], 1, v[4:5]
	v_add_f32_e32 v1, 1.0, v1
	v_rcp_f32_e32 v1, v1
	s_nop 0
	v_mul_f32_e32 v1, v65, v1
	v_mul_f32_e32 v3, v0, v1
	v_cvt_pk_bf16_f32 v0, v8, v10
	v_cvt_pk_bf16_f32 v1, v14, v35
	v_cvt_pk_bf16_f32 v2, v3, v2
	v_cvt_pk_bf16_f32 v3, v7, v6
	global_store_dwordx4 v[4:5], v[0:3], off sc1

.LBB0_1073:
	v_or_b32_e32 v130, s24, v129
	s_add_u32 s6, s10, s20
	s_addc_u32 s7, s11, s21
	v_ashrrev_i32_e32 v129, 31, v128
	v_ashrrev_i32_e32 v131, 31, v130
	v_lshl_add_u64 v[132:133], v[128:129], 1, s[6:7]
	v_lshlrev_b64 v[128:129], 11, v[130:131]
	v_lshl_add_u64 v[128:129], v[132:133], 0, v[128:129]
	v_cvt_pk_bf16_f32 v124, v124, v125
	v_cvt_pk_bf16_f32 v125, v126, v127
	v_cvt_pk_bf16_f32 v126, v120, v121
	v_cvt_pk_bf16_f32 v127, v122, v123
	global_store_dwordx4 v[128:129], v[124:127], off sc1
	v_cvt_pk_bf16_f32 v112, v112, v113
	v_cvt_pk_bf16_f32 v113, v114, v115
	v_cvt_pk_bf16_f32 v114, v104, v105
	v_or_b32_e32 v104, 16, v130
	v_ashrrev_i32_e32 v105, 31, v104
	v_lshlrev_b64 v[104:105], 11, v[104:105]
	v_cvt_pk_bf16_f32 v115, v106, v107
	global_store_dwordx4 v[128:129], v[112:115], off offset:256 sc1
	s_mov_b64 s[6:7], 0x40000
	s_nop 0
	v_lshl_add_u64 v[112:113], v[132:133], 0, v[104:105]
	v_cvt_pk_bf16_f32 v104, v116, v117
	v_cvt_pk_bf16_f32 v105, v118, v119
	v_cvt_pk_bf16_f32 v106, v108, v109
	v_cvt_pk_bf16_f32 v107, v110, v111
	global_store_dwordx4 v[112:113], v[104:107], off sc1
	v_cvt_pk_bf16_f32 v96, v96, v97
	v_cvt_pk_bf16_f32 v97, v98, v99
	v_cvt_pk_bf16_f32 v98, v88, v89
	v_or_b32_e32 v88, 32, v130
	v_ashrrev_i32_e32 v89, 31, v88
	v_lshlrev_b64 v[88:89], 11, v[88:89]
	v_cvt_pk_bf16_f32 v99, v90, v91
	global_store_dwordx4 v[112:113], v[96:99], off offset:256 sc1
	s_nop 1
	v_lshl_add_u64 v[96:97], v[132:133], 0, v[88:89]
	v_cvt_pk_bf16_f32 v88, v100, v101
	v_cvt_pk_bf16_f32 v89, v102, v103
	v_cvt_pk_bf16_f32 v90, v92, v93
	v_cvt_pk_bf16_f32 v91, v94, v95
	global_store_dwordx4 v[96:97], v[88:91], off sc1
	v_cvt_pk_bf16_f32 v80, v80, v81
	v_cvt_pk_bf16_f32 v81, v82, v83
	v_cvt_pk_bf16_f32 v82, v72, v73
	v_or_b32_e32 v72, 48, v130
	v_ashrrev_i32_e32 v73, 31, v72
	v_lshlrev_b64 v[72:73], 11, v[72:73]
	v_cvt_pk_bf16_f32 v83, v74, v75
	global_store_dwordx4 v[96:97], v[80:83], off offset:256 sc1
	s_nop 1
	v_lshl_add_u64 v[80:81], v[132:133], 0, v[72:73]
	v_cvt_pk_bf16_f32 v72, v84, v85
	v_cvt_pk_bf16_f32 v73, v86, v87
	v_cvt_pk_bf16_f32 v74, v76, v77
	v_cvt_pk_bf16_f32 v75, v78, v79
	global_store_dwordx4 v[80:81], v[72:75], off sc1
	v_cvt_pk_bf16_f32 v68, v68, v69
	v_cvt_pk_bf16_f32 v69, v70, v71
	v_cvt_pk_bf16_f32 v70, v64, v65
	v_lshl_add_u64 v[64:65], v[128:129], 0, s[6:7]
	s_mov_b32 s6, 0x40000
	v_cvt_pk_bf16_f32 v71, v66, v67
	global_store_dwordx4 v[80:81], v[68:71], off offset:256 sc1
	v_cvt_pk_bf16_f32 v60, v60, v61
	v_cvt_pk_bf16_f32 v61, v62, v63
	v_cvt_pk_bf16_f32 v62, v56, v57
	v_add_co_u32_e32 v56, vcc, s6, v128
	v_cvt_pk_bf16_f32 v63, v58, v59
	s_mov_b64 s[6:7], 0x48000
	s_nop 0
	v_addc_co_u32_e32 v57, vcc, 0, v129, vcc
	global_store_dwordx4 v[56:57], v[60:63], off sc1
	v_cvt_pk_bf16_f32 v48, v48, v49
	v_cvt_pk_bf16_f32 v49, v50, v51
	v_cvt_pk_bf16_f32 v50, v40, v41
	v_cvt_pk_bf16_f32 v51, v42, v43
	global_store_dwordx4 v[64:65], v[48:51], off offset:256 sc1
	v_cvt_pk_bf16_f32 v40, v52, v53
	v_cvt_pk_bf16_f32 v41, v54, v55
	v_cvt_pk_bf16_f32 v42, v44, v45
	v_cvt_pk_bf16_f32 v43, v46, v47
	s_nop 1
	v_lshl_add_u64 v[48:49], v[128:129], 0, s[6:7]
	s_mov_b32 s6, 0x48000
	v_add_co_u32_e32 v44, vcc, s6, v128
	s_mov_b64 s[6:7], 0x50000
	s_nop 0
	v_addc_co_u32_e32 v45, vcc, 0, v129, vcc
	global_store_dwordx4 v[44:45], v[40:43], off sc1
	v_cvt_pk_bf16_f32 v32, v32, v33
	v_cvt_pk_bf16_f32 v33, v34, v35
	v_cvt_pk_bf16_f32 v34, v24, v25
	v_cvt_pk_bf16_f32 v35, v26, v27
	global_store_dwordx4 v[48:49], v[32:35], off offset:256 sc1
	v_cvt_pk_bf16_f32 v24, v36, v37
	v_cvt_pk_bf16_f32 v25, v38, v39
	v_cvt_pk_bf16_f32 v26, v28, v29
	v_cvt_pk_bf16_f32 v27, v30, v31
	s_nop 1
	v_lshl_add_u64 v[32:33], v[128:129], 0, s[6:7]
	s_mov_b32 s6, 0x50000
	v_add_co_u32_e32 v28, vcc, s6, v128
	s_mov_b64 s[6:7], 0x58000
	s_nop 0
	v_addc_co_u32_e32 v29, vcc, 0, v129, vcc
	global_store_dwordx4 v[28:29], v[24:27], off sc1
	v_cvt_pk_bf16_f32 v16, v16, v17
	v_cvt_pk_bf16_f32 v17, v18, v19
	v_cvt_pk_bf16_f32 v18, v8, v9
	v_cvt_pk_bf16_f32 v19, v10, v11
	global_store_dwordx4 v[32:33], v[16:19], off offset:256 sc1
	v_cvt_pk_bf16_f32 v8, v20, v21
	v_cvt_pk_bf16_f32 v9, v22, v23
	v_cvt_pk_bf16_f32 v10, v12, v13
	v_cvt_pk_bf16_f32 v11, v14, v15
	s_nop 1
	v_lshl_add_u64 v[16:17], v[128:129], 0, s[6:7]
	s_mov_b32 s6, 0x58000
	v_add_co_u32_e32 v12, vcc, s6, v128
	s_nop 1
	v_addc_co_u32_e32 v13, vcc, 0, v129, vcc
	global_store_dwordx4 v[12:13], v[8:11], off sc1
	v_cvt_pk_bf16_f32 v4, v4, v5
	v_cvt_pk_bf16_f32 v5, v6, v7
	v_cvt_pk_bf16_f32 v6, v0, v1
	v_cvt_pk_bf16_f32 v7, v2, v3
	global_store_dwordx4 v[16:17], v[4:7], off offset:256 sc1
